# v2 + first two K-loop waits after an FFN-up epilogue relaxed to vmcnt(16) (epilogue stores stay in flight)
# baseline (speedup 1.0000x reference)
.LBB0_150:
	v_lshrrev_b32_e32 v4, 1, v2
	v_and_b32_e32 v4, 24, v4
	v_and_b32_e32 v3, 15, v2
	v_lshlrev_b32_e32 v5, 1, v4
	v_lshlrev_b32_e32 v2, 2, v2
	s_sext_i32_i16 s86, s2
	v_lshl_or_b32 v135, s8, 6, v3
	v_lshl_or_b32 v3, v3, 6, v5
	s_lshl_b32 s2, s8, 13
	v_and_b32_e32 v2, 32, v2
	v_bitop3_b32 v5, v3, s2, v2 bitop3:0xde
	s_lshl_b32 s2, s9, 5
	s_and_b32 s2, s2, 0x60
	s_lshl_b32 s8, s2, 7
	v_bitop3_b32 v2, v3, s8, v2 bitop3:0xde
	s_add_u32 s8, s0, 0x80
	s_addc_u32 s9, s1, 0
	s_add_i32 s76, s51, 0x18000
	s_waitcnt vmcnt(2)
	s_barrier
	s_mov_b32 s10, m0
	s_mov_b32 m0, s76
	s_nop 4
	global_load_lds_dwordx4 v134, s[8:9]
	s_mov_b32 m0, s10
	s_add_u32 s8, s0, 0x20080
	s_addc_u32 s9, s1, 0
	s_add_i32 s77, s51, 0x1a000
	s_mov_b32 s10, m0
	s_mov_b32 m0, s77
	s_nop 4
	global_load_lds_dwordx4 v134, s[8:9]
	s_mov_b32 m0, s10
	s_add_u32 s8, s52, 0x80
	s_addc_u32 s9, s53, 0
	s_add_i32 s78, s51, 0x8000
	s_mov_b32 s10, m0
	s_mov_b32 m0, s78
	s_nop 4
	global_load_lds_dwordx4 v1, s[8:9]
	s_mov_b32 m0, s10
	s_add_u32 s8, s52, 0x20080
	s_addc_u32 s9, s53, 0
	s_add_i32 s79, s51, 0xa000
	s_mov_b32 s10, m0
	s_mov_b32 m0, s79
	s_nop 4
	global_load_lds_dwordx4 v1, s[8:9]
	s_mov_b32 m0, s10
	s_add_u32 s8, s0, 0x40080
	s_addc_u32 s9, s1, 0
	s_add_i32 s80, s51, 0x1c000
	s_mov_b32 s10, m0
	s_mov_b32 m0, s80
	s_nop 4
	global_load_lds_dwordx4 v134, s[8:9]
	s_mov_b32 m0, s10
	s_add_u32 s8, s0, 0x60080
	s_addc_u32 s9, s1, 0
	s_add_i32 s81, s51, 0x1e000
	s_mov_b32 s10, m0
	s_mov_b32 m0, s81
	s_nop 4
	global_load_lds_dwordx4 v134, s[8:9]
	s_mov_b32 m0, s10
	s_waitcnt vmcnt(6)
	s_add_i32 s83, s51, 0xc000
	s_cmpk_lt_u32 s3, 0x100
	v_mov_b64_e32 v[6:7], 0
	s_cselect_b64 s[8:9], -1, 0
	s_ashr_i32 s84, s72, 31
	v_or_b32_e32 v136, s2, v4
	v_add_u32_e32 v137, 0, v2
	v_add_u32_e32 v138, 0, v5
	s_movk_i32 s85, 0x1600
	v_mov_b64_e32 v[8:9], v[6:7]
	v_mov_b64_e32 v[14:15], v[6:7]
	v_mov_b64_e32 v[16:17], v[6:7]
	v_mov_b64_e32 v[22:23], v[6:7]
	v_mov_b64_e32 v[24:25], v[6:7]
	v_mov_b64_e32 v[30:31], v[6:7]
	v_mov_b64_e32 v[32:33], v[6:7]
	v_mov_b64_e32 v[38:39], v[6:7]
	v_mov_b64_e32 v[40:41], v[6:7]
	v_mov_b64_e32 v[46:47], v[6:7]
	v_mov_b64_e32 v[48:49], v[6:7]
	v_mov_b64_e32 v[54:55], v[6:7]
	v_mov_b64_e32 v[56:57], v[6:7]
	v_mov_b64_e32 v[62:63], v[6:7]
	v_mov_b64_e32 v[64:65], v[6:7]
	v_mov_b64_e32 v[2:3], v[6:7]
	v_mov_b64_e32 v[4:5], v[6:7]
	v_mov_b64_e32 v[10:11], v[6:7]
	v_mov_b64_e32 v[12:13], v[6:7]
	v_mov_b64_e32 v[18:19], v[6:7]
	v_mov_b64_e32 v[20:21], v[6:7]
	v_mov_b64_e32 v[26:27], v[6:7]
	v_mov_b64_e32 v[28:29], v[6:7]
	s_waitcnt lgkmcnt(0)
	v_mov_b64_e32 v[34:35], v[6:7]
	v_mov_b64_e32 v[36:37], v[6:7]
	v_mov_b64_e32 v[42:43], v[6:7]
	v_mov_b64_e32 v[44:45], v[6:7]
	v_mov_b64_e32 v[50:51], v[6:7]
	v_mov_b64_e32 v[52:53], v[6:7]
	v_mov_b64_e32 v[58:59], v[6:7]
	v_mov_b64_e32 v[60:61], v[6:7]
	v_mov_b64_e32 v[70:71], v[6:7]
	v_mov_b64_e32 v[72:73], v[6:7]
	v_mov_b64_e32 v[78:79], v[6:7]
	v_mov_b64_e32 v[80:81], v[6:7]
	v_mov_b64_e32 v[86:87], v[6:7]
	v_mov_b64_e32 v[88:89], v[6:7]
	v_mov_b64_e32 v[94:95], v[6:7]
	v_mov_b64_e32 v[96:97], v[6:7]
	v_mov_b64_e32 v[102:103], v[6:7]
	v_mov_b64_e32 v[104:105], v[6:7]
	v_mov_b64_e32 v[110:111], v[6:7]
	v_mov_b64_e32 v[112:113], v[6:7]
	v_mov_b64_e32 v[118:119], v[6:7]
	v_mov_b64_e32 v[120:121], v[6:7]
	v_mov_b64_e32 v[126:127], v[6:7]
	v_mov_b64_e32 v[128:129], v[6:7]
	v_mov_b64_e32 v[66:67], v[6:7]
	v_mov_b64_e32 v[68:69], v[6:7]
	v_mov_b64_e32 v[74:75], v[6:7]
	v_mov_b64_e32 v[76:77], v[6:7]
	v_mov_b64_e32 v[82:83], v[6:7]
	v_mov_b64_e32 v[84:85], v[6:7]
	v_mov_b64_e32 v[90:91], v[6:7]
	v_mov_b64_e32 v[92:93], v[6:7]
	v_mov_b64_e32 v[98:99], v[6:7]
	v_mov_b64_e32 v[100:101], v[6:7]
	v_mov_b64_e32 v[106:107], v[6:7]
	v_mov_b64_e32 v[108:109], v[6:7]
	v_mov_b64_e32 v[114:115], v[6:7]
	v_mov_b64_e32 v[116:117], v[6:7]
	v_mov_b64_e32 v[122:123], v[6:7]
	v_mov_b64_e32 v[124:125], v[6:7]
	v_mov_b64_e32 v[130:131], 0x16b0
	v_mov_b64_e32 v[132:133], 0x16af
	s_barrier
	s_mov_b32 s98, 0
	s_branch .LBB0_153

.LBB0_156:
	v_add_u32_e32 v139, 0x10000, v137
	ds_read_b128 v[140:143], v139
	ds_read_b128 v[144:147], v139 offset:1024
	ds_read_b128 v[148:151], v139 offset:2048
	ds_read_b128 v[152:155], v139 offset:3072
	v_add_u32_e32 v139, 0x14000, v137
	ds_read_b128 v[156:159], v139
	ds_read_b128 v[160:163], v139 offset:1024
	ds_read_b128 v[164:167], v139 offset:2048
	ds_read_b128 v[168:171], v139 offset:3072
	s_add_u32 s0, s52, 0x100
	s_addc_u32 s1, s53, 0
	s_cmp_eq_u32 s89, 12
	s_cselect_b32 s34, s15, s0
	s_cselect_b32 s35, s14, s1
	s_cselect_b32 s56, s41, s87
	s_cselect_b32 s57, s11, s88
	s_add_u32 s54, s34, 0x80
	s_addc_u32 s55, s35, 0
	ds_read_b128 v[172:175], v138
	ds_read_b128 v[176:179], v138 offset:1024
	ds_read_b128 v[180:183], v138 offset:2048
	ds_read_b128 v[184:187], v138 offset:3072
	ds_read_b128 v[188:191], v138 offset:4096
	ds_read_b128 v[192:195], v138 offset:5120
	ds_read_b128 v[196:199], v138 offset:6144
	ds_read_b128 v[200:203], v138 offset:7168
	s_add_u32 s90, s52, 0x40080
	s_addc_u32 s91, s53, 0
	s_mov_b32 s12, m0
	s_mov_b32 m0, s83
	s_nop 4
	global_load_lds_dwordx4 v1, s[90:91]
	s_mov_b32 m0, s12
	s_add_u32 s52, s52, 0x60080
	s_addc_u32 s53, s53, 0
	s_add_i32 s12, s51, 0xe000
	s_mov_b32 s13, m0
	s_mov_b32 m0, s12
	s_nop 4
	global_load_lds_dwordx4 v1, s[52:53]
	s_mov_b32 m0, s13
	s_cmp_eq_u32 s89, -2
	s_cselect_b32 s99, s98, 0
	s_cmp_eq_u32 s99, 0
	s_cbranch_scc1 .Lw8_0_0
	s_waitcnt vmcnt(16)
	s_branch .Lwd_0_0
.Lw8_0_0:
	s_waitcnt vmcnt(8)
.Lwd_0_0:
	s_waitcnt lgkmcnt(0)
	s_barrier
	s_setprio 1
	s_waitcnt lgkmcnt(7)
	v_mfma_f32_16x16x32_bf16 v[122:125], v[140:143], v[172:175], v[122:125]
	v_mfma_f32_16x16x32_bf16 v[114:117], v[148:151], v[172:175], v[114:117]
	s_waitcnt lgkmcnt(5)
	v_mfma_f32_16x16x32_bf16 v[106:109], v[140:143], v[180:183], v[106:109]
	v_mfma_f32_16x16x32_bf16 v[98:101], v[148:151], v[180:183], v[98:101]
	s_waitcnt lgkmcnt(3)
	v_mfma_f32_16x16x32_bf16 v[90:93], v[140:143], v[188:191], v[90:93]
	v_mfma_f32_16x16x32_bf16 v[82:85], v[148:151], v[188:191], v[82:85]
	s_waitcnt lgkmcnt(1)
	v_mfma_f32_16x16x32_bf16 v[74:77], v[140:143], v[196:199], v[74:77]
	v_mfma_f32_16x16x32_bf16 v[66:69], v[148:151], v[196:199], v[66:69]
	v_mfma_f32_16x16x32_bf16 v[122:125], v[144:147], v[176:179], v[122:125]
	v_mfma_f32_16x16x32_bf16 v[114:117], v[152:155], v[176:179], v[114:117]
	v_mfma_f32_16x16x32_bf16 v[106:109], v[144:147], v[184:187], v[106:109]
	v_mfma_f32_16x16x32_bf16 v[98:101], v[152:155], v[184:187], v[98:101]
	v_mfma_f32_16x16x32_bf16 v[90:93], v[144:147], v[192:195], v[90:93]
	v_mfma_f32_16x16x32_bf16 v[82:85], v[152:155], v[192:195], v[82:85]
	s_waitcnt lgkmcnt(0)
	v_mfma_f32_16x16x32_bf16 v[74:77], v[144:147], v[200:203], v[74:77]
	v_mfma_f32_16x16x32_bf16 v[66:69], v[152:155], v[200:203], v[66:69]
	s_setprio 0
	s_setprio 1
	v_mfma_f32_16x16x32_bf16 v[126:129], v[156:159], v[172:175], v[126:129]
	v_mfma_f32_16x16x32_bf16 v[118:121], v[164:167], v[172:175], v[118:121]
	v_mfma_f32_16x16x32_bf16 v[110:113], v[156:159], v[180:183], v[110:113]
	v_mfma_f32_16x16x32_bf16 v[102:105], v[164:167], v[180:183], v[102:105]
	v_mfma_f32_16x16x32_bf16 v[94:97], v[156:159], v[188:191], v[94:97]
	v_mfma_f32_16x16x32_bf16 v[86:89], v[164:167], v[188:191], v[86:89]
	v_mfma_f32_16x16x32_bf16 v[78:81], v[156:159], v[196:199], v[78:81]
	v_mfma_f32_16x16x32_bf16 v[70:73], v[164:167], v[196:199], v[70:73]
	v_mfma_f32_16x16x32_bf16 v[126:129], v[160:163], v[176:179], v[126:129]
	v_mfma_f32_16x16x32_bf16 v[118:121], v[168:171], v[176:179], v[118:121]
	v_mfma_f32_16x16x32_bf16 v[110:113], v[160:163], v[184:187], v[110:113]
	v_mfma_f32_16x16x32_bf16 v[102:105], v[168:171], v[184:187], v[102:105]
	v_mfma_f32_16x16x32_bf16 v[94:97], v[160:163], v[192:195], v[94:97]
	v_mfma_f32_16x16x32_bf16 v[86:89], v[168:171], v[192:195], v[86:89]
	v_mfma_f32_16x16x32_bf16 v[78:81], v[160:163], v[200:203], v[78:81]
	v_mfma_f32_16x16x32_bf16 v[70:73], v[168:171], v[200:203], v[70:73]
	s_setprio 0
	s_barrier
	s_add_u32 s52, s56, 0x20000
	ds_read_b128 v[172:175], v138 offset:16384
	ds_read_b128 v[176:179], v138 offset:17408
	ds_read_b128 v[180:183], v138 offset:18432
	ds_read_b128 v[184:187], v138 offset:19456
	ds_read_b128 v[188:191], v138 offset:20480
	ds_read_b128 v[192:195], v138 offset:21504
	ds_read_b128 v[196:199], v138 offset:22528
	ds_read_b128 v[200:203], v138 offset:23552
	s_mov_b32 s12, m0
	s_mov_b32 m0, s62
	s_nop 4
	global_load_lds_dwordx4 v134, s[56:57]
	s_mov_b32 m0, s12
	s_addc_u32 s53, s57, 0
	s_mov_b32 s12, m0
	s_mov_b32 m0, s63
	s_nop 4
	global_load_lds_dwordx4 v134, s[52:53]
	s_mov_b32 m0, s12
	s_add_u32 s52, s56, 0x40000
	s_addc_u32 s53, s57, 0
	s_mov_b32 s12, m0
	s_mov_b32 m0, s64
	s_nop 4
	global_load_lds_dwordx4 v134, s[52:53]
	s_mov_b32 m0, s12
	s_add_u32 s52, s56, 0x60000
	s_addc_u32 s53, s57, 0
	s_mov_b32 s12, m0
	s_mov_b32 m0, s65
	s_nop 4
	global_load_lds_dwordx4 v134, s[52:53]
	s_mov_b32 m0, s12
	s_add_u32 s52, s34, 0x20000
	s_mov_b32 s12, m0
	s_mov_b32 m0, s51
	s_nop 4
	global_load_lds_dwordx4 v1, s[34:35]
	s_mov_b32 m0, s12
	s_addc_u32 s53, s35, 0
	s_mov_b32 s12, m0
	s_mov_b32 m0, s73
	s_nop 4
	global_load_lds_dwordx4 v1, s[52:53]
	s_mov_b32 m0, s12
	s_cmp_eq_u32 s89, -2
	s_cselect_b32 s99, s98, 0
	s_cmp_eq_u32 s99, 0
	s_cbranch_scc1 .Lw8_0_1
	s_waitcnt vmcnt(16)
	s_branch .Lwd_0_1

.Lwd_0_1:
	s_waitcnt lgkmcnt(0)
	s_barrier
	s_setprio 1
	s_waitcnt lgkmcnt(7)
	v_mfma_f32_16x16x32_bf16 v[58:61], v[140:143], v[172:175], v[58:61]
	v_mfma_f32_16x16x32_bf16 v[50:53], v[148:151], v[172:175], v[50:53]
	s_waitcnt lgkmcnt(5)
	v_mfma_f32_16x16x32_bf16 v[42:45], v[140:143], v[180:183], v[42:45]
	v_mfma_f32_16x16x32_bf16 v[34:37], v[148:151], v[180:183], v[34:37]
	s_waitcnt lgkmcnt(3)
	v_mfma_f32_16x16x32_bf16 v[26:29], v[140:143], v[188:191], v[26:29]
	v_mfma_f32_16x16x32_bf16 v[18:21], v[148:151], v[188:191], v[18:21]
	s_waitcnt lgkmcnt(1)
	v_mfma_f32_16x16x32_bf16 v[10:13], v[140:143], v[196:199], v[10:13]
	v_mfma_f32_16x16x32_bf16 v[2:5], v[148:151], v[196:199], v[2:5]
	v_mfma_f32_16x16x32_bf16 v[58:61], v[144:147], v[176:179], v[58:61]
	v_mfma_f32_16x16x32_bf16 v[50:53], v[152:155], v[176:179], v[50:53]
	v_mfma_f32_16x16x32_bf16 v[42:45], v[144:147], v[184:187], v[42:45]
	v_mfma_f32_16x16x32_bf16 v[34:37], v[152:155], v[184:187], v[34:37]
	v_mfma_f32_16x16x32_bf16 v[26:29], v[144:147], v[192:195], v[26:29]
	v_mfma_f32_16x16x32_bf16 v[18:21], v[152:155], v[192:195], v[18:21]
	s_waitcnt lgkmcnt(0)
	v_mfma_f32_16x16x32_bf16 v[10:13], v[144:147], v[200:203], v[10:13]
	v_mfma_f32_16x16x32_bf16 v[2:5], v[152:155], v[200:203], v[2:5]
	s_setprio 0
	s_setprio 1
	v_mfma_f32_16x16x32_bf16 v[62:65], v[156:159], v[172:175], v[62:65]
	v_mfma_f32_16x16x32_bf16 v[54:57], v[164:167], v[172:175], v[54:57]
	v_mfma_f32_16x16x32_bf16 v[46:49], v[156:159], v[180:183], v[46:49]
	v_mfma_f32_16x16x32_bf16 v[38:41], v[164:167], v[180:183], v[38:41]
	v_mfma_f32_16x16x32_bf16 v[30:33], v[156:159], v[188:191], v[30:33]
	v_mfma_f32_16x16x32_bf16 v[22:25], v[164:167], v[188:191], v[22:25]
	v_mfma_f32_16x16x32_bf16 v[14:17], v[156:159], v[196:199], v[14:17]
	v_mfma_f32_16x16x32_bf16 v[6:9], v[164:167], v[196:199], v[6:9]
	v_mfma_f32_16x16x32_bf16 v[62:65], v[160:163], v[176:179], v[62:65]
	v_mfma_f32_16x16x32_bf16 v[54:57], v[168:171], v[176:179], v[54:57]
	v_mfma_f32_16x16x32_bf16 v[46:49], v[160:163], v[184:187], v[46:49]
	v_mfma_f32_16x16x32_bf16 v[38:41], v[168:171], v[184:187], v[38:41]
	v_mfma_f32_16x16x32_bf16 v[30:33], v[160:163], v[192:195], v[30:33]
	v_mfma_f32_16x16x32_bf16 v[22:25], v[168:171], v[192:195], v[22:25]
	v_mfma_f32_16x16x32_bf16 v[14:17], v[160:163], v[200:203], v[14:17]
	v_mfma_f32_16x16x32_bf16 v[6:9], v[168:171], v[200:203], v[6:9]
	s_setprio 0
	s_barrier
	v_add_u32_e32 v139, 0x18000, v137
	ds_read_b128 v[140:143], v139
	ds_read_b128 v[144:147], v139 offset:1024
	ds_read_b128 v[148:151], v139 offset:2048
	ds_read_b128 v[152:155], v139 offset:3072
	v_add_u32_e32 v139, 0x1c000, v137
	ds_read_b128 v[156:159], v139
	ds_read_b128 v[160:163], v139 offset:1024
	ds_read_b128 v[164:167], v139 offset:2048
	ds_read_b128 v[168:171], v139 offset:3072
	ds_read_b128 v[172:175], v138 offset:32768
	ds_read_b128 v[176:179], v138 offset:33792
	ds_read_b128 v[180:183], v138 offset:34816
	ds_read_b128 v[184:187], v138 offset:35840
	ds_read_b128 v[188:191], v138 offset:36864
	ds_read_b128 v[192:195], v138 offset:37888
	ds_read_b128 v[196:199], v138 offset:38912
	ds_read_b128 v[200:203], v138 offset:39936
	s_add_u32 s52, s34, 0x40000
	s_addc_u32 s53, s35, 0
	s_mov_b32 s12, m0
	s_mov_b32 m0, s74
	s_nop 4
	global_load_lds_dwordx4 v1, s[52:53]
	s_mov_b32 m0, s12
	s_add_u32 s52, s34, 0x60000
	s_addc_u32 s53, s35, 0
	s_mov_b32 s12, m0
	s_mov_b32 m0, s75
	s_nop 4
	global_load_lds_dwordx4 v1, s[52:53]
	s_mov_b32 m0, s12
	s_waitcnt vmcnt(8)
	s_waitcnt lgkmcnt(0)
	s_barrier
	s_setprio 1
	s_waitcnt lgkmcnt(7)
	v_mfma_f32_16x16x32_bf16 v[122:125], v[140:143], v[172:175], v[122:125]
	v_mfma_f32_16x16x32_bf16 v[114:117], v[148:151], v[172:175], v[114:117]
	s_waitcnt lgkmcnt(5)
	v_mfma_f32_16x16x32_bf16 v[106:109], v[140:143], v[180:183], v[106:109]
	v_mfma_f32_16x16x32_bf16 v[98:101], v[148:151], v[180:183], v[98:101]
	s_waitcnt lgkmcnt(3)
	v_mfma_f32_16x16x32_bf16 v[90:93], v[140:143], v[188:191], v[90:93]
	v_mfma_f32_16x16x32_bf16 v[82:85], v[148:151], v[188:191], v[82:85]
	s_waitcnt lgkmcnt(1)
	v_mfma_f32_16x16x32_bf16 v[74:77], v[140:143], v[196:199], v[74:77]
	v_mfma_f32_16x16x32_bf16 v[66:69], v[148:151], v[196:199], v[66:69]
	v_mfma_f32_16x16x32_bf16 v[122:125], v[144:147], v[176:179], v[122:125]
	v_mfma_f32_16x16x32_bf16 v[114:117], v[152:155], v[176:179], v[114:117]
	v_mfma_f32_16x16x32_bf16 v[106:109], v[144:147], v[184:187], v[106:109]
	v_mfma_f32_16x16x32_bf16 v[98:101], v[152:155], v[184:187], v[98:101]
	v_mfma_f32_16x16x32_bf16 v[90:93], v[144:147], v[192:195], v[90:93]
	v_mfma_f32_16x16x32_bf16 v[82:85], v[152:155], v[192:195], v[82:85]
	s_waitcnt lgkmcnt(0)
	v_mfma_f32_16x16x32_bf16 v[74:77], v[144:147], v[200:203], v[74:77]
	v_mfma_f32_16x16x32_bf16 v[66:69], v[152:155], v[200:203], v[66:69]
	s_setprio 0
	s_setprio 1
	v_mfma_f32_16x16x32_bf16 v[126:129], v[156:159], v[172:175], v[126:129]
	v_mfma_f32_16x16x32_bf16 v[118:121], v[164:167], v[172:175], v[118:121]
	v_mfma_f32_16x16x32_bf16 v[110:113], v[156:159], v[180:183], v[110:113]
	v_mfma_f32_16x16x32_bf16 v[102:105], v[164:167], v[180:183], v[102:105]
	v_mfma_f32_16x16x32_bf16 v[94:97], v[156:159], v[188:191], v[94:97]
	v_mfma_f32_16x16x32_bf16 v[86:89], v[164:167], v[188:191], v[86:89]
	v_mfma_f32_16x16x32_bf16 v[78:81], v[156:159], v[196:199], v[78:81]
	v_mfma_f32_16x16x32_bf16 v[70:73], v[164:167], v[196:199], v[70:73]
	v_mfma_f32_16x16x32_bf16 v[126:129], v[160:163], v[176:179], v[126:129]
	v_mfma_f32_16x16x32_bf16 v[118:121], v[168:171], v[176:179], v[118:121]
	v_mfma_f32_16x16x32_bf16 v[110:113], v[160:163], v[184:187], v[110:113]
	v_mfma_f32_16x16x32_bf16 v[102:105], v[168:171], v[184:187], v[102:105]
	v_mfma_f32_16x16x32_bf16 v[94:97], v[160:163], v[192:195], v[94:97]
	v_mfma_f32_16x16x32_bf16 v[86:89], v[168:171], v[192:195], v[86:89]
	v_mfma_f32_16x16x32_bf16 v[78:81], v[160:163], v[200:203], v[78:81]
	v_mfma_f32_16x16x32_bf16 v[70:73], v[168:171], v[200:203], v[70:73]
	s_setprio 0
	s_barrier
	s_add_u32 s52, s56, 0x80
	s_addc_u32 s53, s57, 0
	ds_read_b128 v[172:175], v138 offset:49152
	ds_read_b128 v[176:179], v138 offset:50176
	ds_read_b128 v[180:183], v138 offset:51200
	ds_read_b128 v[184:187], v138 offset:52224
	ds_read_b128 v[188:191], v138 offset:53248
	ds_read_b128 v[192:195], v138 offset:54272
	ds_read_b128 v[196:199], v138 offset:55296
	ds_read_b128 v[200:203], v138 offset:56320
	s_mov_b32 s12, m0
	s_mov_b32 m0, s76
	s_nop 4
	global_load_lds_dwordx4 v134, s[52:53]
	s_mov_b32 m0, s12
	s_add_u32 s52, s56, 0x20080
	s_addc_u32 s53, s57, 0
	s_mov_b32 s12, m0
	s_mov_b32 m0, s77
	s_nop 4
	global_load_lds_dwordx4 v134, s[52:53]
	s_mov_b32 m0, s12
	s_add_u32 s52, s56, 0x40080
	s_addc_u32 s53, s57, 0
	s_mov_b32 s12, m0
	s_mov_b32 m0, s80
	s_nop 4
	global_load_lds_dwordx4 v134, s[52:53]
	s_mov_b32 m0, s12
	s_add_u32 s52, s56, 0x60080
	s_addc_u32 s53, s57, 0
	s_mov_b32 s12, m0
	s_mov_b32 m0, s81
	s_nop 4
	global_load_lds_dwordx4 v134, s[52:53]
	s_mov_b32 m0, s12
	s_add_u32 s34, s34, 0x20080
	s_mov_b32 s12, m0
	s_mov_b32 m0, s78
	s_nop 4
	global_load_lds_dwordx4 v1, s[54:55]
	s_mov_b32 m0, s12
	s_addc_u32 s35, s35, 0
	s_mov_b32 s12, m0
	s_mov_b32 m0, s79
	s_nop 4
	global_load_lds_dwordx4 v1, s[34:35]
	s_mov_b32 m0, s12
	s_waitcnt vmcnt(8)
	s_waitcnt lgkmcnt(0)
	s_barrier
	s_setprio 1
	s_waitcnt lgkmcnt(7)
	v_mfma_f32_16x16x32_bf16 v[58:61], v[140:143], v[172:175], v[58:61]
	v_mfma_f32_16x16x32_bf16 v[50:53], v[148:151], v[172:175], v[50:53]
	s_waitcnt lgkmcnt(5)
	v_mfma_f32_16x16x32_bf16 v[42:45], v[140:143], v[180:183], v[42:45]
	v_mfma_f32_16x16x32_bf16 v[34:37], v[148:151], v[180:183], v[34:37]
	s_waitcnt lgkmcnt(3)
	v_mfma_f32_16x16x32_bf16 v[26:29], v[140:143], v[188:191], v[26:29]
	v_mfma_f32_16x16x32_bf16 v[18:21], v[148:151], v[188:191], v[18:21]
	s_waitcnt lgkmcnt(1)
	v_mfma_f32_16x16x32_bf16 v[10:13], v[140:143], v[196:199], v[10:13]
	v_mfma_f32_16x16x32_bf16 v[2:5], v[148:151], v[196:199], v[2:5]
	v_mfma_f32_16x16x32_bf16 v[58:61], v[144:147], v[176:179], v[58:61]
	v_mfma_f32_16x16x32_bf16 v[50:53], v[152:155], v[176:179], v[50:53]
	v_mfma_f32_16x16x32_bf16 v[42:45], v[144:147], v[184:187], v[42:45]
	v_mfma_f32_16x16x32_bf16 v[34:37], v[152:155], v[184:187], v[34:37]
	v_mfma_f32_16x16x32_bf16 v[26:29], v[144:147], v[192:195], v[26:29]
	v_mfma_f32_16x16x32_bf16 v[18:21], v[152:155], v[192:195], v[18:21]
	s_waitcnt lgkmcnt(0)
	v_mfma_f32_16x16x32_bf16 v[10:13], v[144:147], v[200:203], v[10:13]
	v_mfma_f32_16x16x32_bf16 v[2:5], v[152:155], v[200:203], v[2:5]
	s_setprio 0
	s_setprio 1
	v_mfma_f32_16x16x32_bf16 v[62:65], v[156:159], v[172:175], v[62:65]
	v_mfma_f32_16x16x32_bf16 v[54:57], v[164:167], v[172:175], v[54:57]
	v_mfma_f32_16x16x32_bf16 v[46:49], v[156:159], v[180:183], v[46:49]
	v_mfma_f32_16x16x32_bf16 v[38:41], v[164:167], v[180:183], v[38:41]
	v_mfma_f32_16x16x32_bf16 v[30:33], v[156:159], v[188:191], v[30:33]
	v_mfma_f32_16x16x32_bf16 v[22:25], v[164:167], v[188:191], v[22:25]
	v_mfma_f32_16x16x32_bf16 v[14:17], v[156:159], v[196:199], v[14:17]
	v_mfma_f32_16x16x32_bf16 v[6:9], v[164:167], v[196:199], v[6:9]
	v_mfma_f32_16x16x32_bf16 v[62:65], v[160:163], v[176:179], v[62:65]
	v_mfma_f32_16x16x32_bf16 v[54:57], v[168:171], v[176:179], v[54:57]
	v_mfma_f32_16x16x32_bf16 v[46:49], v[160:163], v[184:187], v[46:49]
	v_mfma_f32_16x16x32_bf16 v[38:41], v[168:171], v[184:187], v[38:41]
	v_mfma_f32_16x16x32_bf16 v[30:33], v[160:163], v[192:195], v[30:33]
	v_mfma_f32_16x16x32_bf16 v[22:25], v[168:171], v[192:195], v[22:25]
	v_mfma_f32_16x16x32_bf16 v[14:17], v[160:163], v[200:203], v[14:17]
	v_mfma_f32_16x16x32_bf16 v[6:9], v[168:171], v[200:203], v[6:9]
	s_setprio 0
	s_barrier
	s_add_i32 s89, s89, 2
	s_add_u32 s87, s87, 0x100
	s_addc_u32 s88, s88, 0
	s_cmp_gt_u32 s89, 13
	s_mov_b64 s[52:53], s[0:1]
	s_cbranch_scc0 .LBB0_156
	s_and_b64 vcc, exec, s[8:9]
	s_cbranch_vccz .LBB0_159
	s_barrier
.LBB0_159:
	v_exp_f32_e64 v140, -v122
	v_exp_f32_e64 v141, -v123
	v_pk_mul_f32 v[128:129], v[124:125], v[128:129]
	v_exp_f32_e64 v124, -v124
	v_exp_f32_e64 v125, -v125
	v_pk_add_f32 v[140:141], v[140:141], 1.0 op_sel_hi:[1,0]
	v_pk_mul_f32 v[122:123], v[122:123], v[126:127]
	v_rcp_f32_e32 v126, v140
	v_rcp_f32_e32 v127, v141
	v_pk_add_f32 v[124:125], v[124:125], 1.0 op_sel_hi:[1,0]
	v_lshl_or_b32 v142, s86, 7, v136
	v_rcp_f32_e32 v124, v124
	v_rcp_f32_e32 v125, v125
	v_pk_mul_f32 v[122:123], v[126:127], v[122:123]
	v_exp_f32_e64 v126, -v114
	v_exp_f32_e64 v127, -v115
	v_pk_mul_f32 v[124:125], v[124:125], v[128:129]
	v_exp_f32_e64 v128, -v116
	v_exp_f32_e64 v129, -v117
	v_pk_add_f32 v[126:127], v[126:127], 1.0 op_sel_hi:[1,0]
	v_pk_mul_f32 v[114:115], v[114:115], v[118:119]
	v_rcp_f32_e32 v126, v126
	v_rcp_f32_e32 v127, v127
	v_pk_add_f32 v[128:129], v[128:129], 1.0 op_sel_hi:[1,0]
	v_pk_mul_f32 v[116:117], v[116:117], v[120:121]
	v_rcp_f32_e32 v128, v128
	v_rcp_f32_e32 v129, v129
	v_pk_mul_f32 v[114:115], v[126:127], v[114:115]
	v_cvt_pk_bf16_f32 v118, v122, v123
	v_cvt_pk_bf16_f32 v119, v124, v125
	v_exp_f32_e64 v124, -v106
	v_exp_f32_e64 v125, -v107
	v_lshl_add_u32 v139, s50, 8, v135
	v_ashrrev_i32_e32 v143, 31, v142
	v_pk_mul_f32 v[116:117], v[128:129], v[116:117]
	v_cvt_pk_bf16_f32 v120, v114, v115
	v_mov_b64_e32 v[114:115], s[18:19]
	v_pk_mul_f32 v[112:113], v[108:109], v[112:113]
	v_exp_f32_e64 v108, -v108
	v_exp_f32_e64 v109, -v109
	v_cvt_pk_bf16_f32 v121, v116, v117
	v_mad_i64_i32 v[122:123], s[0:1], v139, s85, v[114:115]
	v_lshlrev_b64 v[116:117], 1, v[142:143]
	v_lshl_add_u64 v[122:123], v[122:123], 0, v[116:117]
	global_store_dwordx4 v[122:123], v[118:121], off
	v_pk_mul_f32 v[106:107], v[106:107], v[110:111]
	v_pk_add_f32 v[108:109], v[108:109], 1.0 op_sel_hi:[1,0]
	v_pk_add_f32 v[118:119], v[124:125], 1.0 op_sel_hi:[1,0]
	v_rcp_f32_e32 v108, v108
	v_rcp_f32_e32 v110, v118
	v_rcp_f32_e32 v111, v119
	v_rcp_f32_e32 v109, v109
	v_pk_mul_f32 v[96:97], v[92:93], v[96:97]
	v_exp_f32_e64 v92, -v92
	v_pk_mul_f32 v[106:107], v[110:111], v[106:107]
	v_exp_f32_e64 v110, -v98
	v_exp_f32_e64 v111, -v99
	v_pk_mul_f32 v[108:109], v[108:109], v[112:113]
	v_exp_f32_e64 v112, -v100
	v_exp_f32_e64 v113, -v101
	v_pk_add_f32 v[110:111], v[110:111], 1.0 op_sel_hi:[1,0]
	v_pk_mul_f32 v[98:99], v[98:99], v[102:103]
	v_rcp_f32_e32 v110, v110
	v_rcp_f32_e32 v111, v111
	v_pk_add_f32 v[112:113], v[112:113], 1.0 op_sel_hi:[1,0]
	v_pk_mul_f32 v[100:101], v[100:101], v[104:105]
	v_rcp_f32_e32 v112, v112
	v_rcp_f32_e32 v113, v113
	v_pk_mul_f32 v[102:103], v[110:111], v[98:99]
	v_cvt_pk_bf16_f32 v98, v106, v107
	v_cvt_pk_bf16_f32 v99, v108, v109
	v_pk_mul_f32 v[104:105], v[112:113], v[100:101]
	v_cvt_pk_bf16_f32 v100, v102, v103
	v_exp_f32_e64 v102, -v90
	v_exp_f32_e64 v103, -v91
	v_cvt_pk_bf16_f32 v101, v104, v105
	v_or_b32_e32 v104, 16, v139
	v_exp_f32_e64 v93, -v93
	v_mad_i64_i32 v[104:105], s[0:1], v104, s85, v[114:115]
	v_lshl_add_u64 v[104:105], v[104:105], 0, v[116:117]
	global_store_dwordx4 v[104:105], v[98:101], off
	v_pk_mul_f32 v[90:91], v[90:91], v[94:95]
	v_pk_add_f32 v[92:93], v[92:93], 1.0 op_sel_hi:[1,0]
	v_pk_add_f32 v[98:99], v[102:103], 1.0 op_sel_hi:[1,0]
	v_rcp_f32_e32 v92, v92
	v_rcp_f32_e32 v94, v98
	v_rcp_f32_e32 v95, v99
	v_rcp_f32_e32 v93, v93
	v_pk_mul_f32 v[80:81], v[76:77], v[80:81]
	v_exp_f32_e64 v76, -v76
	v_pk_mul_f32 v[90:91], v[94:95], v[90:91]
	v_exp_f32_e64 v94, -v82
	v_exp_f32_e64 v95, -v83
	v_pk_mul_f32 v[92:93], v[92:93], v[96:97]
	v_exp_f32_e64 v96, -v84
	v_exp_f32_e64 v97, -v85
	v_pk_add_f32 v[94:95], v[94:95], 1.0 op_sel_hi:[1,0]
	v_pk_mul_f32 v[82:83], v[82:83], v[86:87]
	v_rcp_f32_e32 v94, v94
	v_rcp_f32_e32 v95, v95
	v_pk_add_f32 v[96:97], v[96:97], 1.0 op_sel_hi:[1,0]
	v_pk_mul_f32 v[84:85], v[84:85], v[88:89]
	v_rcp_f32_e32 v96, v96
	v_rcp_f32_e32 v97, v97
	v_pk_mul_f32 v[86:87], v[94:95], v[82:83]
	v_exp_f32_e64 v77, -v77
	v_cvt_pk_bf16_f32 v82, v90, v91
	v_pk_mul_f32 v[88:89], v[96:97], v[84:85]
	v_cvt_pk_bf16_f32 v83, v92, v93
	v_cvt_pk_bf16_f32 v84, v86, v87
	v_exp_f32_e64 v86, -v74
	v_exp_f32_e64 v87, -v75
	v_cvt_pk_bf16_f32 v85, v88, v89
	v_or_b32_e32 v88, 32, v139
	v_mad_i64_i32 v[88:89], s[0:1], v88, s85, v[114:115]
	v_lshl_add_u64 v[88:89], v[88:89], 0, v[116:117]
	v_pk_add_f32 v[76:77], v[76:77], 1.0 op_sel_hi:[1,0]
	global_store_dwordx4 v[88:89], v[82:85], off
	v_rcp_f32_e32 v76, v76
	v_rcp_f32_e32 v77, v77
	v_pk_add_f32 v[82:83], v[86:87], 1.0 op_sel_hi:[1,0]
	v_pk_mul_f32 v[74:75], v[74:75], v[78:79]
	v_rcp_f32_e32 v78, v82
	v_rcp_f32_e32 v79, v83
	v_pk_mul_f32 v[76:77], v[76:77], v[80:81]
	v_exp_f32_e64 v80, -v68
	v_exp_f32_e64 v81, -v69
	v_pk_mul_f32 v[74:75], v[78:79], v[74:75]
	v_exp_f32_e64 v78, -v66
	v_exp_f32_e64 v79, -v67
	v_pk_add_f32 v[80:81], v[80:81], 1.0 op_sel_hi:[1,0]
	v_pk_mul_f32 v[68:69], v[68:69], v[72:73]
	v_rcp_f32_e32 v80, v80
	v_pk_add_f32 v[78:79], v[78:79], 1.0 op_sel_hi:[1,0]
	v_rcp_f32_e32 v81, v81
	v_rcp_f32_e32 v78, v78
	v_rcp_f32_e32 v79, v79
	v_pk_mul_f32 v[66:67], v[66:67], v[70:71]
	v_pk_mul_f32 v[72:73], v[80:81], v[68:69]
	v_pk_mul_f32 v[64:65], v[60:61], v[64:65]
	v_pk_mul_f32 v[70:71], v[78:79], v[66:67]
	v_cvt_pk_bf16_f32 v66, v74, v75
	v_cvt_pk_bf16_f32 v67, v76, v77
	v_exp_f32_e64 v60, -v60
	v_cvt_pk_bf16_f32 v68, v70, v71
	v_cvt_pk_bf16_f32 v69, v72, v73
	v_exp_f32_e64 v72, -v58
	v_exp_f32_e64 v73, -v59
	v_or_b32_e32 v70, 48, v139
	v_exp_f32_e64 v61, -v61
	v_mad_i64_i32 v[70:71], s[0:1], v70, s85, v[114:115]
	v_lshl_add_u64 v[70:71], v[70:71], 0, v[116:117]
	global_store_dwordx4 v[70:71], v[66:69], off
	v_pk_mul_f32 v[58:59], v[58:59], v[62:63]
	v_pk_add_f32 v[60:61], v[60:61], 1.0 op_sel_hi:[1,0]
	v_pk_add_f32 v[66:67], v[72:73], 1.0 op_sel_hi:[1,0]
	v_rcp_f32_e32 v60, v60
	v_rcp_f32_e32 v62, v66
	v_rcp_f32_e32 v63, v67
	v_rcp_f32_e32 v61, v61
	v_add_u32_e32 v68, 0x80, v139
	v_pk_mul_f32 v[48:49], v[44:45], v[48:49]
	v_pk_mul_f32 v[58:59], v[62:63], v[58:59]
	v_exp_f32_e64 v62, -v50
	v_exp_f32_e64 v63, -v51
	v_pk_mul_f32 v[60:61], v[60:61], v[64:65]
	v_exp_f32_e64 v64, -v52
	v_exp_f32_e64 v65, -v53
	v_pk_add_f32 v[62:63], v[62:63], 1.0 op_sel_hi:[1,0]
	v_pk_mul_f32 v[50:51], v[50:51], v[54:55]
	v_rcp_f32_e32 v62, v62
	v_rcp_f32_e32 v63, v63
	v_pk_add_f32 v[64:65], v[64:65], 1.0 op_sel_hi:[1,0]
	v_pk_mul_f32 v[52:53], v[52:53], v[56:57]
	v_rcp_f32_e32 v64, v64
	v_rcp_f32_e32 v65, v65
	v_pk_mul_f32 v[54:55], v[62:63], v[50:51]
	v_cvt_pk_bf16_f32 v50, v58, v59
	v_cvt_pk_bf16_f32 v51, v60, v61
	v_pk_mul_f32 v[56:57], v[64:65], v[52:53]
	v_cvt_pk_bf16_f32 v52, v54, v55
	v_exp_f32_e64 v54, -v42
	v_exp_f32_e64 v55, -v43
	v_exp_f32_e64 v44, -v44
	v_exp_f32_e64 v45, -v45
	v_cvt_pk_bf16_f32 v53, v56, v57
	v_mad_i64_i32 v[56:57], s[0:1], v68, s85, v[114:115]
	v_lshl_add_u64 v[56:57], v[56:57], 0, v[116:117]
	global_store_dwordx4 v[56:57], v[50:53], off
	v_pk_mul_f32 v[42:43], v[42:43], v[46:47]
	v_pk_add_f32 v[44:45], v[44:45], 1.0 op_sel_hi:[1,0]
	v_pk_add_f32 v[50:51], v[54:55], 1.0 op_sel_hi:[1,0]
	v_rcp_f32_e32 v44, v44
	v_rcp_f32_e32 v46, v50
	v_rcp_f32_e32 v47, v51
	v_rcp_f32_e32 v45, v45
	v_pk_mul_f32 v[32:33], v[28:29], v[32:33]
	v_exp_f32_e64 v28, -v28
	v_pk_mul_f32 v[42:43], v[46:47], v[42:43]
	v_exp_f32_e64 v46, -v34
	v_exp_f32_e64 v47, -v35
	v_pk_mul_f32 v[44:45], v[44:45], v[48:49]
	v_exp_f32_e64 v48, -v36
	v_exp_f32_e64 v49, -v37
	v_pk_add_f32 v[46:47], v[46:47], 1.0 op_sel_hi:[1,0]
	v_pk_mul_f32 v[34:35], v[34:35], v[38:39]
	v_rcp_f32_e32 v46, v46
	v_rcp_f32_e32 v47, v47
	v_pk_add_f32 v[48:49], v[48:49], 1.0 op_sel_hi:[1,0]
	v_pk_mul_f32 v[36:37], v[36:37], v[40:41]
	v_rcp_f32_e32 v48, v48
	v_rcp_f32_e32 v49, v49
	v_pk_mul_f32 v[38:39], v[46:47], v[34:35]
	v_cvt_pk_bf16_f32 v34, v42, v43
	v_cvt_pk_bf16_f32 v35, v44, v45
	v_pk_mul_f32 v[40:41], v[48:49], v[36:37]
	v_cvt_pk_bf16_f32 v36, v38, v39
	v_exp_f32_e64 v38, -v26
	v_exp_f32_e64 v39, -v27
	v_cvt_pk_bf16_f32 v37, v40, v41
	v_add_u32_e32 v40, 0x90, v139
	v_exp_f32_e64 v29, -v29
	v_mad_i64_i32 v[40:41], s[0:1], v40, s85, v[114:115]
	v_lshl_add_u64 v[40:41], v[40:41], 0, v[116:117]
	global_store_dwordx4 v[40:41], v[34:37], off
	v_pk_mul_f32 v[26:27], v[26:27], v[30:31]
	v_pk_add_f32 v[28:29], v[28:29], 1.0 op_sel_hi:[1,0]
	v_pk_add_f32 v[34:35], v[38:39], 1.0 op_sel_hi:[1,0]
	v_rcp_f32_e32 v28, v28
	v_rcp_f32_e32 v30, v34
	v_rcp_f32_e32 v31, v35
	v_rcp_f32_e32 v29, v29
	v_pk_mul_f32 v[16:17], v[12:13], v[16:17]
	v_exp_f32_e64 v12, -v12
	v_pk_mul_f32 v[26:27], v[30:31], v[26:27]
	v_exp_f32_e64 v30, -v18
	v_exp_f32_e64 v31, -v19
	v_pk_mul_f32 v[28:29], v[28:29], v[32:33]
	v_exp_f32_e64 v32, -v20
	v_exp_f32_e64 v33, -v21
	v_pk_add_f32 v[30:31], v[30:31], 1.0 op_sel_hi:[1,0]
	v_pk_mul_f32 v[18:19], v[18:19], v[22:23]
	v_rcp_f32_e32 v30, v30
	v_rcp_f32_e32 v31, v31
	v_pk_add_f32 v[32:33], v[32:33], 1.0 op_sel_hi:[1,0]
	v_pk_mul_f32 v[20:21], v[20:21], v[24:25]
	v_rcp_f32_e32 v32, v32
	v_rcp_f32_e32 v33, v33
	v_pk_mul_f32 v[22:23], v[30:31], v[18:19]
	v_cvt_pk_bf16_f32 v18, v26, v27
	v_cvt_pk_bf16_f32 v19, v28, v29
	v_pk_mul_f32 v[24:25], v[32:33], v[20:21]
	v_cvt_pk_bf16_f32 v20, v22, v23
	v_exp_f32_e64 v22, -v10
	v_exp_f32_e64 v23, -v11
	v_cvt_pk_bf16_f32 v21, v24, v25
	v_add_u32_e32 v24, 0xa0, v139
	v_exp_f32_e64 v13, -v13
	v_mad_i64_i32 v[24:25], s[0:1], v24, s85, v[114:115]
	v_lshl_add_u64 v[24:25], v[24:25], 0, v[116:117]
	global_store_dwordx4 v[24:25], v[18:21], off
	v_pk_mul_f32 v[10:11], v[10:11], v[14:15]
	v_pk_add_f32 v[12:13], v[12:13], 1.0 op_sel_hi:[1,0]
	v_pk_add_f32 v[18:19], v[22:23], 1.0 op_sel_hi:[1,0]
	v_rcp_f32_e32 v12, v12
	v_rcp_f32_e32 v14, v18
	v_rcp_f32_e32 v15, v19
	v_rcp_f32_e32 v13, v13
	s_andn2_b64 vcc, exec, s[2:3]
	v_pk_mul_f32 v[10:11], v[14:15], v[10:11]
	v_exp_f32_e64 v14, -v2
	v_exp_f32_e64 v15, -v3
	v_pk_mul_f32 v[12:13], v[12:13], v[16:17]
	v_exp_f32_e64 v16, -v4
	v_exp_f32_e64 v17, -v5
	v_pk_add_f32 v[14:15], v[14:15], 1.0 op_sel_hi:[1,0]
	v_pk_mul_f32 v[2:3], v[2:3], v[6:7]
	v_rcp_f32_e32 v14, v14
	v_rcp_f32_e32 v15, v15
	v_pk_add_f32 v[16:17], v[16:17], 1.0 op_sel_hi:[1,0]
	v_pk_mul_f32 v[4:5], v[4:5], v[8:9]
	v_rcp_f32_e32 v16, v16
	v_rcp_f32_e32 v17, v17
	v_pk_mul_f32 v[6:7], v[14:15], v[2:3]
	v_cvt_pk_bf16_f32 v2, v10, v11
	v_cvt_pk_bf16_f32 v3, v12, v13
	v_pk_mul_f32 v[8:9], v[16:17], v[4:5]
	v_cvt_pk_bf16_f32 v4, v6, v7
	v_add_u32_e32 v6, 0xb0, v139
	v_mad_i64_i32 v[6:7], s[0:1], v6, s85, v[114:115]
	v_cvt_pk_bf16_f32 v5, v8, v9
	v_lshl_add_u64 v[6:7], v[6:7], 0, v[116:117]
	s_mov_b64 s[0:1], -1
	global_store_dwordx4 v[6:7], v[2:5], off
	s_mov_b32 s98, 1
	s_cbranch_vccnz .LBB0_152
	s_andn2_b64 vcc, exec, s[6:7]
	v_mov_b64 v[122:123], 0
	v_mov_b64 v[124:125], 0
	v_mov_b64 v[114:115], 0
	v_mov_b64 v[116:117], 0
	v_mov_b64 v[106:107], 0
	v_mov_b64 v[108:109], 0
	v_mov_b64 v[98:99], 0
	v_mov_b64 v[100:101], 0
	v_mov_b64 v[90:91], 0
	v_mov_b64 v[92:93], 0
	v_mov_b64 v[82:83], 0
	v_mov_b64 v[84:85], 0
	v_mov_b64 v[74:75], 0
	v_mov_b64 v[76:77], 0
	v_mov_b64 v[66:67], 0
	v_mov_b64 v[68:69], 0
	v_mov_b64 v[126:127], 0
	v_mov_b64 v[128:129], 0
	v_mov_b64 v[118:119], 0
	v_mov_b64 v[120:121], 0
	v_mov_b64 v[110:111], 0
	v_mov_b64 v[112:113], 0
	v_mov_b64 v[102:103], 0
	v_mov_b64 v[104:105], 0
	v_mov_b64 v[94:95], 0
	v_mov_b64 v[96:97], 0
	v_mov_b64 v[86:87], 0
	v_mov_b64 v[88:89], 0
	v_mov_b64 v[78:79], 0
	v_mov_b64 v[80:81], 0
	v_mov_b64 v[70:71], 0
	v_mov_b64 v[72:73], 0
	v_mov_b64 v[58:59], 0
	v_mov_b64 v[60:61], 0
	v_mov_b64 v[50:51], 0
	v_mov_b64 v[52:53], 0
	v_mov_b64 v[42:43], 0
	v_mov_b64 v[44:45], 0
	v_mov_b64 v[34:35], 0
	v_mov_b64 v[36:37], 0
	v_mov_b64 v[26:27], 0
	v_mov_b64 v[28:29], 0
	v_mov_b64 v[18:19], 0
	v_mov_b64 v[20:21], 0
	v_mov_b64 v[10:11], 0
	v_mov_b64 v[12:13], 0
	v_mov_b64 v[2:3], 0
	v_mov_b64 v[4:5], 0
	v_mov_b64 v[62:63], 0
	v_mov_b64 v[64:65], 0
	v_mov_b64 v[54:55], 0
	v_mov_b64 v[56:57], 0
	v_mov_b64 v[46:47], 0
	v_mov_b64 v[48:49], 0
	v_mov_b64 v[38:39], 0
	v_mov_b64 v[40:41], 0
	v_mov_b64 v[30:31], 0
	v_mov_b64 v[32:33], 0
	v_mov_b64 v[22:23], 0
	v_mov_b64 v[24:25], 0
	v_mov_b64 v[14:15], 0
	v_mov_b64 v[16:17], 0
	v_mov_b64 v[6:7], 0
	v_mov_b64 v[8:9], 0
	s_cbranch_vccnz .LBB0_151
	s_barrier
	s_branch .LBB0_151

.LBB0_551:
	v_lshrrev_b32_e32 v4, 1, v2
	v_and_b32_e32 v4, 24, v4
	v_and_b32_e32 v3, 15, v2
	v_lshlrev_b32_e32 v5, 1, v4
	v_lshlrev_b32_e32 v2, 2, v2
	v_lshl_or_b32 v137, s10, 6, v3
	v_lshl_or_b32 v3, v3, 6, v5
	s_lshl_b32 s2, s10, 13
	v_and_b32_e32 v2, 32, v2
	v_bitop3_b32 v5, v3, s2, v2 bitop3:0xde
	s_lshl_b32 s2, s11, 5
	s_and_b32 s2, s2, 0x60
	s_lshl_b32 s3, s2, 7
	s_add_u32 s10, s0, 0x80
	s_addc_u32 s11, s1, 0
	s_add_i32 s63, s43, 0x18000
	v_bitop3_b32 v6, v3, s3, v2 bitop3:0xde
	s_waitcnt vmcnt(2)
	s_barrier
	s_mov_b32 s3, m0
	s_mov_b32 m0, s63
	s_nop 4
	global_load_lds_dwordx4 v136, s[10:11]
	s_mov_b32 m0, s3
	s_add_u32 s10, s0, 0x20080
	s_addc_u32 s11, s1, 0
	s_add_i32 s64, s43, 0x1a000
	s_mov_b32 s3, m0
	s_mov_b32 m0, s64
	s_nop 4
	global_load_lds_dwordx4 v136, s[10:11]
	s_mov_b32 m0, s3
	s_add_u32 s10, s44, 0x80
	s_addc_u32 s11, s45, 0
	s_add_i32 s65, s43, 0x8000
	s_mov_b32 s3, m0
	s_mov_b32 m0, s65
	s_nop 4
	global_load_lds_dwordx4 v1, s[10:11]
	s_mov_b32 m0, s3
	s_add_u32 s10, s44, 0x20080
	s_addc_u32 s11, s45, 0
	s_add_i32 s66, s43, 0xa000
	s_mov_b32 s3, m0
	s_mov_b32 m0, s66
	s_nop 4
	global_load_lds_dwordx4 v1, s[10:11]
	s_mov_b32 m0, s3
	s_add_u32 s10, s0, 0x40080
	s_addc_u32 s11, s1, 0
	s_add_i32 s67, s43, 0x1c000
	s_mov_b32 s3, m0
	s_mov_b32 m0, s67
	s_nop 4
	global_load_lds_dwordx4 v136, s[10:11]
	s_mov_b32 m0, s3
	s_add_u32 s10, s0, 0x60080
	s_addc_u32 s11, s1, 0
	s_add_i32 s73, s43, 0x1e000
	s_mov_b32 s3, m0
	s_mov_b32 m0, s73
	s_nop 4
	global_load_lds_dwordx4 v136, s[10:11]
	s_mov_b32 m0, s3
	s_waitcnt vmcnt(6)
	s_add_i32 s74, s43, 0xc000
	s_cmpk_lt_u32 s5, 0x100
	v_mov_b64_e32 v[2:3], 0
	s_sext_i32_i16 s78, s4
	s_cselect_b64 s[10:11], -1, 0
	s_ashr_i32 s75, s72, 31
	v_or_b32_e32 v138, s2, v4
	v_mov_b64_e32 v[130:131], 0x16b0
	v_mov_b64_e32 v[132:133], 0x16af
	v_add_u32_e32 v139, 0, v6
	v_add_u32_e32 v140, 0, v5
	s_mov_b32 s76, 0xc3dc0000
	s_movk_i32 s77, 0xb00
	v_mov_b32_e32 v141, 0x43dc0000
	v_mov_b64_e32 v[4:5], v[2:3]
	v_mov_b64_e32 v[14:15], v[2:3]
	v_mov_b64_e32 v[16:17], v[2:3]
	v_mov_b64_e32 v[22:23], v[2:3]
	v_mov_b64_e32 v[24:25], v[2:3]
	v_mov_b64_e32 v[30:31], v[2:3]
	v_mov_b64_e32 v[32:33], v[2:3]
	s_waitcnt vmcnt(3)
	v_mov_b64_e32 v[38:39], v[2:3]
	v_mov_b64_e32 v[40:41], v[2:3]
	v_mov_b64_e32 v[46:47], v[2:3]
	v_mov_b64_e32 v[48:49], v[2:3]
	v_mov_b64_e32 v[54:55], v[2:3]
	v_mov_b64_e32 v[56:57], v[2:3]
	v_mov_b64_e32 v[62:63], v[2:3]
	v_mov_b64_e32 v[64:65], v[2:3]
	v_mov_b64_e32 v[6:7], v[2:3]
	v_mov_b64_e32 v[8:9], v[2:3]
	v_mov_b64_e32 v[10:11], v[2:3]
	v_mov_b64_e32 v[12:13], v[2:3]
	v_mov_b64_e32 v[18:19], v[2:3]
	v_mov_b64_e32 v[20:21], v[2:3]
	v_mov_b64_e32 v[26:27], v[2:3]
	v_mov_b64_e32 v[28:29], v[2:3]
	s_waitcnt vmcnt(2) lgkmcnt(0)
	v_mov_b64_e32 v[34:35], v[2:3]
	v_mov_b64_e32 v[36:37], v[2:3]
	v_mov_b64_e32 v[42:43], v[2:3]
	v_mov_b64_e32 v[44:45], v[2:3]
	v_mov_b64_e32 v[50:51], v[2:3]
	v_mov_b64_e32 v[52:53], v[2:3]
	v_mov_b64_e32 v[58:59], v[2:3]
	v_mov_b64_e32 v[60:61], v[2:3]
	v_mov_b64_e32 v[70:71], v[2:3]
	v_mov_b64_e32 v[72:73], v[2:3]
	v_mov_b64_e32 v[78:79], v[2:3]
	v_mov_b64_e32 v[80:81], v[2:3]
	v_mov_b64_e32 v[86:87], v[2:3]
	v_mov_b64_e32 v[88:89], v[2:3]
	v_mov_b64_e32 v[94:95], v[2:3]
	v_mov_b64_e32 v[96:97], v[2:3]
	v_mov_b64_e32 v[102:103], v[2:3]
	v_mov_b64_e32 v[104:105], v[2:3]
	v_mov_b64_e32 v[110:111], v[2:3]
	v_mov_b64_e32 v[112:113], v[2:3]
	v_mov_b64_e32 v[118:119], v[2:3]
	v_mov_b64_e32 v[120:121], v[2:3]
	v_mov_b64_e32 v[126:127], v[2:3]
	v_mov_b64_e32 v[128:129], v[2:3]
	v_mov_b64_e32 v[66:67], v[2:3]
	v_mov_b64_e32 v[68:69], v[2:3]
	v_mov_b64_e32 v[74:75], v[2:3]
	v_mov_b64_e32 v[76:77], v[2:3]
	v_mov_b64_e32 v[82:83], v[2:3]
	v_mov_b64_e32 v[84:85], v[2:3]
	v_mov_b64_e32 v[90:91], v[2:3]
	v_mov_b64_e32 v[92:93], v[2:3]
	v_mov_b64_e32 v[98:99], v[2:3]
	v_mov_b64_e32 v[100:101], v[2:3]
	v_mov_b64_e32 v[106:107], v[2:3]
	v_mov_b64_e32 v[108:109], v[2:3]
	v_mov_b64_e32 v[114:115], v[2:3]
	v_mov_b64_e32 v[116:117], v[2:3]
	v_mov_b64_e32 v[122:123], v[2:3]
	v_mov_b64_e32 v[124:125], v[2:3]
	s_barrier
	s_mov_b32 s98, 0
	s_branch .LBB0_554

.LBB0_557:
	v_add_u32_e32 v134, 0x10000, v139
	ds_read_b128 v[142:145], v134
	ds_read_b128 v[146:149], v134 offset:1024
	ds_read_b128 v[150:153], v134 offset:2048
	ds_read_b128 v[154:157], v134 offset:3072
	v_add_u32_e32 v134, 0x14000, v139
	ds_read_b128 v[158:161], v134
	ds_read_b128 v[162:165], v134 offset:1024
	ds_read_b128 v[166:169], v134 offset:2048
	ds_read_b128 v[170:173], v134 offset:3072
	s_add_u32 s0, s44, 0x100
	s_addc_u32 s1, s45, 0
	s_cmp_eq_u32 s81, 12
	s_cselect_b32 s34, s15, s0
	s_cselect_b32 s35, s14, s1
	s_cselect_b32 s52, s27, s79
	s_cselect_b32 s53, s25, s80
	s_add_u32 s50, s34, 0x80
	s_addc_u32 s51, s35, 0
	ds_read_b128 v[174:177], v140
	ds_read_b128 v[178:181], v140 offset:1024
	ds_read_b128 v[182:185], v140 offset:2048
	ds_read_b128 v[186:189], v140 offset:3072
	ds_read_b128 v[190:193], v140 offset:4096
	ds_read_b128 v[194:197], v140 offset:5120
	ds_read_b128 v[198:201], v140 offset:6144
	ds_read_b128 v[202:205], v140 offset:7168
	s_add_u32 s84, s44, 0x40080
	s_addc_u32 s85, s45, 0
	s_mov_b32 s2, m0
	s_mov_b32 m0, s74
	s_nop 4
	global_load_lds_dwordx4 v1, s[84:85]
	s_mov_b32 m0, s2
	s_add_u32 s44, s44, 0x60080
	s_addc_u32 s45, s45, 0
	s_add_i32 s2, s43, 0xe000
	s_mov_b32 s3, m0
	s_mov_b32 m0, s2
	s_nop 4
	global_load_lds_dwordx4 v1, s[44:45]
	s_mov_b32 m0, s3
	s_cmp_eq_u32 s81, -2
	s_cselect_b32 s99, s98, 0
	s_cmp_eq_u32 s99, 0
	s_cbranch_scc1 .Lw8_1_0
	s_waitcnt vmcnt(16)
	s_branch .Lwd_1_0

.Lwd_1_0:
	s_waitcnt lgkmcnt(0)
	s_barrier
	s_setprio 1
	s_waitcnt lgkmcnt(7)
	v_mfma_f32_16x16x32_bf16 v[122:125], v[142:145], v[174:177], v[122:125]
	v_mfma_f32_16x16x32_bf16 v[114:117], v[150:153], v[174:177], v[114:117]
	s_waitcnt lgkmcnt(5)
	v_mfma_f32_16x16x32_bf16 v[106:109], v[142:145], v[182:185], v[106:109]
	v_mfma_f32_16x16x32_bf16 v[98:101], v[150:153], v[182:185], v[98:101]
	s_waitcnt lgkmcnt(3)
	v_mfma_f32_16x16x32_bf16 v[90:93], v[142:145], v[190:193], v[90:93]
	v_mfma_f32_16x16x32_bf16 v[82:85], v[150:153], v[190:193], v[82:85]
	s_waitcnt lgkmcnt(1)
	v_mfma_f32_16x16x32_bf16 v[74:77], v[142:145], v[198:201], v[74:77]
	v_mfma_f32_16x16x32_bf16 v[66:69], v[150:153], v[198:201], v[66:69]
	v_mfma_f32_16x16x32_bf16 v[122:125], v[146:149], v[178:181], v[122:125]
	v_mfma_f32_16x16x32_bf16 v[114:117], v[154:157], v[178:181], v[114:117]
	v_mfma_f32_16x16x32_bf16 v[106:109], v[146:149], v[186:189], v[106:109]
	v_mfma_f32_16x16x32_bf16 v[98:101], v[154:157], v[186:189], v[98:101]
	v_mfma_f32_16x16x32_bf16 v[90:93], v[146:149], v[194:197], v[90:93]
	v_mfma_f32_16x16x32_bf16 v[82:85], v[154:157], v[194:197], v[82:85]
	s_waitcnt lgkmcnt(0)
	v_mfma_f32_16x16x32_bf16 v[74:77], v[146:149], v[202:205], v[74:77]
	v_mfma_f32_16x16x32_bf16 v[66:69], v[154:157], v[202:205], v[66:69]
	s_setprio 0
	s_setprio 1
	v_mfma_f32_16x16x32_bf16 v[126:129], v[158:161], v[174:177], v[126:129]
	v_mfma_f32_16x16x32_bf16 v[118:121], v[166:169], v[174:177], v[118:121]
	v_mfma_f32_16x16x32_bf16 v[110:113], v[158:161], v[182:185], v[110:113]
	v_mfma_f32_16x16x32_bf16 v[102:105], v[166:169], v[182:185], v[102:105]
	v_mfma_f32_16x16x32_bf16 v[94:97], v[158:161], v[190:193], v[94:97]
	v_mfma_f32_16x16x32_bf16 v[86:89], v[166:169], v[190:193], v[86:89]
	v_mfma_f32_16x16x32_bf16 v[78:81], v[158:161], v[198:201], v[78:81]
	v_mfma_f32_16x16x32_bf16 v[70:73], v[166:169], v[198:201], v[70:73]
	v_mfma_f32_16x16x32_bf16 v[126:129], v[162:165], v[178:181], v[126:129]
	v_mfma_f32_16x16x32_bf16 v[118:121], v[170:173], v[178:181], v[118:121]
	v_mfma_f32_16x16x32_bf16 v[110:113], v[162:165], v[186:189], v[110:113]
	v_mfma_f32_16x16x32_bf16 v[102:105], v[170:173], v[186:189], v[102:105]
	v_mfma_f32_16x16x32_bf16 v[94:97], v[162:165], v[194:197], v[94:97]
	v_mfma_f32_16x16x32_bf16 v[86:89], v[170:173], v[194:197], v[86:89]
	v_mfma_f32_16x16x32_bf16 v[78:81], v[162:165], v[202:205], v[78:81]
	v_mfma_f32_16x16x32_bf16 v[70:73], v[170:173], v[202:205], v[70:73]
	s_setprio 0
	s_barrier
	s_add_u32 s44, s52, 0x20000
	ds_read_b128 v[174:177], v140 offset:16384
	ds_read_b128 v[178:181], v140 offset:17408
	ds_read_b128 v[182:185], v140 offset:18432
	ds_read_b128 v[186:189], v140 offset:19456
	ds_read_b128 v[190:193], v140 offset:20480
	ds_read_b128 v[194:197], v140 offset:21504
	ds_read_b128 v[198:201], v140 offset:22528
	ds_read_b128 v[202:205], v140 offset:23552
	s_mov_b32 s2, m0
	s_mov_b32 m0, s56
	s_nop 4
	global_load_lds_dwordx4 v136, s[52:53]
	s_mov_b32 m0, s2
	s_addc_u32 s45, s53, 0
	s_mov_b32 s2, m0
	s_mov_b32 m0, s57
	s_nop 4
	global_load_lds_dwordx4 v136, s[44:45]
	s_mov_b32 m0, s2
	s_add_u32 s44, s52, 0x40000
	s_addc_u32 s45, s53, 0
	s_mov_b32 s2, m0
	s_mov_b32 m0, s58
	s_nop 4
	global_load_lds_dwordx4 v136, s[44:45]
	s_mov_b32 m0, s2
	s_add_u32 s44, s52, 0x60000
	s_addc_u32 s45, s53, 0
	s_mov_b32 s2, m0
	s_mov_b32 m0, s59
	s_nop 4
	global_load_lds_dwordx4 v136, s[44:45]
	s_mov_b32 m0, s2
	s_add_u32 s44, s34, 0x20000
	s_mov_b32 s2, m0
	s_mov_b32 m0, s43
	s_nop 4
	global_load_lds_dwordx4 v1, s[34:35]
	s_mov_b32 m0, s2
	s_addc_u32 s45, s35, 0
	s_mov_b32 s2, m0
	s_mov_b32 m0, s60
	s_nop 4
	global_load_lds_dwordx4 v1, s[44:45]
	s_mov_b32 m0, s2
	s_cmp_eq_u32 s81, -2
	s_cselect_b32 s99, s98, 0
	s_cmp_eq_u32 s99, 0
	s_cbranch_scc1 .Lw8_1_1
	s_waitcnt vmcnt(16)
	s_branch .Lwd_1_1

.Lwd_1_1:
	s_waitcnt lgkmcnt(0)
	s_barrier
	s_setprio 1
	s_waitcnt lgkmcnt(7)
	v_mfma_f32_16x16x32_bf16 v[58:61], v[142:145], v[174:177], v[58:61]
	v_mfma_f32_16x16x32_bf16 v[50:53], v[150:153], v[174:177], v[50:53]
	s_waitcnt lgkmcnt(5)
	v_mfma_f32_16x16x32_bf16 v[42:45], v[142:145], v[182:185], v[42:45]
	v_mfma_f32_16x16x32_bf16 v[34:37], v[150:153], v[182:185], v[34:37]
	s_waitcnt lgkmcnt(3)
	v_mfma_f32_16x16x32_bf16 v[26:29], v[142:145], v[190:193], v[26:29]
	v_mfma_f32_16x16x32_bf16 v[18:21], v[150:153], v[190:193], v[18:21]
	s_waitcnt lgkmcnt(1)
	v_mfma_f32_16x16x32_bf16 v[10:13], v[142:145], v[198:201], v[10:13]
	v_mfma_f32_16x16x32_bf16 v[6:9], v[150:153], v[198:201], v[6:9]
	v_mfma_f32_16x16x32_bf16 v[58:61], v[146:149], v[178:181], v[58:61]
	v_mfma_f32_16x16x32_bf16 v[50:53], v[154:157], v[178:181], v[50:53]
	v_mfma_f32_16x16x32_bf16 v[42:45], v[146:149], v[186:189], v[42:45]
	v_mfma_f32_16x16x32_bf16 v[34:37], v[154:157], v[186:189], v[34:37]
	v_mfma_f32_16x16x32_bf16 v[26:29], v[146:149], v[194:197], v[26:29]
	v_mfma_f32_16x16x32_bf16 v[18:21], v[154:157], v[194:197], v[18:21]
	s_waitcnt lgkmcnt(0)
	v_mfma_f32_16x16x32_bf16 v[10:13], v[146:149], v[202:205], v[10:13]
	v_mfma_f32_16x16x32_bf16 v[6:9], v[154:157], v[202:205], v[6:9]
	s_setprio 0
	s_setprio 1
	v_mfma_f32_16x16x32_bf16 v[62:65], v[158:161], v[174:177], v[62:65]
	v_mfma_f32_16x16x32_bf16 v[54:57], v[166:169], v[174:177], v[54:57]
	v_mfma_f32_16x16x32_bf16 v[46:49], v[158:161], v[182:185], v[46:49]
	v_mfma_f32_16x16x32_bf16 v[38:41], v[166:169], v[182:185], v[38:41]
	v_mfma_f32_16x16x32_bf16 v[30:33], v[158:161], v[190:193], v[30:33]
	v_mfma_f32_16x16x32_bf16 v[22:25], v[166:169], v[190:193], v[22:25]
	v_mfma_f32_16x16x32_bf16 v[14:17], v[158:161], v[198:201], v[14:17]
	v_mfma_f32_16x16x32_bf16 v[2:5], v[166:169], v[198:201], v[2:5]
	v_mfma_f32_16x16x32_bf16 v[62:65], v[162:165], v[178:181], v[62:65]
	v_mfma_f32_16x16x32_bf16 v[54:57], v[170:173], v[178:181], v[54:57]
	v_mfma_f32_16x16x32_bf16 v[46:49], v[162:165], v[186:189], v[46:49]
	v_mfma_f32_16x16x32_bf16 v[38:41], v[170:173], v[186:189], v[38:41]
	v_mfma_f32_16x16x32_bf16 v[30:33], v[162:165], v[194:197], v[30:33]
	v_mfma_f32_16x16x32_bf16 v[22:25], v[170:173], v[194:197], v[22:25]
	v_mfma_f32_16x16x32_bf16 v[14:17], v[162:165], v[202:205], v[14:17]
	v_mfma_f32_16x16x32_bf16 v[2:5], v[170:173], v[202:205], v[2:5]
	s_setprio 0
	s_barrier
	v_add_u32_e32 v134, 0x18000, v139
	ds_read_b128 v[142:145], v134
	ds_read_b128 v[146:149], v134 offset:1024
	ds_read_b128 v[150:153], v134 offset:2048
	ds_read_b128 v[154:157], v134 offset:3072
	v_add_u32_e32 v134, 0x1c000, v139
	ds_read_b128 v[158:161], v134
	ds_read_b128 v[162:165], v134 offset:1024
	ds_read_b128 v[166:169], v134 offset:2048
	ds_read_b128 v[170:173], v134 offset:3072
	ds_read_b128 v[174:177], v140 offset:32768
	ds_read_b128 v[178:181], v140 offset:33792
	ds_read_b128 v[182:185], v140 offset:34816
	ds_read_b128 v[186:189], v140 offset:35840
	ds_read_b128 v[190:193], v140 offset:36864
	ds_read_b128 v[194:197], v140 offset:37888
	ds_read_b128 v[198:201], v140 offset:38912
	ds_read_b128 v[202:205], v140 offset:39936
	s_add_u32 s44, s34, 0x40000
	s_addc_u32 s45, s35, 0
	s_mov_b32 s2, m0
	s_mov_b32 m0, s61
	s_nop 4
	global_load_lds_dwordx4 v1, s[44:45]
	s_mov_b32 m0, s2
	s_add_u32 s44, s34, 0x60000
	s_addc_u32 s45, s35, 0
	s_mov_b32 s2, m0
	s_mov_b32 m0, s62
	s_nop 4
	global_load_lds_dwordx4 v1, s[44:45]
	s_mov_b32 m0, s2
	s_waitcnt vmcnt(8)
	s_waitcnt lgkmcnt(0)
	s_barrier
	s_setprio 1
	s_waitcnt lgkmcnt(7)
	v_mfma_f32_16x16x32_bf16 v[122:125], v[142:145], v[174:177], v[122:125]
	v_mfma_f32_16x16x32_bf16 v[114:117], v[150:153], v[174:177], v[114:117]
	s_waitcnt lgkmcnt(5)
	v_mfma_f32_16x16x32_bf16 v[106:109], v[142:145], v[182:185], v[106:109]
	v_mfma_f32_16x16x32_bf16 v[98:101], v[150:153], v[182:185], v[98:101]
	s_waitcnt lgkmcnt(3)
	v_mfma_f32_16x16x32_bf16 v[90:93], v[142:145], v[190:193], v[90:93]
	v_mfma_f32_16x16x32_bf16 v[82:85], v[150:153], v[190:193], v[82:85]
	s_waitcnt lgkmcnt(1)
	v_mfma_f32_16x16x32_bf16 v[74:77], v[142:145], v[198:201], v[74:77]
	v_mfma_f32_16x16x32_bf16 v[66:69], v[150:153], v[198:201], v[66:69]
	v_mfma_f32_16x16x32_bf16 v[122:125], v[146:149], v[178:181], v[122:125]
	v_mfma_f32_16x16x32_bf16 v[114:117], v[154:157], v[178:181], v[114:117]
	v_mfma_f32_16x16x32_bf16 v[106:109], v[146:149], v[186:189], v[106:109]
	v_mfma_f32_16x16x32_bf16 v[98:101], v[154:157], v[186:189], v[98:101]
	v_mfma_f32_16x16x32_bf16 v[90:93], v[146:149], v[194:197], v[90:93]
	v_mfma_f32_16x16x32_bf16 v[82:85], v[154:157], v[194:197], v[82:85]
	s_waitcnt lgkmcnt(0)
	v_mfma_f32_16x16x32_bf16 v[74:77], v[146:149], v[202:205], v[74:77]
	v_mfma_f32_16x16x32_bf16 v[66:69], v[154:157], v[202:205], v[66:69]
	s_setprio 0
	s_setprio 1
	v_mfma_f32_16x16x32_bf16 v[126:129], v[158:161], v[174:177], v[126:129]
	v_mfma_f32_16x16x32_bf16 v[118:121], v[166:169], v[174:177], v[118:121]
	v_mfma_f32_16x16x32_bf16 v[110:113], v[158:161], v[182:185], v[110:113]
	v_mfma_f32_16x16x32_bf16 v[102:105], v[166:169], v[182:185], v[102:105]
	v_mfma_f32_16x16x32_bf16 v[94:97], v[158:161], v[190:193], v[94:97]
	v_mfma_f32_16x16x32_bf16 v[86:89], v[166:169], v[190:193], v[86:89]
	v_mfma_f32_16x16x32_bf16 v[78:81], v[158:161], v[198:201], v[78:81]
	v_mfma_f32_16x16x32_bf16 v[70:73], v[166:169], v[198:201], v[70:73]
	v_mfma_f32_16x16x32_bf16 v[126:129], v[162:165], v[178:181], v[126:129]
	v_mfma_f32_16x16x32_bf16 v[118:121], v[170:173], v[178:181], v[118:121]
	v_mfma_f32_16x16x32_bf16 v[110:113], v[162:165], v[186:189], v[110:113]
	v_mfma_f32_16x16x32_bf16 v[102:105], v[170:173], v[186:189], v[102:105]
	v_mfma_f32_16x16x32_bf16 v[94:97], v[162:165], v[194:197], v[94:97]
	v_mfma_f32_16x16x32_bf16 v[86:89], v[170:173], v[194:197], v[86:89]
	v_mfma_f32_16x16x32_bf16 v[78:81], v[162:165], v[202:205], v[78:81]
	v_mfma_f32_16x16x32_bf16 v[70:73], v[170:173], v[202:205], v[70:73]
	s_setprio 0
	s_barrier
	s_add_u32 s44, s52, 0x80
	s_addc_u32 s45, s53, 0
	ds_read_b128 v[174:177], v140 offset:49152
	ds_read_b128 v[178:181], v140 offset:50176
	ds_read_b128 v[182:185], v140 offset:51200
	ds_read_b128 v[186:189], v140 offset:52224
	ds_read_b128 v[190:193], v140 offset:53248
	ds_read_b128 v[194:197], v140 offset:54272
	ds_read_b128 v[198:201], v140 offset:55296
	ds_read_b128 v[202:205], v140 offset:56320
	s_mov_b32 s2, m0
	s_mov_b32 m0, s63
	s_nop 4
	global_load_lds_dwordx4 v136, s[44:45]
	s_mov_b32 m0, s2
	s_add_u32 s44, s52, 0x20080
	s_addc_u32 s45, s53, 0
	s_mov_b32 s2, m0
	s_mov_b32 m0, s64
	s_nop 4
	global_load_lds_dwordx4 v136, s[44:45]
	s_mov_b32 m0, s2
	s_add_u32 s44, s52, 0x40080
	s_addc_u32 s45, s53, 0
	s_mov_b32 s2, m0
	s_mov_b32 m0, s67
	s_nop 4
	global_load_lds_dwordx4 v136, s[44:45]
	s_mov_b32 m0, s2
	s_add_u32 s44, s52, 0x60080
	s_addc_u32 s45, s53, 0
	s_mov_b32 s2, m0
	s_mov_b32 m0, s73
	s_nop 4
	global_load_lds_dwordx4 v136, s[44:45]
	s_mov_b32 m0, s2
	s_add_u32 s34, s34, 0x20080
	s_mov_b32 s2, m0
	s_mov_b32 m0, s65
	s_nop 4
	global_load_lds_dwordx4 v1, s[50:51]
	s_mov_b32 m0, s2
	s_addc_u32 s35, s35, 0
	s_mov_b32 s2, m0
	s_mov_b32 m0, s66
	s_nop 4
	global_load_lds_dwordx4 v1, s[34:35]
	s_mov_b32 m0, s2
	s_waitcnt vmcnt(8)
	s_waitcnt lgkmcnt(0)
	s_barrier
	s_setprio 1
	s_waitcnt lgkmcnt(7)
	v_mfma_f32_16x16x32_bf16 v[58:61], v[142:145], v[174:177], v[58:61]
	v_mfma_f32_16x16x32_bf16 v[50:53], v[150:153], v[174:177], v[50:53]
	s_waitcnt lgkmcnt(5)
	v_mfma_f32_16x16x32_bf16 v[42:45], v[142:145], v[182:185], v[42:45]
	v_mfma_f32_16x16x32_bf16 v[34:37], v[150:153], v[182:185], v[34:37]
	s_waitcnt lgkmcnt(3)
	v_mfma_f32_16x16x32_bf16 v[26:29], v[142:145], v[190:193], v[26:29]
	v_mfma_f32_16x16x32_bf16 v[18:21], v[150:153], v[190:193], v[18:21]
	s_waitcnt lgkmcnt(1)
	v_mfma_f32_16x16x32_bf16 v[10:13], v[142:145], v[198:201], v[10:13]
	v_mfma_f32_16x16x32_bf16 v[6:9], v[150:153], v[198:201], v[6:9]
	v_mfma_f32_16x16x32_bf16 v[58:61], v[146:149], v[178:181], v[58:61]
	v_mfma_f32_16x16x32_bf16 v[50:53], v[154:157], v[178:181], v[50:53]
	v_mfma_f32_16x16x32_bf16 v[42:45], v[146:149], v[186:189], v[42:45]
	v_mfma_f32_16x16x32_bf16 v[34:37], v[154:157], v[186:189], v[34:37]
	v_mfma_f32_16x16x32_bf16 v[26:29], v[146:149], v[194:197], v[26:29]
	v_mfma_f32_16x16x32_bf16 v[18:21], v[154:157], v[194:197], v[18:21]
	s_waitcnt lgkmcnt(0)
	v_mfma_f32_16x16x32_bf16 v[10:13], v[146:149], v[202:205], v[10:13]
	v_mfma_f32_16x16x32_bf16 v[6:9], v[154:157], v[202:205], v[6:9]
	s_setprio 0
	s_setprio 1
	v_mfma_f32_16x16x32_bf16 v[62:65], v[158:161], v[174:177], v[62:65]
	v_mfma_f32_16x16x32_bf16 v[54:57], v[166:169], v[174:177], v[54:57]
	v_mfma_f32_16x16x32_bf16 v[46:49], v[158:161], v[182:185], v[46:49]
	v_mfma_f32_16x16x32_bf16 v[38:41], v[166:169], v[182:185], v[38:41]
	v_mfma_f32_16x16x32_bf16 v[30:33], v[158:161], v[190:193], v[30:33]
	v_mfma_f32_16x16x32_bf16 v[22:25], v[166:169], v[190:193], v[22:25]
	v_mfma_f32_16x16x32_bf16 v[14:17], v[158:161], v[198:201], v[14:17]
	v_mfma_f32_16x16x32_bf16 v[2:5], v[166:169], v[198:201], v[2:5]
	v_mfma_f32_16x16x32_bf16 v[62:65], v[162:165], v[178:181], v[62:65]
	v_mfma_f32_16x16x32_bf16 v[54:57], v[170:173], v[178:181], v[54:57]
	v_mfma_f32_16x16x32_bf16 v[46:49], v[162:165], v[186:189], v[46:49]
	v_mfma_f32_16x16x32_bf16 v[38:41], v[170:173], v[186:189], v[38:41]
	v_mfma_f32_16x16x32_bf16 v[30:33], v[162:165], v[194:197], v[30:33]
	v_mfma_f32_16x16x32_bf16 v[22:25], v[170:173], v[194:197], v[22:25]
	v_mfma_f32_16x16x32_bf16 v[14:17], v[162:165], v[202:205], v[14:17]
	v_mfma_f32_16x16x32_bf16 v[2:5], v[170:173], v[202:205], v[2:5]
	s_setprio 0
	s_barrier
	s_add_i32 s81, s81, 2
	s_add_u32 s79, s79, 0x100
	s_addc_u32 s80, s80, 0
	s_cmp_gt_u32 s81, 13
	s_mov_b64 s[44:45], s[0:1]
	s_cbranch_scc0 .LBB0_557
	s_and_b64 vcc, exec, s[10:11]
	s_cbranch_vccz .LBB0_560
	s_barrier
.LBB0_560:
	v_exp_f32_e64 v144, -v122
	v_exp_f32_e64 v145, -v123
	v_pk_mul_f32 v[128:129], v[124:125], v[128:129]
	v_exp_f32_e64 v124, -v124
	v_exp_f32_e64 v125, -v125
	v_pk_add_f32 v[144:145], v[144:145], 1.0 op_sel_hi:[1,0]
	v_pk_mul_f32 v[122:123], v[122:123], v[126:127]
	v_rcp_f32_e32 v126, v144
	v_rcp_f32_e32 v127, v145
	v_pk_add_f32 v[124:125], v[124:125], 1.0 op_sel_hi:[1,0]
	v_pk_mul_f32 v[112:113], v[108:109], v[112:113]
	v_rcp_f32_e32 v124, v124
	v_rcp_f32_e32 v125, v125
	v_pk_mul_f32 v[122:123], v[126:127], v[122:123]
	v_exp_f32_e64 v126, -v114
	v_exp_f32_e64 v127, -v115
	v_pk_mul_f32 v[124:125], v[124:125], v[128:129]
	v_exp_f32_e64 v128, -v116
	v_exp_f32_e64 v129, -v117
	v_pk_add_f32 v[126:127], v[126:127], 1.0 op_sel_hi:[1,0]
	v_pk_mul_f32 v[114:115], v[114:115], v[118:119]
	v_rcp_f32_e32 v126, v126
	v_rcp_f32_e32 v127, v127
	v_pk_add_f32 v[128:129], v[128:129], 1.0 op_sel_hi:[1,0]
	v_pk_mul_f32 v[116:117], v[116:117], v[120:121]
	v_rcp_f32_e32 v128, v128
	v_rcp_f32_e32 v129, v129
	v_pk_mul_f32 v[114:115], v[126:127], v[114:115]
	v_med3_f32 v119, v122, s76, v141
	v_med3_f32 v120, v123, s76, v141
	v_mov_b32_e32 v118, 0
	v_pk_mul_f32 v[116:117], v[128:129], v[116:117]
	v_med3_f32 v114, v114, s76, v141
	v_med3_f32 v115, v115, s76, v141
	v_cvt_pk_fp8_f32 v118, v119, v120
	v_mov_b32_e32 v119, 0
	v_cvt_pk_fp8_f32 v119, v114, v115
	v_med3_f32 v114, v116, s76, v141
	v_med3_f32 v115, v117, s76, v141
	v_exp_f32_e64 v116, -v106
	v_exp_f32_e64 v117, -v107
	v_exp_f32_e64 v108, -v108
	v_exp_f32_e64 v109, -v109
	v_pk_mul_f32 v[106:107], v[106:107], v[110:111]
	v_pk_add_f32 v[116:117], v[116:117], 1.0 op_sel_hi:[1,0]
	v_lshl_add_u32 v142, s42, 8, v137
	v_rcp_f32_e32 v110, v116
	v_rcp_f32_e32 v111, v117
	v_pk_add_f32 v[108:109], v[108:109], 1.0 op_sel_hi:[1,0]
	v_lshl_or_b32 v134, s78, 7, v138
	v_rcp_f32_e32 v108, v108
	v_rcp_f32_e32 v109, v109
	v_pk_mul_f32 v[106:107], v[110:111], v[106:107]
	v_exp_f32_e64 v110, -v98
	v_exp_f32_e64 v111, -v99
	v_pk_mul_f32 v[108:109], v[108:109], v[112:113]
	v_exp_f32_e64 v112, -v100
	v_exp_f32_e64 v113, -v101
	v_pk_add_f32 v[110:111], v[110:111], 1.0 op_sel_hi:[1,0]
	v_pk_mul_f32 v[98:99], v[98:99], v[102:103]
	v_rcp_f32_e32 v110, v110
	v_rcp_f32_e32 v111, v111
	v_pk_add_f32 v[112:113], v[112:113], 1.0 op_sel_hi:[1,0]
	v_med3_f32 v102, v106, s76, v141
	v_rcp_f32_e32 v112, v112
	v_rcp_f32_e32 v113, v113
	v_pk_mul_f32 v[98:99], v[110:111], v[98:99]
	v_med3_f32 v103, v107, s76, v141
	v_med3_f32 v106, v98, s76, v141
	v_med3_f32 v107, v99, s76, v141
	v_mov_b32_e32 v98, 0
	v_mov_b32_e32 v99, 0
	v_cvt_pk_fp8_f32 v98, v102, v103
	v_cvt_pk_fp8_f32 v99, v106, v107
	v_pk_mul_f32 v[100:101], v[100:101], v[104:105]
	v_med3_f32 v104, v108, s76, v141
	v_pk_mul_f32 v[100:101], v[112:113], v[100:101]
	v_med3_f32 v105, v109, s76, v141
	v_med3_f32 v100, v100, s76, v141
	v_med3_f32 v101, v101, s76, v141
	v_cvt_pk_fp8_f32 v98, v104, v105 op_sel:[0,0,1]
	v_cvt_pk_fp8_f32 v99, v100, v101 op_sel:[0,0,1]
	v_exp_f32_e64 v100, -v90
	v_exp_f32_e64 v101, -v91
	v_cvt_pk_fp8_f32 v119, v114, v115 op_sel:[0,0,1]
	v_mov_b64_e32 v[114:115], s[18:19]
	v_or_b32_e32 v102, 16, v142
	v_ashrrev_i32_e32 v135, 31, v134
	v_mad_i64_i32 v[102:103], s[0:1], v102, s77, v[114:115]
	v_lshl_add_u64 v[102:103], v[102:103], 0, v[134:135]
	global_store_dwordx2 v[102:103], v[98:99], off
	v_pk_add_f32 v[98:99], v[100:101], 1.0 op_sel_hi:[1,0]
	v_pk_mul_f32 v[96:97], v[92:93], v[96:97]
	v_exp_f32_e64 v92, -v92
	v_exp_f32_e64 v93, -v93
	v_pk_mul_f32 v[90:91], v[90:91], v[94:95]
	v_rcp_f32_e32 v94, v98
	v_rcp_f32_e32 v95, v99
	v_pk_add_f32 v[92:93], v[92:93], 1.0 op_sel_hi:[1,0]
	v_pk_mul_f32 v[80:81], v[76:77], v[80:81]
	v_rcp_f32_e32 v92, v92
	v_rcp_f32_e32 v93, v93
	v_pk_mul_f32 v[90:91], v[94:95], v[90:91]
	v_exp_f32_e64 v94, -v82
	v_exp_f32_e64 v95, -v83
	v_pk_mul_f32 v[92:93], v[92:93], v[96:97]
	v_exp_f32_e64 v96, -v84
	v_exp_f32_e64 v97, -v85
	v_pk_add_f32 v[94:95], v[94:95], 1.0 op_sel_hi:[1,0]
	v_pk_mul_f32 v[82:83], v[82:83], v[86:87]
	v_rcp_f32_e32 v94, v94
	v_rcp_f32_e32 v95, v95
	v_pk_add_f32 v[96:97], v[96:97], 1.0 op_sel_hi:[1,0]
	v_med3_f32 v86, v90, s76, v141
	v_rcp_f32_e32 v96, v96
	v_rcp_f32_e32 v97, v97
	v_pk_mul_f32 v[82:83], v[94:95], v[82:83]
	v_med3_f32 v87, v91, s76, v141
	v_med3_f32 v90, v82, s76, v141
	v_med3_f32 v91, v83, s76, v141
	v_mov_b32_e32 v82, 0
	v_mov_b32_e32 v83, 0
	v_cvt_pk_fp8_f32 v82, v86, v87
	v_cvt_pk_fp8_f32 v83, v90, v91
	v_pk_mul_f32 v[84:85], v[84:85], v[88:89]
	v_med3_f32 v88, v92, s76, v141
	v_pk_mul_f32 v[84:85], v[96:97], v[84:85]
	v_med3_f32 v89, v93, s76, v141
	v_med3_f32 v84, v84, s76, v141
	v_med3_f32 v85, v85, s76, v141
	v_cvt_pk_fp8_f32 v82, v88, v89 op_sel:[0,0,1]
	v_cvt_pk_fp8_f32 v83, v84, v85 op_sel:[0,0,1]
	v_exp_f32_e64 v84, -v74
	v_exp_f32_e64 v85, -v75
	v_or_b32_e32 v86, 32, v142
	v_mad_i64_i32 v[86:87], s[0:1], v86, s77, v[114:115]
	v_lshl_add_u64 v[86:87], v[86:87], 0, v[134:135]
	global_store_dwordx2 v[86:87], v[82:83], off
	v_pk_add_f32 v[82:83], v[84:85], 1.0 op_sel_hi:[1,0]
	v_exp_f32_e64 v76, -v76
	v_exp_f32_e64 v77, -v77
	v_pk_mul_f32 v[74:75], v[74:75], v[78:79]
	v_rcp_f32_e32 v78, v82
	v_rcp_f32_e32 v79, v83
	v_pk_add_f32 v[76:77], v[76:77], 1.0 op_sel_hi:[1,0]
	v_pk_mul_f32 v[64:65], v[60:61], v[64:65]
	v_rcp_f32_e32 v76, v76
	v_rcp_f32_e32 v77, v77
	v_pk_mul_f32 v[74:75], v[78:79], v[74:75]
	v_exp_f32_e64 v78, -v66
	v_exp_f32_e64 v79, -v67
	v_pk_mul_f32 v[76:77], v[76:77], v[80:81]
	v_exp_f32_e64 v80, -v68
	v_exp_f32_e64 v81, -v69
	v_pk_add_f32 v[78:79], v[78:79], 1.0 op_sel_hi:[1,0]
	v_pk_mul_f32 v[66:67], v[66:67], v[70:71]
	v_rcp_f32_e32 v78, v78
	v_rcp_f32_e32 v79, v79
	v_pk_add_f32 v[80:81], v[80:81], 1.0 op_sel_hi:[1,0]
	v_med3_f32 v70, v74, s76, v141
	v_rcp_f32_e32 v80, v80
	v_rcp_f32_e32 v81, v81
	v_pk_mul_f32 v[66:67], v[78:79], v[66:67]
	v_med3_f32 v71, v75, s76, v141
	v_med3_f32 v74, v66, s76, v141
	v_med3_f32 v75, v67, s76, v141
	v_mov_b32_e32 v66, 0
	v_mov_b32_e32 v67, 0
	v_cvt_pk_fp8_f32 v66, v70, v71
	v_cvt_pk_fp8_f32 v67, v74, v75
	v_pk_mul_f32 v[68:69], v[68:69], v[72:73]
	v_med3_f32 v72, v76, s76, v141
	v_pk_mul_f32 v[68:69], v[80:81], v[68:69]
	v_med3_f32 v73, v77, s76, v141
	v_med3_f32 v68, v68, s76, v141
	v_med3_f32 v69, v69, s76, v141
	v_cvt_pk_fp8_f32 v66, v72, v73 op_sel:[0,0,1]
	v_cvt_pk_fp8_f32 v67, v68, v69 op_sel:[0,0,1]
	v_exp_f32_e64 v70, -v58
	v_exp_f32_e64 v71, -v59
	v_or_b32_e32 v68, 48, v142
	v_mad_i64_i32 v[68:69], s[0:1], v68, s77, v[114:115]
	v_lshl_add_u64 v[68:69], v[68:69], 0, v[134:135]
	global_store_dwordx2 v[68:69], v[66:67], off
	v_pk_add_f32 v[66:67], v[70:71], 1.0 op_sel_hi:[1,0]
	v_exp_f32_e64 v60, -v60
	v_exp_f32_e64 v61, -v61
	v_pk_mul_f32 v[58:59], v[58:59], v[62:63]
	v_rcp_f32_e32 v62, v66
	v_rcp_f32_e32 v63, v67
	v_pk_add_f32 v[60:61], v[60:61], 1.0 op_sel_hi:[1,0]
	v_add_u32_e32 v68, 0x80, v142
	v_rcp_f32_e32 v60, v60
	v_rcp_f32_e32 v61, v61
	v_pk_mul_f32 v[58:59], v[62:63], v[58:59]
	v_exp_f32_e64 v62, -v50
	v_exp_f32_e64 v63, -v51
	v_pk_mul_f32 v[60:61], v[60:61], v[64:65]
	v_exp_f32_e64 v64, -v52
	v_exp_f32_e64 v65, -v53
	v_pk_add_f32 v[62:63], v[62:63], 1.0 op_sel_hi:[1,0]
	v_pk_mul_f32 v[50:51], v[50:51], v[54:55]
	v_rcp_f32_e32 v62, v62
	v_rcp_f32_e32 v63, v63
	v_pk_add_f32 v[64:65], v[64:65], 1.0 op_sel_hi:[1,0]
	v_med3_f32 v54, v58, s76, v141
	v_rcp_f32_e32 v64, v64
	v_rcp_f32_e32 v65, v65
	v_pk_mul_f32 v[50:51], v[62:63], v[50:51]
	v_med3_f32 v55, v59, s76, v141
	v_med3_f32 v58, v50, s76, v141
	v_med3_f32 v59, v51, s76, v141
	v_mov_b32_e32 v50, 0
	v_mov_b32_e32 v51, 0
	v_cvt_pk_fp8_f32 v50, v54, v55
	v_cvt_pk_fp8_f32 v51, v58, v59
	v_pk_mul_f32 v[52:53], v[52:53], v[56:57]
	v_med3_f32 v56, v60, s76, v141
	v_pk_mul_f32 v[52:53], v[64:65], v[52:53]
	v_med3_f32 v57, v61, s76, v141
	v_med3_f32 v52, v52, s76, v141
	v_med3_f32 v53, v53, s76, v141
	v_cvt_pk_fp8_f32 v50, v56, v57 op_sel:[0,0,1]
	v_cvt_pk_fp8_f32 v51, v52, v53 op_sel:[0,0,1]
	v_exp_f32_e64 v52, -v42
	v_exp_f32_e64 v53, -v43
	v_mad_i64_i32 v[54:55], s[0:1], v68, s77, v[114:115]
	v_lshl_add_u64 v[54:55], v[54:55], 0, v[134:135]
	global_store_dwordx2 v[54:55], v[50:51], off
	v_pk_add_f32 v[50:51], v[52:53], 1.0 op_sel_hi:[1,0]
	v_pk_mul_f32 v[48:49], v[44:45], v[48:49]
	v_exp_f32_e64 v44, -v44
	v_exp_f32_e64 v45, -v45
	v_pk_mul_f32 v[42:43], v[42:43], v[46:47]
	v_rcp_f32_e32 v46, v50
	v_rcp_f32_e32 v47, v51
	v_pk_add_f32 v[44:45], v[44:45], 1.0 op_sel_hi:[1,0]
	v_pk_mul_f32 v[32:33], v[28:29], v[32:33]
	v_rcp_f32_e32 v44, v44
	v_rcp_f32_e32 v45, v45
	v_pk_mul_f32 v[42:43], v[46:47], v[42:43]
	v_exp_f32_e64 v46, -v34
	v_exp_f32_e64 v47, -v35
	v_pk_mul_f32 v[44:45], v[44:45], v[48:49]
	v_exp_f32_e64 v48, -v36
	v_exp_f32_e64 v49, -v37
	v_pk_add_f32 v[46:47], v[46:47], 1.0 op_sel_hi:[1,0]
	v_pk_mul_f32 v[34:35], v[34:35], v[38:39]
	v_rcp_f32_e32 v46, v46
	v_rcp_f32_e32 v47, v47
	v_pk_add_f32 v[48:49], v[48:49], 1.0 op_sel_hi:[1,0]
	v_med3_f32 v38, v42, s76, v141
	v_rcp_f32_e32 v48, v48
	v_rcp_f32_e32 v49, v49
	v_pk_mul_f32 v[34:35], v[46:47], v[34:35]
	v_med3_f32 v39, v43, s76, v141
	v_med3_f32 v42, v34, s76, v141
	v_med3_f32 v43, v35, s76, v141
	v_mov_b32_e32 v34, 0
	v_mov_b32_e32 v35, 0
	v_cvt_pk_fp8_f32 v34, v38, v39
	v_cvt_pk_fp8_f32 v35, v42, v43
	v_pk_mul_f32 v[36:37], v[36:37], v[40:41]
	v_med3_f32 v40, v44, s76, v141
	v_pk_mul_f32 v[36:37], v[48:49], v[36:37]
	v_med3_f32 v41, v45, s76, v141
	v_med3_f32 v36, v36, s76, v141
	v_med3_f32 v37, v37, s76, v141
	v_cvt_pk_fp8_f32 v34, v40, v41 op_sel:[0,0,1]
	v_cvt_pk_fp8_f32 v35, v36, v37 op_sel:[0,0,1]
	v_exp_f32_e64 v36, -v26
	v_exp_f32_e64 v37, -v27
	v_add_u32_e32 v38, 0x90, v142
	v_mad_i64_i32 v[38:39], s[0:1], v38, s77, v[114:115]
	v_lshl_add_u64 v[38:39], v[38:39], 0, v[134:135]
	global_store_dwordx2 v[38:39], v[34:35], off
	v_pk_add_f32 v[34:35], v[36:37], 1.0 op_sel_hi:[1,0]
	v_exp_f32_e64 v28, -v28
	v_exp_f32_e64 v29, -v29
	v_pk_mul_f32 v[26:27], v[26:27], v[30:31]
	v_rcp_f32_e32 v30, v34
	v_rcp_f32_e32 v31, v35
	v_pk_add_f32 v[28:29], v[28:29], 1.0 op_sel_hi:[1,0]
	v_pk_mul_f32 v[16:17], v[12:13], v[16:17]
	v_rcp_f32_e32 v28, v28
	v_rcp_f32_e32 v29, v29
	v_pk_mul_f32 v[26:27], v[30:31], v[26:27]
	v_exp_f32_e64 v30, -v18
	v_exp_f32_e64 v31, -v19
	v_pk_mul_f32 v[28:29], v[28:29], v[32:33]
	v_exp_f32_e64 v32, -v20
	v_exp_f32_e64 v33, -v21
	v_pk_add_f32 v[30:31], v[30:31], 1.0 op_sel_hi:[1,0]
	v_pk_mul_f32 v[18:19], v[18:19], v[22:23]
	v_rcp_f32_e32 v30, v30
	v_rcp_f32_e32 v31, v31
	v_pk_add_f32 v[32:33], v[32:33], 1.0 op_sel_hi:[1,0]
	v_med3_f32 v22, v26, s76, v141
	v_rcp_f32_e32 v32, v32
	v_rcp_f32_e32 v33, v33
	v_pk_mul_f32 v[18:19], v[30:31], v[18:19]
	v_med3_f32 v23, v27, s76, v141
	v_med3_f32 v26, v18, s76, v141
	v_med3_f32 v27, v19, s76, v141
	v_mov_b32_e32 v18, 0
	v_mov_b32_e32 v19, 0
	v_cvt_pk_fp8_f32 v18, v22, v23
	v_cvt_pk_fp8_f32 v19, v26, v27
	v_pk_mul_f32 v[20:21], v[20:21], v[24:25]
	v_med3_f32 v24, v28, s76, v141
	v_pk_mul_f32 v[20:21], v[32:33], v[20:21]
	v_med3_f32 v25, v29, s76, v141
	v_med3_f32 v20, v20, s76, v141
	v_med3_f32 v21, v21, s76, v141
	v_cvt_pk_fp8_f32 v18, v24, v25 op_sel:[0,0,1]
	v_cvt_pk_fp8_f32 v19, v20, v21 op_sel:[0,0,1]
	v_exp_f32_e64 v20, -v10
	v_exp_f32_e64 v21, -v11
	v_add_u32_e32 v22, 0xa0, v142
	v_mad_i64_i32 v[22:23], s[0:1], v22, s77, v[114:115]
	v_lshl_add_u64 v[22:23], v[22:23], 0, v[134:135]
	global_store_dwordx2 v[22:23], v[18:19], off
	v_pk_add_f32 v[18:19], v[20:21], 1.0 op_sel_hi:[1,0]
	v_exp_f32_e64 v12, -v12
	v_exp_f32_e64 v13, -v13
	v_pk_mul_f32 v[10:11], v[10:11], v[14:15]
	v_rcp_f32_e32 v14, v18
	v_rcp_f32_e32 v15, v19
	v_pk_add_f32 v[12:13], v[12:13], 1.0 op_sel_hi:[1,0]
	v_pk_mul_f32 v[2:3], v[6:7], v[2:3]
	v_rcp_f32_e32 v12, v12
	v_rcp_f32_e32 v13, v13
	v_pk_mul_f32 v[10:11], v[14:15], v[10:11]
	v_exp_f32_e64 v14, -v6
	v_exp_f32_e64 v15, -v7
	v_pk_mul_f32 v[12:13], v[12:13], v[16:17]
	v_exp_f32_e64 v16, -v8
	v_exp_f32_e64 v17, -v9
	v_pk_add_f32 v[14:15], v[14:15], 1.0 op_sel_hi:[1,0]
	v_med3_f32 v6, v10, s76, v141
	v_rcp_f32_e32 v14, v14
	v_rcp_f32_e32 v15, v15
	v_pk_add_f32 v[16:17], v[16:17], 1.0 op_sel_hi:[1,0]
	v_med3_f32 v7, v11, s76, v141
	v_rcp_f32_e32 v16, v16
	v_rcp_f32_e32 v17, v17
	v_pk_mul_f32 v[2:3], v[14:15], v[2:3]
	v_pk_mul_f32 v[4:5], v[8:9], v[4:5]
	v_med3_f32 v10, v2, s76, v141
	v_med3_f32 v11, v3, s76, v141
	v_mov_b32_e32 v2, 0
	v_mov_b32_e32 v3, 0
	v_cvt_pk_fp8_f32 v2, v6, v7
	v_cvt_pk_fp8_f32 v3, v10, v11
	v_pk_mul_f32 v[4:5], v[16:17], v[4:5]
	v_med3_f32 v121, v124, s76, v141
	v_med3_f32 v122, v125, s76, v141
	v_med3_f32 v8, v12, s76, v141
	v_med3_f32 v9, v13, s76, v141
	v_med3_f32 v4, v4, s76, v141
	v_med3_f32 v5, v5, s76, v141
	v_cvt_pk_fp8_f32 v118, v121, v122 op_sel:[0,0,1]
	v_cvt_pk_fp8_f32 v2, v8, v9 op_sel:[0,0,1]
	v_cvt_pk_fp8_f32 v3, v4, v5 op_sel:[0,0,1]
	v_add_u32_e32 v4, 0xb0, v142
	v_mad_i64_i32 v[120:121], s[0:1], v142, s77, v[114:115]
	v_mad_i64_i32 v[4:5], s[0:1], v4, s77, v[114:115]
	v_lshl_add_u64 v[120:121], v[120:121], 0, v[134:135]
	v_lshl_add_u64 v[4:5], v[4:5], 0, v[134:135]
	s_andn2_b64 vcc, exec, s[4:5]
	s_mov_b64 s[0:1], -1
	global_store_dwordx2 v[120:121], v[118:119], off
	global_store_dwordx2 v[4:5], v[2:3], off
	s_mov_b32 s98, 1
	s_cbranch_vccnz .LBB0_553
	s_andn2_b64 vcc, exec, s[8:9]
	v_mov_b64 v[122:123], 0
	v_mov_b64 v[124:125], 0
	v_mov_b64 v[114:115], 0
	v_mov_b64 v[116:117], 0
	v_mov_b64 v[106:107], 0
	v_mov_b64 v[108:109], 0
	v_mov_b64 v[98:99], 0
	v_mov_b64 v[100:101], 0
	v_mov_b64 v[90:91], 0
	v_mov_b64 v[92:93], 0
	v_mov_b64 v[82:83], 0
	v_mov_b64 v[84:85], 0
	v_mov_b64 v[74:75], 0
	v_mov_b64 v[76:77], 0
	v_mov_b64 v[66:67], 0
	v_mov_b64 v[68:69], 0
	v_mov_b64 v[126:127], 0
	v_mov_b64 v[128:129], 0
	v_mov_b64 v[118:119], 0
	v_mov_b64 v[120:121], 0
	v_mov_b64 v[110:111], 0
	v_mov_b64 v[112:113], 0
	v_mov_b64 v[102:103], 0
	v_mov_b64 v[104:105], 0
	v_mov_b64 v[94:95], 0
	v_mov_b64 v[96:97], 0
	v_mov_b64 v[86:87], 0
	v_mov_b64 v[88:89], 0
	v_mov_b64 v[78:79], 0
	v_mov_b64 v[80:81], 0
	v_mov_b64 v[70:71], 0
	v_mov_b64 v[72:73], 0
	v_mov_b64 v[58:59], 0
	v_mov_b64 v[60:61], 0
	v_mov_b64 v[50:51], 0
	v_mov_b64 v[52:53], 0
	v_mov_b64 v[42:43], 0
	v_mov_b64 v[44:45], 0
	v_mov_b64 v[34:35], 0
	v_mov_b64 v[36:37], 0
	v_mov_b64 v[26:27], 0
	v_mov_b64 v[28:29], 0
	v_mov_b64 v[18:19], 0
	v_mov_b64 v[20:21], 0
	v_mov_b64 v[10:11], 0
	v_mov_b64 v[12:13], 0
	v_mov_b64 v[6:7], 0
	v_mov_b64 v[8:9], 0
	v_mov_b64 v[62:63], 0
	v_mov_b64 v[64:65], 0
	v_mov_b64 v[54:55], 0
	v_mov_b64 v[56:57], 0
	v_mov_b64 v[46:47], 0
	v_mov_b64 v[48:49], 0
	v_mov_b64 v[38:39], 0
	v_mov_b64 v[40:41], 0
	v_mov_b64 v[30:31], 0
	v_mov_b64 v[32:33], 0
	v_mov_b64 v[22:23], 0
	v_mov_b64 v[24:25], 0
	v_mov_b64 v[14:15], 0
	v_mov_b64 v[16:17], 0
	v_mov_b64 v[2:3], 0
	v_mov_b64 v[4:5], 0
	s_cbranch_vccnz .LBB0_552
	s_barrier
	s_branch .LBB0_552

.LBB0_794:
	v_lshrrev_b32_e32 v4, 1, v2
	v_and_b32_e32 v4, 24, v4
	v_and_b32_e32 v3, 15, v2
	v_lshlrev_b32_e32 v5, 1, v4
	v_lshlrev_b32_e32 v2, 2, v2
	v_lshl_or_b32 v137, s8, 6, v3
	v_lshl_or_b32 v3, v3, 6, v5
	s_lshl_b32 s2, s8, 13
	v_and_b32_e32 v2, 32, v2
	v_bitop3_b32 v5, v3, s2, v2 bitop3:0xde
	s_lshl_b32 s2, s9, 5
	s_sext_i32_i16 s85, s4
	s_and_b32 s4, s2, 0x60
	s_lshl_b32 s2, s4, 7
	v_bitop3_b32 v6, v3, s2, v2 bitop3:0xde
	s_add_u32 s2, s0, 0x80
	s_addc_u32 s3, s1, 0
	s_add_i32 s61, s39, 0x18000
	s_waitcnt vmcnt(2)
	s_barrier
	s_mov_b32 s8, m0
	s_mov_b32 m0, s61
	s_nop 4
	global_load_lds_dwordx4 v136, s[2:3]
	s_mov_b32 m0, s8
	s_add_u32 s2, s0, 0x20080
	s_addc_u32 s3, s1, 0
	s_add_i32 s62, s39, 0x1a000
	s_mov_b32 s8, m0
	s_mov_b32 m0, s62
	s_nop 4
	global_load_lds_dwordx4 v136, s[2:3]
	s_mov_b32 m0, s8
	s_add_u32 s2, s42, 0x80
	s_addc_u32 s3, s43, 0
	s_add_i32 s63, s39, 0x8000
	s_mov_b32 s8, m0
	s_mov_b32 m0, s63
	s_nop 4
	global_load_lds_dwordx4 v1, s[2:3]
	s_mov_b32 m0, s8
	s_add_u32 s2, s42, 0x20080
	s_addc_u32 s3, s43, 0
	s_add_i32 s64, s39, 0xa000
	s_mov_b32 s8, m0
	s_mov_b32 m0, s64
	s_nop 4
	global_load_lds_dwordx4 v1, s[2:3]
	s_mov_b32 m0, s8
	s_add_u32 s2, s0, 0x40080
	s_addc_u32 s3, s1, 0
	s_add_i32 s65, s39, 0x1c000
	s_mov_b32 s8, m0
	s_mov_b32 m0, s65
	s_nop 4
	global_load_lds_dwordx4 v136, s[2:3]
	s_mov_b32 m0, s8
	s_add_u32 s2, s0, 0x60080
	s_addc_u32 s3, s1, 0
	s_add_i32 s66, s39, 0x1e000
	s_mov_b32 s8, m0
	s_mov_b32 m0, s66
	s_nop 4
	global_load_lds_dwordx4 v136, s[2:3]
	s_mov_b32 m0, s8
	s_waitcnt vmcnt(6)
	s_add_i32 s67, s39, 0xc000
	s_cmpk_lt_u32 s5, 0x100
	v_mov_b64_e32 v[2:3], 0
	s_cselect_b64 s[8:9], -1, 0
	s_ashr_i32 s73, s72, 31
	v_or_b32_e32 v138, s4, v4
	v_mov_b64_e32 v[130:131], 0x16b0
	v_mov_b64_e32 v[132:133], 0x16af
	v_add_u32_e32 v139, 0, v6
	v_add_u32_e32 v140, 0, v5
	s_mov_b32 s82, 0xc3dc0000
	s_movk_i32 s84, 0xb00
	v_mov_b32_e32 v141, 0x43dc0000
	v_mov_b64_e32 v[4:5], v[2:3]
	v_mov_b64_e32 v[14:15], v[2:3]
	v_mov_b64_e32 v[16:17], v[2:3]
	v_mov_b64_e32 v[22:23], v[2:3]
	v_mov_b64_e32 v[24:25], v[2:3]
	v_mov_b64_e32 v[30:31], v[2:3]
	v_mov_b64_e32 v[32:33], v[2:3]
	s_waitcnt vmcnt(3)
	v_mov_b64_e32 v[38:39], v[2:3]
	v_mov_b64_e32 v[40:41], v[2:3]
	v_mov_b64_e32 v[46:47], v[2:3]
	v_mov_b64_e32 v[48:49], v[2:3]
	v_mov_b64_e32 v[54:55], v[2:3]
	v_mov_b64_e32 v[56:57], v[2:3]
	v_mov_b64_e32 v[62:63], v[2:3]
	v_mov_b64_e32 v[64:65], v[2:3]
	v_mov_b64_e32 v[6:7], v[2:3]
	v_mov_b64_e32 v[8:9], v[2:3]
	v_mov_b64_e32 v[10:11], v[2:3]
	v_mov_b64_e32 v[12:13], v[2:3]
	v_mov_b64_e32 v[18:19], v[2:3]
	v_mov_b64_e32 v[20:21], v[2:3]
	v_mov_b64_e32 v[26:27], v[2:3]
	v_mov_b64_e32 v[28:29], v[2:3]
	s_waitcnt vmcnt(2) lgkmcnt(0)
	v_mov_b64_e32 v[34:35], v[2:3]
	v_mov_b64_e32 v[36:37], v[2:3]
	v_mov_b64_e32 v[42:43], v[2:3]
	v_mov_b64_e32 v[44:45], v[2:3]
	v_mov_b64_e32 v[50:51], v[2:3]
	v_mov_b64_e32 v[52:53], v[2:3]
	v_mov_b64_e32 v[58:59], v[2:3]
	v_mov_b64_e32 v[60:61], v[2:3]
	v_mov_b64_e32 v[70:71], v[2:3]
	v_mov_b64_e32 v[72:73], v[2:3]
	v_mov_b64_e32 v[78:79], v[2:3]
	v_mov_b64_e32 v[80:81], v[2:3]
	v_mov_b64_e32 v[86:87], v[2:3]
	v_mov_b64_e32 v[88:89], v[2:3]
	v_mov_b64_e32 v[94:95], v[2:3]
	v_mov_b64_e32 v[96:97], v[2:3]
	v_mov_b64_e32 v[102:103], v[2:3]
	v_mov_b64_e32 v[104:105], v[2:3]
	v_mov_b64_e32 v[110:111], v[2:3]
	v_mov_b64_e32 v[112:113], v[2:3]
	v_mov_b64_e32 v[118:119], v[2:3]
	v_mov_b64_e32 v[120:121], v[2:3]
	v_mov_b64_e32 v[126:127], v[2:3]
	v_mov_b64_e32 v[128:129], v[2:3]
	v_mov_b64_e32 v[66:67], v[2:3]
	v_mov_b64_e32 v[68:69], v[2:3]
	v_mov_b64_e32 v[74:75], v[2:3]
	v_mov_b64_e32 v[76:77], v[2:3]
	v_mov_b64_e32 v[82:83], v[2:3]
	v_mov_b64_e32 v[84:85], v[2:3]
	v_mov_b64_e32 v[90:91], v[2:3]
	v_mov_b64_e32 v[92:93], v[2:3]
	v_mov_b64_e32 v[98:99], v[2:3]
	v_mov_b64_e32 v[100:101], v[2:3]
	v_mov_b64_e32 v[106:107], v[2:3]
	v_mov_b64_e32 v[108:109], v[2:3]
	v_mov_b64_e32 v[114:115], v[2:3]
	v_mov_b64_e32 v[116:117], v[2:3]
	v_mov_b64_e32 v[122:123], v[2:3]
	v_mov_b64_e32 v[124:125], v[2:3]
	s_barrier
	s_mov_b32 s98, 0
	s_branch .LBB0_797

.LBB0_800:
	v_add_u32_e32 v134, 0x10000, v139
	ds_read_b128 v[142:145], v134
	ds_read_b128 v[146:149], v134 offset:1024
	ds_read_b128 v[150:153], v134 offset:2048
	ds_read_b128 v[154:157], v134 offset:3072
	v_add_u32_e32 v134, 0x14000, v139
	ds_read_b128 v[158:161], v134
	ds_read_b128 v[162:165], v134 offset:1024
	ds_read_b128 v[166:169], v134 offset:2048
	ds_read_b128 v[170:173], v134 offset:3072
	s_add_u32 s0, s42, 0x100
	s_addc_u32 s1, s43, 0
	s_cmp_eq_u32 s88, 12
	s_cselect_b32 s34, s15, s0
	s_cselect_b32 s35, s14, s1
	s_cselect_b32 s50, s25, s86
	s_cselect_b32 s51, s11, s87
	s_add_u32 s44, s34, 0x80
	s_addc_u32 s45, s35, 0
	ds_read_b128 v[174:177], v140
	ds_read_b128 v[178:181], v140 offset:1024
	ds_read_b128 v[182:185], v140 offset:2048
	ds_read_b128 v[186:189], v140 offset:3072
	ds_read_b128 v[190:193], v140 offset:4096
	ds_read_b128 v[194:197], v140 offset:5120
	ds_read_b128 v[198:201], v140 offset:6144
	ds_read_b128 v[202:205], v140 offset:7168
	s_add_u32 s2, s42, 0x40080
	s_addc_u32 s3, s43, 0
	s_mov_b32 s12, m0
	s_mov_b32 m0, s67
	s_nop 4
	global_load_lds_dwordx4 v1, s[2:3]
	s_mov_b32 m0, s12
	s_add_u32 s2, s42, 0x60080
	s_addc_u32 s3, s43, 0
	s_add_i32 s12, s39, 0xe000
	s_mov_b32 s13, m0
	s_mov_b32 m0, s12
	s_nop 4
	global_load_lds_dwordx4 v1, s[2:3]
	s_mov_b32 m0, s13
	s_cmp_eq_u32 s88, -2
	s_cselect_b32 s99, s98, 0
	s_cmp_eq_u32 s99, 0
	s_cbranch_scc1 .Lw8_2_0
	s_waitcnt vmcnt(16)
	s_branch .Lwd_2_0

.Lwd_2_0:
	s_waitcnt lgkmcnt(0)
	s_barrier
	s_setprio 1
	s_waitcnt lgkmcnt(7)
	v_mfma_f32_16x16x32_bf16 v[122:125], v[142:145], v[174:177], v[122:125]
	v_mfma_f32_16x16x32_bf16 v[114:117], v[150:153], v[174:177], v[114:117]
	s_waitcnt lgkmcnt(5)
	v_mfma_f32_16x16x32_bf16 v[106:109], v[142:145], v[182:185], v[106:109]
	v_mfma_f32_16x16x32_bf16 v[98:101], v[150:153], v[182:185], v[98:101]
	s_waitcnt lgkmcnt(3)
	v_mfma_f32_16x16x32_bf16 v[90:93], v[142:145], v[190:193], v[90:93]
	v_mfma_f32_16x16x32_bf16 v[82:85], v[150:153], v[190:193], v[82:85]
	s_waitcnt lgkmcnt(1)
	v_mfma_f32_16x16x32_bf16 v[74:77], v[142:145], v[198:201], v[74:77]
	v_mfma_f32_16x16x32_bf16 v[66:69], v[150:153], v[198:201], v[66:69]
	v_mfma_f32_16x16x32_bf16 v[122:125], v[146:149], v[178:181], v[122:125]
	v_mfma_f32_16x16x32_bf16 v[114:117], v[154:157], v[178:181], v[114:117]
	v_mfma_f32_16x16x32_bf16 v[106:109], v[146:149], v[186:189], v[106:109]
	v_mfma_f32_16x16x32_bf16 v[98:101], v[154:157], v[186:189], v[98:101]
	v_mfma_f32_16x16x32_bf16 v[90:93], v[146:149], v[194:197], v[90:93]
	v_mfma_f32_16x16x32_bf16 v[82:85], v[154:157], v[194:197], v[82:85]
	s_waitcnt lgkmcnt(0)
	v_mfma_f32_16x16x32_bf16 v[74:77], v[146:149], v[202:205], v[74:77]
	v_mfma_f32_16x16x32_bf16 v[66:69], v[154:157], v[202:205], v[66:69]
	s_setprio 0
	s_setprio 1
	v_mfma_f32_16x16x32_bf16 v[126:129], v[158:161], v[174:177], v[126:129]
	v_mfma_f32_16x16x32_bf16 v[118:121], v[166:169], v[174:177], v[118:121]
	v_mfma_f32_16x16x32_bf16 v[110:113], v[158:161], v[182:185], v[110:113]
	v_mfma_f32_16x16x32_bf16 v[102:105], v[166:169], v[182:185], v[102:105]
	v_mfma_f32_16x16x32_bf16 v[94:97], v[158:161], v[190:193], v[94:97]
	v_mfma_f32_16x16x32_bf16 v[86:89], v[166:169], v[190:193], v[86:89]
	v_mfma_f32_16x16x32_bf16 v[78:81], v[158:161], v[198:201], v[78:81]
	v_mfma_f32_16x16x32_bf16 v[70:73], v[166:169], v[198:201], v[70:73]
	v_mfma_f32_16x16x32_bf16 v[126:129], v[162:165], v[178:181], v[126:129]
	v_mfma_f32_16x16x32_bf16 v[118:121], v[170:173], v[178:181], v[118:121]
	v_mfma_f32_16x16x32_bf16 v[110:113], v[162:165], v[186:189], v[110:113]
	v_mfma_f32_16x16x32_bf16 v[102:105], v[170:173], v[186:189], v[102:105]
	v_mfma_f32_16x16x32_bf16 v[94:97], v[162:165], v[194:197], v[94:97]
	v_mfma_f32_16x16x32_bf16 v[86:89], v[170:173], v[194:197], v[86:89]
	v_mfma_f32_16x16x32_bf16 v[78:81], v[162:165], v[202:205], v[78:81]
	v_mfma_f32_16x16x32_bf16 v[70:73], v[170:173], v[202:205], v[70:73]
	s_setprio 0
	s_barrier
	ds_read_b128 v[174:177], v140 offset:16384
	ds_read_b128 v[178:181], v140 offset:17408
	ds_read_b128 v[182:185], v140 offset:18432
	ds_read_b128 v[186:189], v140 offset:19456
	ds_read_b128 v[190:193], v140 offset:20480
	ds_read_b128 v[194:197], v140 offset:21504
	ds_read_b128 v[198:201], v140 offset:22528
	ds_read_b128 v[202:205], v140 offset:23552
	s_mov_b32 s2, m0
	s_mov_b32 m0, s54
	s_nop 4
	global_load_lds_dwordx4 v136, s[50:51]
	s_mov_b32 m0, s2
	s_add_u32 s2, s50, 0x20000
	s_addc_u32 s3, s51, 0
	s_mov_b32 s12, m0
	s_mov_b32 m0, s55
	s_nop 4
	global_load_lds_dwordx4 v136, s[2:3]
	s_mov_b32 m0, s12
	s_add_u32 s2, s50, 0x40000
	s_addc_u32 s3, s51, 0
	s_mov_b32 s12, m0
	s_mov_b32 m0, s56
	s_nop 4
	global_load_lds_dwordx4 v136, s[2:3]
	s_mov_b32 m0, s12
	s_add_u32 s2, s50, 0x60000
	s_addc_u32 s3, s51, 0
	s_mov_b32 s12, m0
	s_mov_b32 m0, s57
	s_nop 4
	global_load_lds_dwordx4 v136, s[2:3]
	s_mov_b32 m0, s12
	s_mov_b32 s2, m0
	s_mov_b32 m0, s39
	s_nop 4
	global_load_lds_dwordx4 v1, s[34:35]
	s_mov_b32 m0, s2
	s_add_u32 s2, s34, 0x20000
	s_addc_u32 s3, s35, 0
	s_mov_b32 s12, m0
	s_mov_b32 m0, s58
	s_nop 4
	global_load_lds_dwordx4 v1, s[2:3]
	s_mov_b32 m0, s12
	s_cmp_eq_u32 s88, -2
	s_cselect_b32 s99, s98, 0
	s_cmp_eq_u32 s99, 0
	s_cbranch_scc1 .Lw8_2_1
	s_waitcnt vmcnt(16)
	s_branch .Lwd_2_1

.Lwd_2_1:
	s_waitcnt lgkmcnt(0)
	s_barrier
	s_setprio 1
	s_waitcnt lgkmcnt(7)
	v_mfma_f32_16x16x32_bf16 v[58:61], v[142:145], v[174:177], v[58:61]
	v_mfma_f32_16x16x32_bf16 v[50:53], v[150:153], v[174:177], v[50:53]
	s_waitcnt lgkmcnt(5)
	v_mfma_f32_16x16x32_bf16 v[42:45], v[142:145], v[182:185], v[42:45]
	v_mfma_f32_16x16x32_bf16 v[34:37], v[150:153], v[182:185], v[34:37]
	s_waitcnt lgkmcnt(3)
	v_mfma_f32_16x16x32_bf16 v[26:29], v[142:145], v[190:193], v[26:29]
	v_mfma_f32_16x16x32_bf16 v[18:21], v[150:153], v[190:193], v[18:21]
	s_waitcnt lgkmcnt(1)
	v_mfma_f32_16x16x32_bf16 v[10:13], v[142:145], v[198:201], v[10:13]
	v_mfma_f32_16x16x32_bf16 v[6:9], v[150:153], v[198:201], v[6:9]
	v_mfma_f32_16x16x32_bf16 v[58:61], v[146:149], v[178:181], v[58:61]
	v_mfma_f32_16x16x32_bf16 v[50:53], v[154:157], v[178:181], v[50:53]
	v_mfma_f32_16x16x32_bf16 v[42:45], v[146:149], v[186:189], v[42:45]
	v_mfma_f32_16x16x32_bf16 v[34:37], v[154:157], v[186:189], v[34:37]
	v_mfma_f32_16x16x32_bf16 v[26:29], v[146:149], v[194:197], v[26:29]
	v_mfma_f32_16x16x32_bf16 v[18:21], v[154:157], v[194:197], v[18:21]
	s_waitcnt lgkmcnt(0)
	v_mfma_f32_16x16x32_bf16 v[10:13], v[146:149], v[202:205], v[10:13]
	v_mfma_f32_16x16x32_bf16 v[6:9], v[154:157], v[202:205], v[6:9]
	s_setprio 0
	s_setprio 1
	v_mfma_f32_16x16x32_bf16 v[62:65], v[158:161], v[174:177], v[62:65]
	v_mfma_f32_16x16x32_bf16 v[54:57], v[166:169], v[174:177], v[54:57]
	v_mfma_f32_16x16x32_bf16 v[46:49], v[158:161], v[182:185], v[46:49]
	v_mfma_f32_16x16x32_bf16 v[38:41], v[166:169], v[182:185], v[38:41]
	v_mfma_f32_16x16x32_bf16 v[30:33], v[158:161], v[190:193], v[30:33]
	v_mfma_f32_16x16x32_bf16 v[22:25], v[166:169], v[190:193], v[22:25]
	v_mfma_f32_16x16x32_bf16 v[14:17], v[158:161], v[198:201], v[14:17]
	v_mfma_f32_16x16x32_bf16 v[2:5], v[166:169], v[198:201], v[2:5]
	v_mfma_f32_16x16x32_bf16 v[62:65], v[162:165], v[178:181], v[62:65]
	v_mfma_f32_16x16x32_bf16 v[54:57], v[170:173], v[178:181], v[54:57]
	v_mfma_f32_16x16x32_bf16 v[46:49], v[162:165], v[186:189], v[46:49]
	v_mfma_f32_16x16x32_bf16 v[38:41], v[170:173], v[186:189], v[38:41]
	v_mfma_f32_16x16x32_bf16 v[30:33], v[162:165], v[194:197], v[30:33]
	v_mfma_f32_16x16x32_bf16 v[22:25], v[170:173], v[194:197], v[22:25]
	v_mfma_f32_16x16x32_bf16 v[14:17], v[162:165], v[202:205], v[14:17]
	v_mfma_f32_16x16x32_bf16 v[2:5], v[170:173], v[202:205], v[2:5]
	s_setprio 0
	s_barrier
	v_add_u32_e32 v134, 0x18000, v139
	ds_read_b128 v[142:145], v134
	ds_read_b128 v[146:149], v134 offset:1024
	ds_read_b128 v[150:153], v134 offset:2048
	ds_read_b128 v[154:157], v134 offset:3072
	v_add_u32_e32 v134, 0x1c000, v139
	ds_read_b128 v[158:161], v134
	ds_read_b128 v[162:165], v134 offset:1024
	ds_read_b128 v[166:169], v134 offset:2048
	ds_read_b128 v[170:173], v134 offset:3072
	ds_read_b128 v[174:177], v140 offset:32768
	ds_read_b128 v[178:181], v140 offset:33792
	ds_read_b128 v[182:185], v140 offset:34816
	ds_read_b128 v[186:189], v140 offset:35840
	ds_read_b128 v[190:193], v140 offset:36864
	ds_read_b128 v[194:197], v140 offset:37888
	ds_read_b128 v[198:201], v140 offset:38912
	ds_read_b128 v[202:205], v140 offset:39936
	s_add_u32 s2, s34, 0x40000
	s_addc_u32 s3, s35, 0
	s_mov_b32 s12, m0
	s_mov_b32 m0, s59
	s_nop 4
	global_load_lds_dwordx4 v1, s[2:3]
	s_mov_b32 m0, s12
	s_add_u32 s2, s34, 0x60000
	s_addc_u32 s3, s35, 0
	s_mov_b32 s12, m0
	s_mov_b32 m0, s60
	s_nop 4
	global_load_lds_dwordx4 v1, s[2:3]
	s_mov_b32 m0, s12
	s_waitcnt vmcnt(8)
	s_waitcnt lgkmcnt(0)
	s_barrier
	s_setprio 1
	s_waitcnt lgkmcnt(7)
	v_mfma_f32_16x16x32_bf16 v[122:125], v[142:145], v[174:177], v[122:125]
	v_mfma_f32_16x16x32_bf16 v[114:117], v[150:153], v[174:177], v[114:117]
	s_waitcnt lgkmcnt(5)
	v_mfma_f32_16x16x32_bf16 v[106:109], v[142:145], v[182:185], v[106:109]
	v_mfma_f32_16x16x32_bf16 v[98:101], v[150:153], v[182:185], v[98:101]
	s_waitcnt lgkmcnt(3)
	v_mfma_f32_16x16x32_bf16 v[90:93], v[142:145], v[190:193], v[90:93]
	v_mfma_f32_16x16x32_bf16 v[82:85], v[150:153], v[190:193], v[82:85]
	s_waitcnt lgkmcnt(1)
	v_mfma_f32_16x16x32_bf16 v[74:77], v[142:145], v[198:201], v[74:77]
	v_mfma_f32_16x16x32_bf16 v[66:69], v[150:153], v[198:201], v[66:69]
	v_mfma_f32_16x16x32_bf16 v[122:125], v[146:149], v[178:181], v[122:125]
	v_mfma_f32_16x16x32_bf16 v[114:117], v[154:157], v[178:181], v[114:117]
	v_mfma_f32_16x16x32_bf16 v[106:109], v[146:149], v[186:189], v[106:109]
	v_mfma_f32_16x16x32_bf16 v[98:101], v[154:157], v[186:189], v[98:101]
	v_mfma_f32_16x16x32_bf16 v[90:93], v[146:149], v[194:197], v[90:93]
	v_mfma_f32_16x16x32_bf16 v[82:85], v[154:157], v[194:197], v[82:85]
	s_waitcnt lgkmcnt(0)
	v_mfma_f32_16x16x32_bf16 v[74:77], v[146:149], v[202:205], v[74:77]
	v_mfma_f32_16x16x32_bf16 v[66:69], v[154:157], v[202:205], v[66:69]
	s_setprio 0
	s_setprio 1
	v_mfma_f32_16x16x32_bf16 v[126:129], v[158:161], v[174:177], v[126:129]
	v_mfma_f32_16x16x32_bf16 v[118:121], v[166:169], v[174:177], v[118:121]
	v_mfma_f32_16x16x32_bf16 v[110:113], v[158:161], v[182:185], v[110:113]
	v_mfma_f32_16x16x32_bf16 v[102:105], v[166:169], v[182:185], v[102:105]
	v_mfma_f32_16x16x32_bf16 v[94:97], v[158:161], v[190:193], v[94:97]
	v_mfma_f32_16x16x32_bf16 v[86:89], v[166:169], v[190:193], v[86:89]
	v_mfma_f32_16x16x32_bf16 v[78:81], v[158:161], v[198:201], v[78:81]
	v_mfma_f32_16x16x32_bf16 v[70:73], v[166:169], v[198:201], v[70:73]
	v_mfma_f32_16x16x32_bf16 v[126:129], v[162:165], v[178:181], v[126:129]
	v_mfma_f32_16x16x32_bf16 v[118:121], v[170:173], v[178:181], v[118:121]
	v_mfma_f32_16x16x32_bf16 v[110:113], v[162:165], v[186:189], v[110:113]
	v_mfma_f32_16x16x32_bf16 v[102:105], v[170:173], v[186:189], v[102:105]
	v_mfma_f32_16x16x32_bf16 v[94:97], v[162:165], v[194:197], v[94:97]
	v_mfma_f32_16x16x32_bf16 v[86:89], v[170:173], v[194:197], v[86:89]
	v_mfma_f32_16x16x32_bf16 v[78:81], v[162:165], v[202:205], v[78:81]
	v_mfma_f32_16x16x32_bf16 v[70:73], v[170:173], v[202:205], v[70:73]
	s_setprio 0
	s_barrier
	s_add_u32 s2, s50, 0x80
	s_addc_u32 s3, s51, 0
	ds_read_b128 v[174:177], v140 offset:49152
	ds_read_b128 v[178:181], v140 offset:50176
	ds_read_b128 v[182:185], v140 offset:51200
	ds_read_b128 v[186:189], v140 offset:52224
	ds_read_b128 v[190:193], v140 offset:53248
	ds_read_b128 v[194:197], v140 offset:54272
	ds_read_b128 v[198:201], v140 offset:55296
	ds_read_b128 v[202:205], v140 offset:56320
	s_mov_b32 s12, m0
	s_mov_b32 m0, s61
	s_nop 4
	global_load_lds_dwordx4 v136, s[2:3]
	s_mov_b32 m0, s12
	s_add_u32 s2, s50, 0x20080
	s_addc_u32 s3, s51, 0
	s_mov_b32 s12, m0
	s_mov_b32 m0, s62
	s_nop 4
	global_load_lds_dwordx4 v136, s[2:3]
	s_mov_b32 m0, s12
	s_add_u32 s2, s50, 0x40080
	s_addc_u32 s3, s51, 0
	s_mov_b32 s12, m0
	s_mov_b32 m0, s65
	s_nop 4
	global_load_lds_dwordx4 v136, s[2:3]
	s_mov_b32 m0, s12
	s_add_u32 s2, s50, 0x60080
	s_addc_u32 s3, s51, 0
	s_mov_b32 s12, m0
	s_mov_b32 m0, s66
	s_nop 4
	global_load_lds_dwordx4 v136, s[2:3]
	s_mov_b32 m0, s12
	s_mov_b32 s2, m0
	s_mov_b32 m0, s63
	s_nop 4
	global_load_lds_dwordx4 v1, s[44:45]
	s_mov_b32 m0, s2
	s_add_u32 s2, s34, 0x20080
	s_addc_u32 s3, s35, 0
	s_mov_b32 s12, m0
	s_mov_b32 m0, s64
	s_nop 4
	global_load_lds_dwordx4 v1, s[2:3]
	s_mov_b32 m0, s12
	s_waitcnt vmcnt(8)
	s_waitcnt lgkmcnt(0)
	s_barrier
	s_setprio 1
	s_waitcnt lgkmcnt(7)
	v_mfma_f32_16x16x32_bf16 v[58:61], v[142:145], v[174:177], v[58:61]
	v_mfma_f32_16x16x32_bf16 v[50:53], v[150:153], v[174:177], v[50:53]
	s_waitcnt lgkmcnt(5)
	v_mfma_f32_16x16x32_bf16 v[42:45], v[142:145], v[182:185], v[42:45]
	v_mfma_f32_16x16x32_bf16 v[34:37], v[150:153], v[182:185], v[34:37]
	s_waitcnt lgkmcnt(3)
	v_mfma_f32_16x16x32_bf16 v[26:29], v[142:145], v[190:193], v[26:29]
	v_mfma_f32_16x16x32_bf16 v[18:21], v[150:153], v[190:193], v[18:21]
	s_waitcnt lgkmcnt(1)
	v_mfma_f32_16x16x32_bf16 v[10:13], v[142:145], v[198:201], v[10:13]
	v_mfma_f32_16x16x32_bf16 v[6:9], v[150:153], v[198:201], v[6:9]
	v_mfma_f32_16x16x32_bf16 v[58:61], v[146:149], v[178:181], v[58:61]
	v_mfma_f32_16x16x32_bf16 v[50:53], v[154:157], v[178:181], v[50:53]
	v_mfma_f32_16x16x32_bf16 v[42:45], v[146:149], v[186:189], v[42:45]
	v_mfma_f32_16x16x32_bf16 v[34:37], v[154:157], v[186:189], v[34:37]
	v_mfma_f32_16x16x32_bf16 v[26:29], v[146:149], v[194:197], v[26:29]
	v_mfma_f32_16x16x32_bf16 v[18:21], v[154:157], v[194:197], v[18:21]
	s_waitcnt lgkmcnt(0)
	v_mfma_f32_16x16x32_bf16 v[10:13], v[146:149], v[202:205], v[10:13]
	v_mfma_f32_16x16x32_bf16 v[6:9], v[154:157], v[202:205], v[6:9]
	s_setprio 0
	s_setprio 1
	v_mfma_f32_16x16x32_bf16 v[62:65], v[158:161], v[174:177], v[62:65]
	v_mfma_f32_16x16x32_bf16 v[54:57], v[166:169], v[174:177], v[54:57]
	v_mfma_f32_16x16x32_bf16 v[46:49], v[158:161], v[182:185], v[46:49]
	v_mfma_f32_16x16x32_bf16 v[38:41], v[166:169], v[182:185], v[38:41]
	v_mfma_f32_16x16x32_bf16 v[30:33], v[158:161], v[190:193], v[30:33]
	v_mfma_f32_16x16x32_bf16 v[22:25], v[166:169], v[190:193], v[22:25]
	v_mfma_f32_16x16x32_bf16 v[14:17], v[158:161], v[198:201], v[14:17]
	v_mfma_f32_16x16x32_bf16 v[2:5], v[166:169], v[198:201], v[2:5]
	v_mfma_f32_16x16x32_bf16 v[62:65], v[162:165], v[178:181], v[62:65]
	v_mfma_f32_16x16x32_bf16 v[54:57], v[170:173], v[178:181], v[54:57]
	v_mfma_f32_16x16x32_bf16 v[46:49], v[162:165], v[186:189], v[46:49]
	v_mfma_f32_16x16x32_bf16 v[38:41], v[170:173], v[186:189], v[38:41]
	v_mfma_f32_16x16x32_bf16 v[30:33], v[162:165], v[194:197], v[30:33]
	v_mfma_f32_16x16x32_bf16 v[22:25], v[170:173], v[194:197], v[22:25]
	v_mfma_f32_16x16x32_bf16 v[14:17], v[162:165], v[202:205], v[14:17]
	v_mfma_f32_16x16x32_bf16 v[2:5], v[170:173], v[202:205], v[2:5]
	s_setprio 0
	s_barrier
	s_add_i32 s88, s88, 2
	s_add_u32 s86, s86, 0x100
	s_addc_u32 s87, s87, 0
	s_cmp_gt_u32 s88, 13
	s_mov_b64 s[42:43], s[0:1]
	s_cbranch_scc0 .LBB0_800
	s_and_b64 vcc, exec, s[8:9]
	s_cbranch_vccz .LBB0_803
	s_barrier
.LBB0_803:
	v_exp_f32_e64 v144, -v122
	v_exp_f32_e64 v145, -v123
	v_pk_mul_f32 v[128:129], v[124:125], v[128:129]
	v_exp_f32_e64 v124, -v124
	v_exp_f32_e64 v125, -v125
	v_pk_add_f32 v[144:145], v[144:145], 1.0 op_sel_hi:[1,0]
	v_pk_mul_f32 v[122:123], v[122:123], v[126:127]
	v_rcp_f32_e32 v126, v144
	v_rcp_f32_e32 v127, v145
	v_pk_add_f32 v[124:125], v[124:125], 1.0 op_sel_hi:[1,0]
	v_pk_mul_f32 v[112:113], v[108:109], v[112:113]
	v_rcp_f32_e32 v124, v124
	v_rcp_f32_e32 v125, v125
	v_pk_mul_f32 v[122:123], v[126:127], v[122:123]
	v_exp_f32_e64 v126, -v114
	v_exp_f32_e64 v127, -v115
	v_pk_mul_f32 v[124:125], v[124:125], v[128:129]
	v_exp_f32_e64 v128, -v116
	v_exp_f32_e64 v129, -v117
	v_pk_add_f32 v[126:127], v[126:127], 1.0 op_sel_hi:[1,0]
	v_pk_mul_f32 v[114:115], v[114:115], v[118:119]
	v_rcp_f32_e32 v126, v126
	v_rcp_f32_e32 v127, v127
	v_pk_add_f32 v[128:129], v[128:129], 1.0 op_sel_hi:[1,0]
	v_pk_mul_f32 v[116:117], v[116:117], v[120:121]
	v_rcp_f32_e32 v128, v128
	v_rcp_f32_e32 v129, v129
	v_pk_mul_f32 v[114:115], v[126:127], v[114:115]
	v_med3_f32 v119, v122, s82, v141
	v_med3_f32 v120, v123, s82, v141
	v_mov_b32_e32 v118, 0
	v_pk_mul_f32 v[116:117], v[128:129], v[116:117]
	v_med3_f32 v114, v114, s82, v141
	v_med3_f32 v115, v115, s82, v141
	v_cvt_pk_fp8_f32 v118, v119, v120
	v_mov_b32_e32 v119, 0
	v_cvt_pk_fp8_f32 v119, v114, v115
	v_med3_f32 v114, v116, s82, v141
	v_med3_f32 v115, v117, s82, v141
	v_exp_f32_e64 v116, -v106
	v_exp_f32_e64 v117, -v107
	v_exp_f32_e64 v108, -v108
	v_exp_f32_e64 v109, -v109
	v_pk_mul_f32 v[106:107], v[106:107], v[110:111]
	v_pk_add_f32 v[116:117], v[116:117], 1.0 op_sel_hi:[1,0]
	v_lshl_add_u32 v142, s38, 8, v137
	v_rcp_f32_e32 v110, v116
	v_rcp_f32_e32 v111, v117
	v_pk_add_f32 v[108:109], v[108:109], 1.0 op_sel_hi:[1,0]
	v_lshl_or_b32 v134, s85, 7, v138
	v_rcp_f32_e32 v108, v108
	v_rcp_f32_e32 v109, v109
	v_pk_mul_f32 v[106:107], v[110:111], v[106:107]
	v_exp_f32_e64 v110, -v98
	v_exp_f32_e64 v111, -v99
	v_pk_mul_f32 v[108:109], v[108:109], v[112:113]
	v_exp_f32_e64 v112, -v100
	v_exp_f32_e64 v113, -v101
	v_pk_add_f32 v[110:111], v[110:111], 1.0 op_sel_hi:[1,0]
	v_pk_mul_f32 v[98:99], v[98:99], v[102:103]
	v_rcp_f32_e32 v110, v110
	v_rcp_f32_e32 v111, v111
	v_pk_add_f32 v[112:113], v[112:113], 1.0 op_sel_hi:[1,0]
	v_med3_f32 v102, v106, s82, v141
	v_rcp_f32_e32 v112, v112
	v_rcp_f32_e32 v113, v113
	v_pk_mul_f32 v[98:99], v[110:111], v[98:99]
	v_med3_f32 v103, v107, s82, v141
	v_med3_f32 v106, v98, s82, v141
	v_med3_f32 v107, v99, s82, v141
	v_mov_b32_e32 v98, 0
	v_mov_b32_e32 v99, 0
	v_cvt_pk_fp8_f32 v98, v102, v103
	v_cvt_pk_fp8_f32 v99, v106, v107
	v_pk_mul_f32 v[100:101], v[100:101], v[104:105]
	v_med3_f32 v104, v108, s82, v141
	v_pk_mul_f32 v[100:101], v[112:113], v[100:101]
	v_med3_f32 v105, v109, s82, v141
	v_med3_f32 v100, v100, s82, v141
	v_med3_f32 v101, v101, s82, v141
	v_cvt_pk_fp8_f32 v98, v104, v105 op_sel:[0,0,1]
	v_cvt_pk_fp8_f32 v99, v100, v101 op_sel:[0,0,1]
	v_exp_f32_e64 v100, -v90
	v_exp_f32_e64 v101, -v91
	v_cvt_pk_fp8_f32 v119, v114, v115 op_sel:[0,0,1]
	v_mov_b64_e32 v[114:115], s[18:19]
	v_or_b32_e32 v102, 16, v142
	v_ashrrev_i32_e32 v135, 31, v134
	v_mad_i64_i32 v[102:103], s[0:1], v102, s84, v[114:115]
	v_lshl_add_u64 v[102:103], v[102:103], 0, v[134:135]
	global_store_dwordx2 v[102:103], v[98:99], off
	v_pk_add_f32 v[98:99], v[100:101], 1.0 op_sel_hi:[1,0]
	v_pk_mul_f32 v[96:97], v[92:93], v[96:97]
	v_exp_f32_e64 v92, -v92
	v_exp_f32_e64 v93, -v93
	v_pk_mul_f32 v[90:91], v[90:91], v[94:95]
	v_rcp_f32_e32 v94, v98
	v_rcp_f32_e32 v95, v99
	v_pk_add_f32 v[92:93], v[92:93], 1.0 op_sel_hi:[1,0]
	v_pk_mul_f32 v[80:81], v[76:77], v[80:81]
	v_rcp_f32_e32 v92, v92
	v_rcp_f32_e32 v93, v93
	v_pk_mul_f32 v[90:91], v[94:95], v[90:91]
	v_exp_f32_e64 v94, -v82
	v_exp_f32_e64 v95, -v83
	v_pk_mul_f32 v[92:93], v[92:93], v[96:97]
	v_exp_f32_e64 v96, -v84
	v_exp_f32_e64 v97, -v85
	v_pk_add_f32 v[94:95], v[94:95], 1.0 op_sel_hi:[1,0]
	v_pk_mul_f32 v[82:83], v[82:83], v[86:87]
	v_rcp_f32_e32 v94, v94
	v_rcp_f32_e32 v95, v95
	v_pk_add_f32 v[96:97], v[96:97], 1.0 op_sel_hi:[1,0]
	v_med3_f32 v86, v90, s82, v141
	v_rcp_f32_e32 v96, v96
	v_rcp_f32_e32 v97, v97
	v_pk_mul_f32 v[82:83], v[94:95], v[82:83]
	v_med3_f32 v87, v91, s82, v141
	v_med3_f32 v90, v82, s82, v141
	v_med3_f32 v91, v83, s82, v141
	v_mov_b32_e32 v82, 0
	v_mov_b32_e32 v83, 0
	v_cvt_pk_fp8_f32 v82, v86, v87
	v_cvt_pk_fp8_f32 v83, v90, v91
	v_pk_mul_f32 v[84:85], v[84:85], v[88:89]
	v_med3_f32 v88, v92, s82, v141
	v_pk_mul_f32 v[84:85], v[96:97], v[84:85]
	v_med3_f32 v89, v93, s82, v141
	v_med3_f32 v84, v84, s82, v141
	v_med3_f32 v85, v85, s82, v141
	v_cvt_pk_fp8_f32 v82, v88, v89 op_sel:[0,0,1]
	v_cvt_pk_fp8_f32 v83, v84, v85 op_sel:[0,0,1]
	v_exp_f32_e64 v84, -v74
	v_exp_f32_e64 v85, -v75
	v_or_b32_e32 v86, 32, v142
	v_mad_i64_i32 v[86:87], s[0:1], v86, s84, v[114:115]
	v_lshl_add_u64 v[86:87], v[86:87], 0, v[134:135]
	global_store_dwordx2 v[86:87], v[82:83], off
	v_pk_add_f32 v[82:83], v[84:85], 1.0 op_sel_hi:[1,0]
	v_exp_f32_e64 v76, -v76
	v_exp_f32_e64 v77, -v77
	v_pk_mul_f32 v[74:75], v[74:75], v[78:79]
	v_rcp_f32_e32 v78, v82
	v_rcp_f32_e32 v79, v83
	v_pk_add_f32 v[76:77], v[76:77], 1.0 op_sel_hi:[1,0]
	v_pk_mul_f32 v[64:65], v[60:61], v[64:65]
	v_rcp_f32_e32 v76, v76
	v_rcp_f32_e32 v77, v77
	v_pk_mul_f32 v[74:75], v[78:79], v[74:75]
	v_exp_f32_e64 v78, -v66
	v_exp_f32_e64 v79, -v67
	v_pk_mul_f32 v[76:77], v[76:77], v[80:81]
	v_exp_f32_e64 v80, -v68
	v_exp_f32_e64 v81, -v69
	v_pk_add_f32 v[78:79], v[78:79], 1.0 op_sel_hi:[1,0]
	v_pk_mul_f32 v[66:67], v[66:67], v[70:71]
	v_rcp_f32_e32 v78, v78
	v_rcp_f32_e32 v79, v79
	v_pk_add_f32 v[80:81], v[80:81], 1.0 op_sel_hi:[1,0]
	v_med3_f32 v70, v74, s82, v141
	v_rcp_f32_e32 v80, v80
	v_rcp_f32_e32 v81, v81
	v_pk_mul_f32 v[66:67], v[78:79], v[66:67]
	v_med3_f32 v71, v75, s82, v141
	v_med3_f32 v74, v66, s82, v141
	v_med3_f32 v75, v67, s82, v141
	v_mov_b32_e32 v66, 0
	v_mov_b32_e32 v67, 0
	v_cvt_pk_fp8_f32 v66, v70, v71
	v_cvt_pk_fp8_f32 v67, v74, v75
	v_pk_mul_f32 v[68:69], v[68:69], v[72:73]
	v_med3_f32 v72, v76, s82, v141
	v_pk_mul_f32 v[68:69], v[80:81], v[68:69]
	v_med3_f32 v73, v77, s82, v141
	v_med3_f32 v68, v68, s82, v141
	v_med3_f32 v69, v69, s82, v141
	v_cvt_pk_fp8_f32 v66, v72, v73 op_sel:[0,0,1]
	v_cvt_pk_fp8_f32 v67, v68, v69 op_sel:[0,0,1]
	v_exp_f32_e64 v70, -v58
	v_exp_f32_e64 v71, -v59
	v_or_b32_e32 v68, 48, v142
	v_mad_i64_i32 v[68:69], s[0:1], v68, s84, v[114:115]
	v_lshl_add_u64 v[68:69], v[68:69], 0, v[134:135]
	global_store_dwordx2 v[68:69], v[66:67], off
	v_pk_add_f32 v[66:67], v[70:71], 1.0 op_sel_hi:[1,0]
	v_exp_f32_e64 v60, -v60
	v_exp_f32_e64 v61, -v61
	v_pk_mul_f32 v[58:59], v[58:59], v[62:63]
	v_rcp_f32_e32 v62, v66
	v_rcp_f32_e32 v63, v67
	v_pk_add_f32 v[60:61], v[60:61], 1.0 op_sel_hi:[1,0]
	v_add_u32_e32 v68, 0x80, v142
	v_rcp_f32_e32 v60, v60
	v_rcp_f32_e32 v61, v61
	v_pk_mul_f32 v[58:59], v[62:63], v[58:59]
	v_exp_f32_e64 v62, -v50
	v_exp_f32_e64 v63, -v51
	v_pk_mul_f32 v[60:61], v[60:61], v[64:65]
	v_exp_f32_e64 v64, -v52
	v_exp_f32_e64 v65, -v53
	v_pk_add_f32 v[62:63], v[62:63], 1.0 op_sel_hi:[1,0]
	v_pk_mul_f32 v[50:51], v[50:51], v[54:55]
	v_rcp_f32_e32 v62, v62
	v_rcp_f32_e32 v63, v63
	v_pk_add_f32 v[64:65], v[64:65], 1.0 op_sel_hi:[1,0]
	v_med3_f32 v54, v58, s82, v141
	v_rcp_f32_e32 v64, v64
	v_rcp_f32_e32 v65, v65
	v_pk_mul_f32 v[50:51], v[62:63], v[50:51]
	v_med3_f32 v55, v59, s82, v141
	v_med3_f32 v58, v50, s82, v141
	v_med3_f32 v59, v51, s82, v141
	v_mov_b32_e32 v50, 0
	v_mov_b32_e32 v51, 0
	v_cvt_pk_fp8_f32 v50, v54, v55
	v_cvt_pk_fp8_f32 v51, v58, v59
	v_pk_mul_f32 v[52:53], v[52:53], v[56:57]
	v_med3_f32 v56, v60, s82, v141
	v_pk_mul_f32 v[52:53], v[64:65], v[52:53]
	v_med3_f32 v57, v61, s82, v141
	v_med3_f32 v52, v52, s82, v141
	v_med3_f32 v53, v53, s82, v141
	v_cvt_pk_fp8_f32 v50, v56, v57 op_sel:[0,0,1]
	v_cvt_pk_fp8_f32 v51, v52, v53 op_sel:[0,0,1]
	v_exp_f32_e64 v52, -v42
	v_exp_f32_e64 v53, -v43
	v_mad_i64_i32 v[54:55], s[0:1], v68, s84, v[114:115]
	v_lshl_add_u64 v[54:55], v[54:55], 0, v[134:135]
	global_store_dwordx2 v[54:55], v[50:51], off
	v_pk_add_f32 v[50:51], v[52:53], 1.0 op_sel_hi:[1,0]
	v_pk_mul_f32 v[48:49], v[44:45], v[48:49]
	v_exp_f32_e64 v44, -v44
	v_exp_f32_e64 v45, -v45
	v_pk_mul_f32 v[42:43], v[42:43], v[46:47]
	v_rcp_f32_e32 v46, v50
	v_rcp_f32_e32 v47, v51
	v_pk_add_f32 v[44:45], v[44:45], 1.0 op_sel_hi:[1,0]
	v_pk_mul_f32 v[32:33], v[28:29], v[32:33]
	v_rcp_f32_e32 v44, v44
	v_rcp_f32_e32 v45, v45
	v_pk_mul_f32 v[42:43], v[46:47], v[42:43]
	v_exp_f32_e64 v46, -v34
	v_exp_f32_e64 v47, -v35
	v_pk_mul_f32 v[44:45], v[44:45], v[48:49]
	v_exp_f32_e64 v48, -v36
	v_exp_f32_e64 v49, -v37
	v_pk_add_f32 v[46:47], v[46:47], 1.0 op_sel_hi:[1,0]
	v_pk_mul_f32 v[34:35], v[34:35], v[38:39]
	v_rcp_f32_e32 v46, v46
	v_rcp_f32_e32 v47, v47
	v_pk_add_f32 v[48:49], v[48:49], 1.0 op_sel_hi:[1,0]
	v_med3_f32 v38, v42, s82, v141
	v_rcp_f32_e32 v48, v48
	v_rcp_f32_e32 v49, v49
	v_pk_mul_f32 v[34:35], v[46:47], v[34:35]
	v_med3_f32 v39, v43, s82, v141
	v_med3_f32 v42, v34, s82, v141
	v_med3_f32 v43, v35, s82, v141
	v_mov_b32_e32 v34, 0
	v_mov_b32_e32 v35, 0
	v_cvt_pk_fp8_f32 v34, v38, v39
	v_cvt_pk_fp8_f32 v35, v42, v43
	v_pk_mul_f32 v[36:37], v[36:37], v[40:41]
	v_med3_f32 v40, v44, s82, v141
	v_pk_mul_f32 v[36:37], v[48:49], v[36:37]
	v_med3_f32 v41, v45, s82, v141
	v_med3_f32 v36, v36, s82, v141
	v_med3_f32 v37, v37, s82, v141
	v_cvt_pk_fp8_f32 v34, v40, v41 op_sel:[0,0,1]
	v_cvt_pk_fp8_f32 v35, v36, v37 op_sel:[0,0,1]
	v_exp_f32_e64 v36, -v26
	v_exp_f32_e64 v37, -v27
	v_add_u32_e32 v38, 0x90, v142
	v_mad_i64_i32 v[38:39], s[0:1], v38, s84, v[114:115]
	v_lshl_add_u64 v[38:39], v[38:39], 0, v[134:135]
	global_store_dwordx2 v[38:39], v[34:35], off
	v_pk_add_f32 v[34:35], v[36:37], 1.0 op_sel_hi:[1,0]
	v_exp_f32_e64 v28, -v28
	v_exp_f32_e64 v29, -v29
	v_pk_mul_f32 v[26:27], v[26:27], v[30:31]
	v_rcp_f32_e32 v30, v34
	v_rcp_f32_e32 v31, v35
	v_pk_add_f32 v[28:29], v[28:29], 1.0 op_sel_hi:[1,0]
	v_pk_mul_f32 v[16:17], v[12:13], v[16:17]
	v_rcp_f32_e32 v28, v28
	v_rcp_f32_e32 v29, v29
	v_pk_mul_f32 v[26:27], v[30:31], v[26:27]
	v_exp_f32_e64 v30, -v18
	v_exp_f32_e64 v31, -v19
	v_pk_mul_f32 v[28:29], v[28:29], v[32:33]
	v_exp_f32_e64 v32, -v20
	v_exp_f32_e64 v33, -v21
	v_pk_add_f32 v[30:31], v[30:31], 1.0 op_sel_hi:[1,0]
	v_pk_mul_f32 v[18:19], v[18:19], v[22:23]
	v_rcp_f32_e32 v30, v30
	v_rcp_f32_e32 v31, v31
	v_pk_add_f32 v[32:33], v[32:33], 1.0 op_sel_hi:[1,0]
	v_med3_f32 v22, v26, s82, v141
	v_rcp_f32_e32 v32, v32
	v_rcp_f32_e32 v33, v33
	v_pk_mul_f32 v[18:19], v[30:31], v[18:19]
	v_med3_f32 v23, v27, s82, v141
	v_med3_f32 v26, v18, s82, v141
	v_med3_f32 v27, v19, s82, v141
	v_mov_b32_e32 v18, 0
	v_mov_b32_e32 v19, 0
	v_cvt_pk_fp8_f32 v18, v22, v23
	v_cvt_pk_fp8_f32 v19, v26, v27
	v_pk_mul_f32 v[20:21], v[20:21], v[24:25]
	v_med3_f32 v24, v28, s82, v141
	v_pk_mul_f32 v[20:21], v[32:33], v[20:21]
	v_med3_f32 v25, v29, s82, v141
	v_med3_f32 v20, v20, s82, v141
	v_med3_f32 v21, v21, s82, v141
	v_cvt_pk_fp8_f32 v18, v24, v25 op_sel:[0,0,1]
	v_cvt_pk_fp8_f32 v19, v20, v21 op_sel:[0,0,1]
	v_exp_f32_e64 v20, -v10
	v_exp_f32_e64 v21, -v11
	v_add_u32_e32 v22, 0xa0, v142
	v_mad_i64_i32 v[22:23], s[0:1], v22, s84, v[114:115]
	v_lshl_add_u64 v[22:23], v[22:23], 0, v[134:135]
	global_store_dwordx2 v[22:23], v[18:19], off
	v_pk_add_f32 v[18:19], v[20:21], 1.0 op_sel_hi:[1,0]
	v_exp_f32_e64 v12, -v12
	v_exp_f32_e64 v13, -v13
	v_pk_mul_f32 v[10:11], v[10:11], v[14:15]
	v_rcp_f32_e32 v14, v18
	v_rcp_f32_e32 v15, v19
	v_pk_add_f32 v[12:13], v[12:13], 1.0 op_sel_hi:[1,0]
	v_pk_mul_f32 v[2:3], v[6:7], v[2:3]
	v_rcp_f32_e32 v12, v12
	v_rcp_f32_e32 v13, v13
	v_pk_mul_f32 v[10:11], v[14:15], v[10:11]
	v_exp_f32_e64 v14, -v6
	v_exp_f32_e64 v15, -v7
	v_pk_mul_f32 v[12:13], v[12:13], v[16:17]
	v_exp_f32_e64 v16, -v8
	v_exp_f32_e64 v17, -v9
	v_pk_add_f32 v[14:15], v[14:15], 1.0 op_sel_hi:[1,0]
	v_med3_f32 v6, v10, s82, v141
	v_rcp_f32_e32 v14, v14
	v_rcp_f32_e32 v15, v15
	v_pk_add_f32 v[16:17], v[16:17], 1.0 op_sel_hi:[1,0]
	v_med3_f32 v7, v11, s82, v141
	v_rcp_f32_e32 v16, v16
	v_rcp_f32_e32 v17, v17
	v_pk_mul_f32 v[2:3], v[14:15], v[2:3]
	v_pk_mul_f32 v[4:5], v[8:9], v[4:5]
	v_med3_f32 v10, v2, s82, v141
	v_med3_f32 v11, v3, s82, v141
	v_mov_b32_e32 v2, 0
	v_mov_b32_e32 v3, 0
	v_cvt_pk_fp8_f32 v2, v6, v7
	v_cvt_pk_fp8_f32 v3, v10, v11
	v_pk_mul_f32 v[4:5], v[16:17], v[4:5]
	v_med3_f32 v121, v124, s82, v141
	v_med3_f32 v122, v125, s82, v141
	v_med3_f32 v8, v12, s82, v141
	v_med3_f32 v9, v13, s82, v141
	v_med3_f32 v4, v4, s82, v141
	v_med3_f32 v5, v5, s82, v141
	v_cvt_pk_fp8_f32 v118, v121, v122 op_sel:[0,0,1]
	v_cvt_pk_fp8_f32 v2, v8, v9 op_sel:[0,0,1]
	v_cvt_pk_fp8_f32 v3, v4, v5 op_sel:[0,0,1]
	v_add_u32_e32 v4, 0xb0, v142
	v_mad_i64_i32 v[120:121], s[0:1], v142, s84, v[114:115]
	v_mad_i64_i32 v[4:5], s[0:1], v4, s84, v[114:115]
	v_lshl_add_u64 v[120:121], v[120:121], 0, v[134:135]
	v_lshl_add_u64 v[4:5], v[4:5], 0, v[134:135]
	s_andn2_b64 vcc, exec, s[4:5]
	s_mov_b64 s[0:1], -1
	global_store_dwordx2 v[120:121], v[118:119], off
	global_store_dwordx2 v[4:5], v[2:3], off
	s_mov_b32 s98, 1
	s_cbranch_vccnz .LBB0_796
	s_andn2_b64 vcc, exec, s[6:7]
	v_mov_b64 v[122:123], 0
	v_mov_b64 v[124:125], 0
	v_mov_b64 v[114:115], 0
	v_mov_b64 v[116:117], 0
	v_mov_b64 v[106:107], 0
	v_mov_b64 v[108:109], 0
	v_mov_b64 v[98:99], 0
	v_mov_b64 v[100:101], 0
	v_mov_b64 v[90:91], 0
	v_mov_b64 v[92:93], 0
	v_mov_b64 v[82:83], 0
	v_mov_b64 v[84:85], 0
	v_mov_b64 v[74:75], 0
	v_mov_b64 v[76:77], 0
	v_mov_b64 v[66:67], 0
	v_mov_b64 v[68:69], 0
	v_mov_b64 v[126:127], 0
	v_mov_b64 v[128:129], 0
	v_mov_b64 v[118:119], 0
	v_mov_b64 v[120:121], 0
	v_mov_b64 v[110:111], 0
	v_mov_b64 v[112:113], 0
	v_mov_b64 v[102:103], 0
	v_mov_b64 v[104:105], 0
	v_mov_b64 v[94:95], 0
	v_mov_b64 v[96:97], 0
	v_mov_b64 v[86:87], 0
	v_mov_b64 v[88:89], 0
	v_mov_b64 v[78:79], 0
	v_mov_b64 v[80:81], 0
	v_mov_b64 v[70:71], 0
	v_mov_b64 v[72:73], 0
	v_mov_b64 v[58:59], 0
	v_mov_b64 v[60:61], 0
	v_mov_b64 v[50:51], 0
	v_mov_b64 v[52:53], 0
	v_mov_b64 v[42:43], 0
	v_mov_b64 v[44:45], 0
	v_mov_b64 v[34:35], 0
	v_mov_b64 v[36:37], 0
	v_mov_b64 v[26:27], 0
	v_mov_b64 v[28:29], 0
	v_mov_b64 v[18:19], 0
	v_mov_b64 v[20:21], 0
	v_mov_b64 v[10:11], 0
	v_mov_b64 v[12:13], 0
	v_mov_b64 v[6:7], 0
	v_mov_b64 v[8:9], 0
	v_mov_b64 v[62:63], 0
	v_mov_b64 v[64:65], 0
	v_mov_b64 v[54:55], 0
	v_mov_b64 v[56:57], 0
	v_mov_b64 v[46:47], 0
	v_mov_b64 v[48:49], 0
	v_mov_b64 v[38:39], 0
	v_mov_b64 v[40:41], 0
	v_mov_b64 v[30:31], 0
	v_mov_b64 v[32:33], 0
	v_mov_b64 v[22:23], 0
	v_mov_b64 v[24:25], 0
	v_mov_b64 v[14:15], 0
	v_mov_b64 v[16:17], 0
	v_mov_b64 v[2:3], 0
	v_mov_b64 v[4:5], 0
	s_cbranch_vccnz .LBB0_795
	s_barrier
	s_branch .LBB0_795

.LBB0_1418:
	v_lshrrev_b32_e32 v4, 1, v2
	v_and_b32_e32 v4, 24, v4
	v_and_b32_e32 v3, 15, v2
	v_lshlrev_b32_e32 v5, 1, v4
	v_lshlrev_b32_e32 v2, 2, v2
	s_sext_i32_i16 s63, s2
	v_lshl_or_b32 v137, s8, 6, v3
	v_lshl_or_b32 v3, v3, 6, v5
	s_lshl_b32 s2, s8, 13
	v_and_b32_e32 v2, 32, v2
	v_bitop3_b32 v5, v3, s2, v2 bitop3:0xde
	s_lshl_b32 s2, s9, 5
	s_and_b32 s2, s2, 0x60
	s_lshl_b32 s8, s2, 7
	v_bitop3_b32 v6, v3, s8, v2 bitop3:0xde
	s_add_u32 s8, s0, 0x80
	s_addc_u32 s9, s1, 0
	s_add_i32 s53, s27, 0x18000
	s_waitcnt vmcnt(2)
	s_barrier
	s_mov_b32 s10, m0
	s_mov_b32 m0, s53
	s_nop 4
	global_load_lds_dwordx4 v136, s[8:9]
	s_mov_b32 m0, s10
	s_add_u32 s8, s0, 0x20080
	s_addc_u32 s9, s1, 0
	s_add_i32 s54, s27, 0x1a000
	s_mov_b32 s10, m0
	s_mov_b32 m0, s54
	s_nop 4
	global_load_lds_dwordx4 v136, s[8:9]
	s_mov_b32 m0, s10
	s_add_u32 s8, s36, 0x80
	s_addc_u32 s9, s37, 0
	s_add_i32 s55, s27, 0x8000
	s_mov_b32 s10, m0
	s_mov_b32 m0, s55
	s_nop 4
	global_load_lds_dwordx4 v1, s[8:9]
	s_mov_b32 m0, s10
	s_add_u32 s8, s36, 0x20080
	s_addc_u32 s9, s37, 0
	s_add_i32 s56, s27, 0xa000
	s_mov_b32 s10, m0
	s_mov_b32 m0, s56
	s_nop 4
	global_load_lds_dwordx4 v1, s[8:9]
	s_mov_b32 m0, s10
	s_add_u32 s8, s0, 0x40080
	s_addc_u32 s9, s1, 0
	s_add_i32 s57, s27, 0x1c000
	s_mov_b32 s10, m0
	s_mov_b32 m0, s57
	s_nop 4
	global_load_lds_dwordx4 v136, s[8:9]
	s_mov_b32 m0, s10
	s_add_u32 s8, s0, 0x60080
	s_addc_u32 s9, s1, 0
	s_add_i32 s58, s27, 0x1e000
	s_mov_b32 s10, m0
	s_mov_b32 m0, s58
	s_nop 4
	global_load_lds_dwordx4 v136, s[8:9]
	s_mov_b32 m0, s10
	s_waitcnt vmcnt(6)
	s_add_i32 s59, s27, 0xc000
	s_cmpk_lt_u32 s3, 0x100
	v_mov_b64_e32 v[2:3], 0
	s_cselect_b64 s[8:9], -1, 0
	s_ashr_i32 s60, s72, 31
	v_or_b32_e32 v138, s2, v4
	v_mov_b64_e32 v[130:131], 0x16b0
	v_mov_b64_e32 v[132:133], 0x16af
	v_add_u32_e32 v139, 0, v6
	v_add_u32_e32 v140, 0, v5
	s_mov_b32 s61, 0xc3dc0000
	s_movk_i32 s62, 0xb00
	v_mov_b32_e32 v141, 0x43dc0000
	v_mov_b64_e32 v[4:5], v[2:3]
	v_mov_b64_e32 v[14:15], v[2:3]
	v_mov_b64_e32 v[16:17], v[2:3]
	v_mov_b64_e32 v[22:23], v[2:3]
	v_mov_b64_e32 v[24:25], v[2:3]
	v_mov_b64_e32 v[30:31], v[2:3]
	v_mov_b64_e32 v[32:33], v[2:3]
	v_mov_b64_e32 v[38:39], v[2:3]
	v_mov_b64_e32 v[40:41], v[2:3]
	v_mov_b64_e32 v[46:47], v[2:3]
	v_mov_b64_e32 v[48:49], v[2:3]
	v_mov_b64_e32 v[54:55], v[2:3]
	v_mov_b64_e32 v[56:57], v[2:3]
	v_mov_b64_e32 v[62:63], v[2:3]
	v_mov_b64_e32 v[64:65], v[2:3]
	v_mov_b64_e32 v[6:7], v[2:3]
	v_mov_b64_e32 v[8:9], v[2:3]
	v_mov_b64_e32 v[10:11], v[2:3]
	v_mov_b64_e32 v[12:13], v[2:3]
	v_mov_b64_e32 v[18:19], v[2:3]
	v_mov_b64_e32 v[20:21], v[2:3]
	v_mov_b64_e32 v[26:27], v[2:3]
	v_mov_b64_e32 v[28:29], v[2:3]
	v_mov_b64_e32 v[34:35], v[2:3]
	v_mov_b64_e32 v[36:37], v[2:3]
	v_mov_b64_e32 v[42:43], v[2:3]
	v_mov_b64_e32 v[44:45], v[2:3]
	v_mov_b64_e32 v[50:51], v[2:3]
	v_mov_b64_e32 v[52:53], v[2:3]
	v_mov_b64_e32 v[58:59], v[2:3]
	v_mov_b64_e32 v[60:61], v[2:3]
	v_mov_b64_e32 v[70:71], v[2:3]
	v_mov_b64_e32 v[72:73], v[2:3]
	v_mov_b64_e32 v[78:79], v[2:3]
	v_mov_b64_e32 v[80:81], v[2:3]
	v_mov_b64_e32 v[86:87], v[2:3]
	v_mov_b64_e32 v[88:89], v[2:3]
	v_mov_b64_e32 v[94:95], v[2:3]
	v_mov_b64_e32 v[96:97], v[2:3]
	v_mov_b64_e32 v[102:103], v[2:3]
	v_mov_b64_e32 v[104:105], v[2:3]
	v_mov_b64_e32 v[110:111], v[2:3]
	v_mov_b64_e32 v[112:113], v[2:3]
	v_mov_b64_e32 v[118:119], v[2:3]
	v_mov_b64_e32 v[120:121], v[2:3]
	v_mov_b64_e32 v[126:127], v[2:3]
	v_mov_b64_e32 v[128:129], v[2:3]
	v_mov_b64_e32 v[66:67], v[2:3]
	v_mov_b64_e32 v[68:69], v[2:3]
	v_mov_b64_e32 v[74:75], v[2:3]
	v_mov_b64_e32 v[76:77], v[2:3]
	v_mov_b64_e32 v[82:83], v[2:3]
	v_mov_b64_e32 v[84:85], v[2:3]
	v_mov_b64_e32 v[90:91], v[2:3]
	v_mov_b64_e32 v[92:93], v[2:3]
	v_mov_b64_e32 v[98:99], v[2:3]
	v_mov_b64_e32 v[100:101], v[2:3]
	v_mov_b64_e32 v[106:107], v[2:3]
	v_mov_b64_e32 v[108:109], v[2:3]
	v_mov_b64_e32 v[114:115], v[2:3]
	v_mov_b64_e32 v[116:117], v[2:3]
	v_mov_b64_e32 v[122:123], v[2:3]
	v_mov_b64_e32 v[124:125], v[2:3]
	s_barrier
	s_mov_b32 s98, 0
	s_branch .LBB0_1421

.LBB0_1424:
	v_add_u32_e32 v134, 0x10000, v139
	ds_read_b128 v[142:145], v134
	ds_read_b128 v[146:149], v134 offset:1024
	ds_read_b128 v[150:153], v134 offset:2048
	ds_read_b128 v[154:157], v134 offset:3072
	v_add_u32_e32 v134, 0x14000, v139
	ds_read_b128 v[158:161], v134
	ds_read_b128 v[162:165], v134 offset:1024
	ds_read_b128 v[166:169], v134 offset:2048
	ds_read_b128 v[170:173], v134 offset:3072
	s_add_u32 s0, s36, 0x100
	s_addc_u32 s1, s37, 0
	s_cmp_eq_u32 s66, 12
	s_cselect_b32 s34, s15, s0
	s_cselect_b32 s35, s14, s1
	s_cselect_b32 s40, s21, s64
	s_cselect_b32 s41, s11, s65
	s_add_u32 s38, s34, 0x80
	s_addc_u32 s39, s35, 0
	ds_read_b128 v[174:177], v140
	ds_read_b128 v[178:181], v140 offset:1024
	ds_read_b128 v[182:185], v140 offset:2048
	ds_read_b128 v[186:189], v140 offset:3072
	ds_read_b128 v[190:193], v140 offset:4096
	ds_read_b128 v[194:197], v140 offset:5120
	ds_read_b128 v[198:201], v140 offset:6144
	ds_read_b128 v[202:205], v140 offset:7168
	s_add_u32 s12, s36, 0x40080
	s_addc_u32 s13, s37, 0
	s_mov_b32 s67, m0
	s_mov_b32 m0, s59
	s_nop 4
	global_load_lds_dwordx4 v1, s[12:13]
	s_mov_b32 m0, s67
	s_add_u32 s12, s36, 0x60080
	s_addc_u32 s13, s37, 0
	s_add_i32 s36, s27, 0xe000
	s_mov_b32 s37, m0
	s_mov_b32 m0, s36
	s_nop 4
	global_load_lds_dwordx4 v1, s[12:13]
	s_mov_b32 m0, s37
	s_cmp_eq_u32 s66, -2
	s_cselect_b32 s99, s98, 0
	s_cmp_eq_u32 s99, 0
	s_cbranch_scc1 .Lw8_3_0
	s_waitcnt vmcnt(16)
	s_branch .Lwd_3_0

.Lwd_3_0:
	s_waitcnt lgkmcnt(0)
	s_barrier
	s_setprio 1
	s_waitcnt lgkmcnt(7)
	v_mfma_f32_16x16x32_bf16 v[122:125], v[142:145], v[174:177], v[122:125]
	v_mfma_f32_16x16x32_bf16 v[114:117], v[150:153], v[174:177], v[114:117]
	s_waitcnt lgkmcnt(5)
	v_mfma_f32_16x16x32_bf16 v[106:109], v[142:145], v[182:185], v[106:109]
	v_mfma_f32_16x16x32_bf16 v[98:101], v[150:153], v[182:185], v[98:101]
	s_waitcnt lgkmcnt(3)
	v_mfma_f32_16x16x32_bf16 v[90:93], v[142:145], v[190:193], v[90:93]
	v_mfma_f32_16x16x32_bf16 v[82:85], v[150:153], v[190:193], v[82:85]
	s_waitcnt lgkmcnt(1)
	v_mfma_f32_16x16x32_bf16 v[74:77], v[142:145], v[198:201], v[74:77]
	v_mfma_f32_16x16x32_bf16 v[66:69], v[150:153], v[198:201], v[66:69]
	v_mfma_f32_16x16x32_bf16 v[122:125], v[146:149], v[178:181], v[122:125]
	v_mfma_f32_16x16x32_bf16 v[114:117], v[154:157], v[178:181], v[114:117]
	v_mfma_f32_16x16x32_bf16 v[106:109], v[146:149], v[186:189], v[106:109]
	v_mfma_f32_16x16x32_bf16 v[98:101], v[154:157], v[186:189], v[98:101]
	v_mfma_f32_16x16x32_bf16 v[90:93], v[146:149], v[194:197], v[90:93]
	v_mfma_f32_16x16x32_bf16 v[82:85], v[154:157], v[194:197], v[82:85]
	s_waitcnt lgkmcnt(0)
	v_mfma_f32_16x16x32_bf16 v[74:77], v[146:149], v[202:205], v[74:77]
	v_mfma_f32_16x16x32_bf16 v[66:69], v[154:157], v[202:205], v[66:69]
	s_setprio 0
	s_setprio 1
	v_mfma_f32_16x16x32_bf16 v[126:129], v[158:161], v[174:177], v[126:129]
	v_mfma_f32_16x16x32_bf16 v[118:121], v[166:169], v[174:177], v[118:121]
	v_mfma_f32_16x16x32_bf16 v[110:113], v[158:161], v[182:185], v[110:113]
	v_mfma_f32_16x16x32_bf16 v[102:105], v[166:169], v[182:185], v[102:105]
	v_mfma_f32_16x16x32_bf16 v[94:97], v[158:161], v[190:193], v[94:97]
	v_mfma_f32_16x16x32_bf16 v[86:89], v[166:169], v[190:193], v[86:89]
	v_mfma_f32_16x16x32_bf16 v[78:81], v[158:161], v[198:201], v[78:81]
	v_mfma_f32_16x16x32_bf16 v[70:73], v[166:169], v[198:201], v[70:73]
	v_mfma_f32_16x16x32_bf16 v[126:129], v[162:165], v[178:181], v[126:129]
	v_mfma_f32_16x16x32_bf16 v[118:121], v[170:173], v[178:181], v[118:121]
	v_mfma_f32_16x16x32_bf16 v[110:113], v[162:165], v[186:189], v[110:113]
	v_mfma_f32_16x16x32_bf16 v[102:105], v[170:173], v[186:189], v[102:105]
	v_mfma_f32_16x16x32_bf16 v[94:97], v[162:165], v[194:197], v[94:97]
	v_mfma_f32_16x16x32_bf16 v[86:89], v[170:173], v[194:197], v[86:89]
	v_mfma_f32_16x16x32_bf16 v[78:81], v[162:165], v[202:205], v[78:81]
	v_mfma_f32_16x16x32_bf16 v[70:73], v[170:173], v[202:205], v[70:73]
	s_setprio 0
	s_barrier
	ds_read_b128 v[174:177], v140 offset:16384
	ds_read_b128 v[178:181], v140 offset:17408
	ds_read_b128 v[182:185], v140 offset:18432
	ds_read_b128 v[186:189], v140 offset:19456
	ds_read_b128 v[190:193], v140 offset:20480
	ds_read_b128 v[194:197], v140 offset:21504
	ds_read_b128 v[198:201], v140 offset:22528
	ds_read_b128 v[202:205], v140 offset:23552
	s_mov_b32 s12, m0
	s_mov_b32 m0, s46
	s_nop 4
	global_load_lds_dwordx4 v136, s[40:41]
	s_mov_b32 m0, s12
	s_add_u32 s12, s40, 0x20000
	s_addc_u32 s13, s41, 0
	s_mov_b32 s36, m0
	s_mov_b32 m0, s47
	s_nop 4
	global_load_lds_dwordx4 v136, s[12:13]
	s_mov_b32 m0, s36
	s_add_u32 s12, s40, 0x40000
	s_addc_u32 s13, s41, 0
	s_mov_b32 s36, m0
	s_mov_b32 m0, s48
	s_nop 4
	global_load_lds_dwordx4 v136, s[12:13]
	s_mov_b32 m0, s36
	s_add_u32 s12, s40, 0x60000
	s_addc_u32 s13, s41, 0
	s_mov_b32 s36, m0
	s_mov_b32 m0, s49
	s_nop 4
	global_load_lds_dwordx4 v136, s[12:13]
	s_mov_b32 m0, s36
	s_mov_b32 s12, m0
	s_mov_b32 m0, s27
	s_nop 4
	global_load_lds_dwordx4 v1, s[34:35]
	s_mov_b32 m0, s12
	s_add_u32 s12, s34, 0x20000
	s_addc_u32 s13, s35, 0
	s_mov_b32 s36, m0
	s_mov_b32 m0, s50
	s_nop 4
	global_load_lds_dwordx4 v1, s[12:13]
	s_mov_b32 m0, s36
	s_cmp_eq_u32 s66, -2
	s_cselect_b32 s99, s98, 0
	s_cmp_eq_u32 s99, 0
	s_cbranch_scc1 .Lw8_3_1
	s_waitcnt vmcnt(16)
	s_branch .Lwd_3_1

.Lwd_3_1:
	s_waitcnt lgkmcnt(0)
	s_barrier
	s_setprio 1
	s_waitcnt lgkmcnt(7)
	v_mfma_f32_16x16x32_bf16 v[58:61], v[142:145], v[174:177], v[58:61]
	v_mfma_f32_16x16x32_bf16 v[50:53], v[150:153], v[174:177], v[50:53]
	s_waitcnt lgkmcnt(5)
	v_mfma_f32_16x16x32_bf16 v[42:45], v[142:145], v[182:185], v[42:45]
	v_mfma_f32_16x16x32_bf16 v[34:37], v[150:153], v[182:185], v[34:37]
	s_waitcnt lgkmcnt(3)
	v_mfma_f32_16x16x32_bf16 v[26:29], v[142:145], v[190:193], v[26:29]
	v_mfma_f32_16x16x32_bf16 v[18:21], v[150:153], v[190:193], v[18:21]
	s_waitcnt lgkmcnt(1)
	v_mfma_f32_16x16x32_bf16 v[10:13], v[142:145], v[198:201], v[10:13]
	v_mfma_f32_16x16x32_bf16 v[6:9], v[150:153], v[198:201], v[6:9]
	v_mfma_f32_16x16x32_bf16 v[58:61], v[146:149], v[178:181], v[58:61]
	v_mfma_f32_16x16x32_bf16 v[50:53], v[154:157], v[178:181], v[50:53]
	v_mfma_f32_16x16x32_bf16 v[42:45], v[146:149], v[186:189], v[42:45]
	v_mfma_f32_16x16x32_bf16 v[34:37], v[154:157], v[186:189], v[34:37]
	v_mfma_f32_16x16x32_bf16 v[26:29], v[146:149], v[194:197], v[26:29]
	v_mfma_f32_16x16x32_bf16 v[18:21], v[154:157], v[194:197], v[18:21]
	s_waitcnt lgkmcnt(0)
	v_mfma_f32_16x16x32_bf16 v[10:13], v[146:149], v[202:205], v[10:13]
	v_mfma_f32_16x16x32_bf16 v[6:9], v[154:157], v[202:205], v[6:9]
	s_setprio 0
	s_setprio 1
	v_mfma_f32_16x16x32_bf16 v[62:65], v[158:161], v[174:177], v[62:65]
	v_mfma_f32_16x16x32_bf16 v[54:57], v[166:169], v[174:177], v[54:57]
	v_mfma_f32_16x16x32_bf16 v[46:49], v[158:161], v[182:185], v[46:49]
	v_mfma_f32_16x16x32_bf16 v[38:41], v[166:169], v[182:185], v[38:41]
	v_mfma_f32_16x16x32_bf16 v[30:33], v[158:161], v[190:193], v[30:33]
	v_mfma_f32_16x16x32_bf16 v[22:25], v[166:169], v[190:193], v[22:25]
	v_mfma_f32_16x16x32_bf16 v[14:17], v[158:161], v[198:201], v[14:17]
	v_mfma_f32_16x16x32_bf16 v[2:5], v[166:169], v[198:201], v[2:5]
	v_mfma_f32_16x16x32_bf16 v[62:65], v[162:165], v[178:181], v[62:65]
	v_mfma_f32_16x16x32_bf16 v[54:57], v[170:173], v[178:181], v[54:57]
	v_mfma_f32_16x16x32_bf16 v[46:49], v[162:165], v[186:189], v[46:49]
	v_mfma_f32_16x16x32_bf16 v[38:41], v[170:173], v[186:189], v[38:41]
	v_mfma_f32_16x16x32_bf16 v[30:33], v[162:165], v[194:197], v[30:33]
	v_mfma_f32_16x16x32_bf16 v[22:25], v[170:173], v[194:197], v[22:25]
	v_mfma_f32_16x16x32_bf16 v[14:17], v[162:165], v[202:205], v[14:17]
	v_mfma_f32_16x16x32_bf16 v[2:5], v[170:173], v[202:205], v[2:5]
	s_setprio 0
	s_barrier
	v_add_u32_e32 v134, 0x18000, v139
	ds_read_b128 v[142:145], v134
	ds_read_b128 v[146:149], v134 offset:1024
	ds_read_b128 v[150:153], v134 offset:2048
	ds_read_b128 v[154:157], v134 offset:3072
	v_add_u32_e32 v134, 0x1c000, v139
	ds_read_b128 v[158:161], v134
	ds_read_b128 v[162:165], v134 offset:1024
	ds_read_b128 v[166:169], v134 offset:2048
	ds_read_b128 v[170:173], v134 offset:3072
	ds_read_b128 v[174:177], v140 offset:32768
	ds_read_b128 v[178:181], v140 offset:33792
	ds_read_b128 v[182:185], v140 offset:34816
	ds_read_b128 v[186:189], v140 offset:35840
	ds_read_b128 v[190:193], v140 offset:36864
	ds_read_b128 v[194:197], v140 offset:37888
	ds_read_b128 v[198:201], v140 offset:38912
	ds_read_b128 v[202:205], v140 offset:39936
	s_add_u32 s12, s34, 0x40000
	s_addc_u32 s13, s35, 0
	s_mov_b32 s36, m0
	s_mov_b32 m0, s51
	s_nop 4
	global_load_lds_dwordx4 v1, s[12:13]
	s_mov_b32 m0, s36
	s_add_u32 s12, s34, 0x60000
	s_addc_u32 s13, s35, 0
	s_mov_b32 s36, m0
	s_mov_b32 m0, s52
	s_nop 4
	global_load_lds_dwordx4 v1, s[12:13]
	s_mov_b32 m0, s36
	s_waitcnt vmcnt(8)
	s_waitcnt lgkmcnt(0)
	s_barrier
	s_setprio 1
	s_waitcnt lgkmcnt(7)
	v_mfma_f32_16x16x32_bf16 v[122:125], v[142:145], v[174:177], v[122:125]
	v_mfma_f32_16x16x32_bf16 v[114:117], v[150:153], v[174:177], v[114:117]
	s_waitcnt lgkmcnt(5)
	v_mfma_f32_16x16x32_bf16 v[106:109], v[142:145], v[182:185], v[106:109]
	v_mfma_f32_16x16x32_bf16 v[98:101], v[150:153], v[182:185], v[98:101]
	s_waitcnt lgkmcnt(3)
	v_mfma_f32_16x16x32_bf16 v[90:93], v[142:145], v[190:193], v[90:93]
	v_mfma_f32_16x16x32_bf16 v[82:85], v[150:153], v[190:193], v[82:85]
	s_waitcnt lgkmcnt(1)
	v_mfma_f32_16x16x32_bf16 v[74:77], v[142:145], v[198:201], v[74:77]
	v_mfma_f32_16x16x32_bf16 v[66:69], v[150:153], v[198:201], v[66:69]
	v_mfma_f32_16x16x32_bf16 v[122:125], v[146:149], v[178:181], v[122:125]
	v_mfma_f32_16x16x32_bf16 v[114:117], v[154:157], v[178:181], v[114:117]
	v_mfma_f32_16x16x32_bf16 v[106:109], v[146:149], v[186:189], v[106:109]
	v_mfma_f32_16x16x32_bf16 v[98:101], v[154:157], v[186:189], v[98:101]
	v_mfma_f32_16x16x32_bf16 v[90:93], v[146:149], v[194:197], v[90:93]
	v_mfma_f32_16x16x32_bf16 v[82:85], v[154:157], v[194:197], v[82:85]
	s_waitcnt lgkmcnt(0)
	v_mfma_f32_16x16x32_bf16 v[74:77], v[146:149], v[202:205], v[74:77]
	v_mfma_f32_16x16x32_bf16 v[66:69], v[154:157], v[202:205], v[66:69]
	s_setprio 0
	s_setprio 1
	v_mfma_f32_16x16x32_bf16 v[126:129], v[158:161], v[174:177], v[126:129]
	v_mfma_f32_16x16x32_bf16 v[118:121], v[166:169], v[174:177], v[118:121]
	v_mfma_f32_16x16x32_bf16 v[110:113], v[158:161], v[182:185], v[110:113]
	v_mfma_f32_16x16x32_bf16 v[102:105], v[166:169], v[182:185], v[102:105]
	v_mfma_f32_16x16x32_bf16 v[94:97], v[158:161], v[190:193], v[94:97]
	v_mfma_f32_16x16x32_bf16 v[86:89], v[166:169], v[190:193], v[86:89]
	v_mfma_f32_16x16x32_bf16 v[78:81], v[158:161], v[198:201], v[78:81]
	v_mfma_f32_16x16x32_bf16 v[70:73], v[166:169], v[198:201], v[70:73]
	v_mfma_f32_16x16x32_bf16 v[126:129], v[162:165], v[178:181], v[126:129]
	v_mfma_f32_16x16x32_bf16 v[118:121], v[170:173], v[178:181], v[118:121]
	v_mfma_f32_16x16x32_bf16 v[110:113], v[162:165], v[186:189], v[110:113]
	v_mfma_f32_16x16x32_bf16 v[102:105], v[170:173], v[186:189], v[102:105]
	v_mfma_f32_16x16x32_bf16 v[94:97], v[162:165], v[194:197], v[94:97]
	v_mfma_f32_16x16x32_bf16 v[86:89], v[170:173], v[194:197], v[86:89]
	v_mfma_f32_16x16x32_bf16 v[78:81], v[162:165], v[202:205], v[78:81]
	v_mfma_f32_16x16x32_bf16 v[70:73], v[170:173], v[202:205], v[70:73]
	s_setprio 0
	s_barrier
	s_add_u32 s12, s40, 0x80
	s_addc_u32 s13, s41, 0
	ds_read_b128 v[174:177], v140 offset:49152
	ds_read_b128 v[178:181], v140 offset:50176
	ds_read_b128 v[182:185], v140 offset:51200
	ds_read_b128 v[186:189], v140 offset:52224
	ds_read_b128 v[190:193], v140 offset:53248
	ds_read_b128 v[194:197], v140 offset:54272
	ds_read_b128 v[198:201], v140 offset:55296
	ds_read_b128 v[202:205], v140 offset:56320
	s_mov_b32 s36, m0
	s_mov_b32 m0, s53
	s_nop 4
	global_load_lds_dwordx4 v136, s[12:13]
	s_mov_b32 m0, s36
	s_add_u32 s12, s40, 0x20080
	s_addc_u32 s13, s41, 0
	s_mov_b32 s36, m0
	s_mov_b32 m0, s54
	s_nop 4
	global_load_lds_dwordx4 v136, s[12:13]
	s_mov_b32 m0, s36
	s_add_u32 s12, s40, 0x40080
	s_addc_u32 s13, s41, 0
	s_mov_b32 s36, m0
	s_mov_b32 m0, s57
	s_nop 4
	global_load_lds_dwordx4 v136, s[12:13]
	s_mov_b32 m0, s36
	s_add_u32 s12, s40, 0x60080
	s_addc_u32 s13, s41, 0
	s_mov_b32 s36, m0
	s_mov_b32 m0, s58
	s_nop 4
	global_load_lds_dwordx4 v136, s[12:13]
	s_mov_b32 m0, s36
	s_mov_b32 s12, m0
	s_mov_b32 m0, s55
	s_nop 4
	global_load_lds_dwordx4 v1, s[38:39]
	s_mov_b32 m0, s12
	s_add_u32 s12, s34, 0x20080
	s_addc_u32 s13, s35, 0
	s_mov_b32 s34, m0
	s_mov_b32 m0, s56
	s_nop 4
	global_load_lds_dwordx4 v1, s[12:13]
	s_mov_b32 m0, s34
	s_waitcnt vmcnt(8)
	s_waitcnt lgkmcnt(0)
	s_barrier
	s_setprio 1
	s_waitcnt lgkmcnt(7)
	v_mfma_f32_16x16x32_bf16 v[58:61], v[142:145], v[174:177], v[58:61]
	v_mfma_f32_16x16x32_bf16 v[50:53], v[150:153], v[174:177], v[50:53]
	s_waitcnt lgkmcnt(5)
	v_mfma_f32_16x16x32_bf16 v[42:45], v[142:145], v[182:185], v[42:45]
	v_mfma_f32_16x16x32_bf16 v[34:37], v[150:153], v[182:185], v[34:37]
	s_waitcnt lgkmcnt(3)
	v_mfma_f32_16x16x32_bf16 v[26:29], v[142:145], v[190:193], v[26:29]
	v_mfma_f32_16x16x32_bf16 v[18:21], v[150:153], v[190:193], v[18:21]
	s_waitcnt lgkmcnt(1)
	v_mfma_f32_16x16x32_bf16 v[10:13], v[142:145], v[198:201], v[10:13]
	v_mfma_f32_16x16x32_bf16 v[6:9], v[150:153], v[198:201], v[6:9]
	v_mfma_f32_16x16x32_bf16 v[58:61], v[146:149], v[178:181], v[58:61]
	v_mfma_f32_16x16x32_bf16 v[50:53], v[154:157], v[178:181], v[50:53]
	v_mfma_f32_16x16x32_bf16 v[42:45], v[146:149], v[186:189], v[42:45]
	v_mfma_f32_16x16x32_bf16 v[34:37], v[154:157], v[186:189], v[34:37]
	v_mfma_f32_16x16x32_bf16 v[26:29], v[146:149], v[194:197], v[26:29]
	v_mfma_f32_16x16x32_bf16 v[18:21], v[154:157], v[194:197], v[18:21]
	s_waitcnt lgkmcnt(0)
	v_mfma_f32_16x16x32_bf16 v[10:13], v[146:149], v[202:205], v[10:13]
	v_mfma_f32_16x16x32_bf16 v[6:9], v[154:157], v[202:205], v[6:9]
	s_setprio 0
	s_setprio 1
	v_mfma_f32_16x16x32_bf16 v[62:65], v[158:161], v[174:177], v[62:65]
	v_mfma_f32_16x16x32_bf16 v[54:57], v[166:169], v[174:177], v[54:57]
	v_mfma_f32_16x16x32_bf16 v[46:49], v[158:161], v[182:185], v[46:49]
	v_mfma_f32_16x16x32_bf16 v[38:41], v[166:169], v[182:185], v[38:41]
	v_mfma_f32_16x16x32_bf16 v[30:33], v[158:161], v[190:193], v[30:33]
	v_mfma_f32_16x16x32_bf16 v[22:25], v[166:169], v[190:193], v[22:25]
	v_mfma_f32_16x16x32_bf16 v[14:17], v[158:161], v[198:201], v[14:17]
	v_mfma_f32_16x16x32_bf16 v[2:5], v[166:169], v[198:201], v[2:5]
	v_mfma_f32_16x16x32_bf16 v[62:65], v[162:165], v[178:181], v[62:65]
	v_mfma_f32_16x16x32_bf16 v[54:57], v[170:173], v[178:181], v[54:57]
	v_mfma_f32_16x16x32_bf16 v[46:49], v[162:165], v[186:189], v[46:49]
	v_mfma_f32_16x16x32_bf16 v[38:41], v[170:173], v[186:189], v[38:41]
	v_mfma_f32_16x16x32_bf16 v[30:33], v[162:165], v[194:197], v[30:33]
	v_mfma_f32_16x16x32_bf16 v[22:25], v[170:173], v[194:197], v[22:25]
	v_mfma_f32_16x16x32_bf16 v[14:17], v[162:165], v[202:205], v[14:17]
	v_mfma_f32_16x16x32_bf16 v[2:5], v[170:173], v[202:205], v[2:5]
	s_setprio 0
	s_barrier
	s_add_i32 s66, s66, 2
	s_add_u32 s64, s64, 0x100
	s_addc_u32 s65, s65, 0
	s_cmp_gt_u32 s66, 13
	s_mov_b64 s[36:37], s[0:1]
	s_cbranch_scc0 .LBB0_1424
	s_and_b64 vcc, exec, s[8:9]
	s_cbranch_vccz .LBB0_1427
	s_barrier
.LBB0_1427:
	v_exp_f32_e64 v144, -v122
	v_exp_f32_e64 v145, -v123
	v_pk_mul_f32 v[128:129], v[124:125], v[128:129]
	v_exp_f32_e64 v124, -v124
	v_exp_f32_e64 v125, -v125
	v_pk_add_f32 v[144:145], v[144:145], 1.0 op_sel_hi:[1,0]
	v_pk_mul_f32 v[122:123], v[122:123], v[126:127]
	v_rcp_f32_e32 v126, v144
	v_rcp_f32_e32 v127, v145
	v_pk_add_f32 v[124:125], v[124:125], 1.0 op_sel_hi:[1,0]
	v_pk_mul_f32 v[112:113], v[108:109], v[112:113]
	v_rcp_f32_e32 v124, v124
	v_rcp_f32_e32 v125, v125
	v_pk_mul_f32 v[122:123], v[126:127], v[122:123]
	v_exp_f32_e64 v126, -v114
	v_exp_f32_e64 v127, -v115
	v_pk_mul_f32 v[124:125], v[124:125], v[128:129]
	v_exp_f32_e64 v128, -v116
	v_exp_f32_e64 v129, -v117
	v_pk_add_f32 v[126:127], v[126:127], 1.0 op_sel_hi:[1,0]
	v_pk_mul_f32 v[114:115], v[114:115], v[118:119]
	v_rcp_f32_e32 v126, v126
	v_rcp_f32_e32 v127, v127
	v_pk_add_f32 v[128:129], v[128:129], 1.0 op_sel_hi:[1,0]
	v_pk_mul_f32 v[116:117], v[116:117], v[120:121]
	v_rcp_f32_e32 v128, v128
	v_rcp_f32_e32 v129, v129
	v_pk_mul_f32 v[114:115], v[126:127], v[114:115]
	v_med3_f32 v119, v122, s61, v141
	v_med3_f32 v120, v123, s61, v141
	v_mov_b32_e32 v118, 0
	v_pk_mul_f32 v[116:117], v[128:129], v[116:117]
	v_med3_f32 v114, v114, s61, v141
	v_med3_f32 v115, v115, s61, v141
	v_cvt_pk_fp8_f32 v118, v119, v120
	v_mov_b32_e32 v119, 0
	v_cvt_pk_fp8_f32 v119, v114, v115
	v_med3_f32 v114, v116, s61, v141
	v_med3_f32 v115, v117, s61, v141
	v_exp_f32_e64 v116, -v106
	v_exp_f32_e64 v117, -v107
	v_exp_f32_e64 v108, -v108
	v_exp_f32_e64 v109, -v109
	v_pk_mul_f32 v[106:107], v[106:107], v[110:111]
	v_pk_add_f32 v[116:117], v[116:117], 1.0 op_sel_hi:[1,0]
	v_lshl_add_u32 v142, s26, 8, v137
	v_rcp_f32_e32 v110, v116
	v_rcp_f32_e32 v111, v117
	v_pk_add_f32 v[108:109], v[108:109], 1.0 op_sel_hi:[1,0]
	v_lshl_or_b32 v134, s63, 7, v138
	v_rcp_f32_e32 v108, v108
	v_rcp_f32_e32 v109, v109
	v_pk_mul_f32 v[106:107], v[110:111], v[106:107]
	v_exp_f32_e64 v110, -v98
	v_exp_f32_e64 v111, -v99
	v_pk_mul_f32 v[108:109], v[108:109], v[112:113]
	v_exp_f32_e64 v112, -v100
	v_exp_f32_e64 v113, -v101
	v_pk_add_f32 v[110:111], v[110:111], 1.0 op_sel_hi:[1,0]
	v_pk_mul_f32 v[98:99], v[98:99], v[102:103]
	v_rcp_f32_e32 v110, v110
	v_rcp_f32_e32 v111, v111
	v_pk_add_f32 v[112:113], v[112:113], 1.0 op_sel_hi:[1,0]
	v_med3_f32 v102, v106, s61, v141
	v_rcp_f32_e32 v112, v112
	v_rcp_f32_e32 v113, v113
	v_pk_mul_f32 v[98:99], v[110:111], v[98:99]
	v_med3_f32 v103, v107, s61, v141
	v_med3_f32 v106, v98, s61, v141
	v_med3_f32 v107, v99, s61, v141
	v_mov_b32_e32 v98, 0
	v_mov_b32_e32 v99, 0
	v_cvt_pk_fp8_f32 v98, v102, v103
	v_cvt_pk_fp8_f32 v99, v106, v107
	v_pk_mul_f32 v[100:101], v[100:101], v[104:105]
	v_med3_f32 v104, v108, s61, v141
	v_pk_mul_f32 v[100:101], v[112:113], v[100:101]
	v_med3_f32 v105, v109, s61, v141
	v_med3_f32 v100, v100, s61, v141
	v_med3_f32 v101, v101, s61, v141
	v_cvt_pk_fp8_f32 v98, v104, v105 op_sel:[0,0,1]
	v_cvt_pk_fp8_f32 v99, v100, v101 op_sel:[0,0,1]
	v_exp_f32_e64 v100, -v90
	v_exp_f32_e64 v101, -v91
	v_cvt_pk_fp8_f32 v119, v114, v115 op_sel:[0,0,1]
	v_mov_b64_e32 v[114:115], s[18:19]
	v_or_b32_e32 v102, 16, v142
	v_ashrrev_i32_e32 v135, 31, v134
	v_mad_i64_i32 v[102:103], s[0:1], v102, s62, v[114:115]
	v_lshl_add_u64 v[102:103], v[102:103], 0, v[134:135]
	global_store_dwordx2 v[102:103], v[98:99], off
	v_pk_add_f32 v[98:99], v[100:101], 1.0 op_sel_hi:[1,0]
	v_pk_mul_f32 v[96:97], v[92:93], v[96:97]
	v_exp_f32_e64 v92, -v92
	v_exp_f32_e64 v93, -v93
	v_pk_mul_f32 v[90:91], v[90:91], v[94:95]
	v_rcp_f32_e32 v94, v98
	v_rcp_f32_e32 v95, v99
	v_pk_add_f32 v[92:93], v[92:93], 1.0 op_sel_hi:[1,0]
	v_pk_mul_f32 v[80:81], v[76:77], v[80:81]
	v_rcp_f32_e32 v92, v92
	v_rcp_f32_e32 v93, v93
	v_pk_mul_f32 v[90:91], v[94:95], v[90:91]
	v_exp_f32_e64 v94, -v82
	v_exp_f32_e64 v95, -v83
	v_pk_mul_f32 v[92:93], v[92:93], v[96:97]
	v_exp_f32_e64 v96, -v84
	v_exp_f32_e64 v97, -v85
	v_pk_add_f32 v[94:95], v[94:95], 1.0 op_sel_hi:[1,0]
	v_pk_mul_f32 v[82:83], v[82:83], v[86:87]
	v_rcp_f32_e32 v94, v94
	v_rcp_f32_e32 v95, v95
	v_pk_add_f32 v[96:97], v[96:97], 1.0 op_sel_hi:[1,0]
	v_med3_f32 v86, v90, s61, v141
	v_rcp_f32_e32 v96, v96
	v_rcp_f32_e32 v97, v97
	v_pk_mul_f32 v[82:83], v[94:95], v[82:83]
	v_med3_f32 v87, v91, s61, v141
	v_med3_f32 v90, v82, s61, v141
	v_med3_f32 v91, v83, s61, v141
	v_mov_b32_e32 v82, 0
	v_mov_b32_e32 v83, 0
	v_cvt_pk_fp8_f32 v82, v86, v87
	v_cvt_pk_fp8_f32 v83, v90, v91
	v_pk_mul_f32 v[84:85], v[84:85], v[88:89]
	v_med3_f32 v88, v92, s61, v141
	v_pk_mul_f32 v[84:85], v[96:97], v[84:85]
	v_med3_f32 v89, v93, s61, v141
	v_med3_f32 v84, v84, s61, v141
	v_med3_f32 v85, v85, s61, v141
	v_cvt_pk_fp8_f32 v82, v88, v89 op_sel:[0,0,1]
	v_cvt_pk_fp8_f32 v83, v84, v85 op_sel:[0,0,1]
	v_exp_f32_e64 v84, -v74
	v_exp_f32_e64 v85, -v75
	v_or_b32_e32 v86, 32, v142
	v_mad_i64_i32 v[86:87], s[0:1], v86, s62, v[114:115]
	v_lshl_add_u64 v[86:87], v[86:87], 0, v[134:135]
	global_store_dwordx2 v[86:87], v[82:83], off
	v_pk_add_f32 v[82:83], v[84:85], 1.0 op_sel_hi:[1,0]
	v_exp_f32_e64 v76, -v76
	v_exp_f32_e64 v77, -v77
	v_pk_mul_f32 v[74:75], v[74:75], v[78:79]
	v_rcp_f32_e32 v78, v82
	v_rcp_f32_e32 v79, v83
	v_pk_add_f32 v[76:77], v[76:77], 1.0 op_sel_hi:[1,0]
	v_pk_mul_f32 v[64:65], v[60:61], v[64:65]
	v_rcp_f32_e32 v76, v76
	v_rcp_f32_e32 v77, v77
	v_pk_mul_f32 v[74:75], v[78:79], v[74:75]
	v_exp_f32_e64 v78, -v66
	v_exp_f32_e64 v79, -v67
	v_pk_mul_f32 v[76:77], v[76:77], v[80:81]
	v_exp_f32_e64 v80, -v68
	v_exp_f32_e64 v81, -v69
	v_pk_add_f32 v[78:79], v[78:79], 1.0 op_sel_hi:[1,0]
	v_pk_mul_f32 v[66:67], v[66:67], v[70:71]
	v_rcp_f32_e32 v78, v78
	v_rcp_f32_e32 v79, v79
	v_pk_add_f32 v[80:81], v[80:81], 1.0 op_sel_hi:[1,0]
	v_med3_f32 v70, v74, s61, v141
	v_rcp_f32_e32 v80, v80
	v_rcp_f32_e32 v81, v81
	v_pk_mul_f32 v[66:67], v[78:79], v[66:67]
	v_med3_f32 v71, v75, s61, v141
	v_med3_f32 v74, v66, s61, v141
	v_med3_f32 v75, v67, s61, v141
	v_mov_b32_e32 v66, 0
	v_mov_b32_e32 v67, 0
	v_cvt_pk_fp8_f32 v66, v70, v71
	v_cvt_pk_fp8_f32 v67, v74, v75
	v_pk_mul_f32 v[68:69], v[68:69], v[72:73]
	v_med3_f32 v72, v76, s61, v141
	v_pk_mul_f32 v[68:69], v[80:81], v[68:69]
	v_med3_f32 v73, v77, s61, v141
	v_med3_f32 v68, v68, s61, v141
	v_med3_f32 v69, v69, s61, v141
	v_cvt_pk_fp8_f32 v66, v72, v73 op_sel:[0,0,1]
	v_cvt_pk_fp8_f32 v67, v68, v69 op_sel:[0,0,1]
	v_exp_f32_e64 v70, -v58
	v_exp_f32_e64 v71, -v59
	v_or_b32_e32 v68, 48, v142
	v_mad_i64_i32 v[68:69], s[0:1], v68, s62, v[114:115]
	v_lshl_add_u64 v[68:69], v[68:69], 0, v[134:135]
	global_store_dwordx2 v[68:69], v[66:67], off
	v_pk_add_f32 v[66:67], v[70:71], 1.0 op_sel_hi:[1,0]
	v_exp_f32_e64 v60, -v60
	v_exp_f32_e64 v61, -v61
	v_pk_mul_f32 v[58:59], v[58:59], v[62:63]
	v_rcp_f32_e32 v62, v66
	v_rcp_f32_e32 v63, v67
	v_pk_add_f32 v[60:61], v[60:61], 1.0 op_sel_hi:[1,0]
	v_add_u32_e32 v68, 0x80, v142
	v_rcp_f32_e32 v60, v60
	v_rcp_f32_e32 v61, v61
	v_pk_mul_f32 v[58:59], v[62:63], v[58:59]
	v_exp_f32_e64 v62, -v50
	v_exp_f32_e64 v63, -v51
	v_pk_mul_f32 v[60:61], v[60:61], v[64:65]
	v_exp_f32_e64 v64, -v52
	v_exp_f32_e64 v65, -v53
	v_pk_add_f32 v[62:63], v[62:63], 1.0 op_sel_hi:[1,0]
	v_pk_mul_f32 v[50:51], v[50:51], v[54:55]
	v_rcp_f32_e32 v62, v62
	v_rcp_f32_e32 v63, v63
	v_pk_add_f32 v[64:65], v[64:65], 1.0 op_sel_hi:[1,0]
	v_med3_f32 v54, v58, s61, v141
	v_rcp_f32_e32 v64, v64
	v_rcp_f32_e32 v65, v65
	v_pk_mul_f32 v[50:51], v[62:63], v[50:51]
	v_med3_f32 v55, v59, s61, v141
	v_med3_f32 v58, v50, s61, v141
	v_med3_f32 v59, v51, s61, v141
	v_mov_b32_e32 v50, 0
	v_mov_b32_e32 v51, 0
	v_cvt_pk_fp8_f32 v50, v54, v55
	v_cvt_pk_fp8_f32 v51, v58, v59
	v_pk_mul_f32 v[52:53], v[52:53], v[56:57]
	v_med3_f32 v56, v60, s61, v141
	v_pk_mul_f32 v[52:53], v[64:65], v[52:53]
	v_med3_f32 v57, v61, s61, v141
	v_med3_f32 v52, v52, s61, v141
	v_med3_f32 v53, v53, s61, v141
	v_cvt_pk_fp8_f32 v50, v56, v57 op_sel:[0,0,1]
	v_cvt_pk_fp8_f32 v51, v52, v53 op_sel:[0,0,1]
	v_exp_f32_e64 v52, -v42
	v_exp_f32_e64 v53, -v43
	v_mad_i64_i32 v[54:55], s[0:1], v68, s62, v[114:115]
	v_lshl_add_u64 v[54:55], v[54:55], 0, v[134:135]
	global_store_dwordx2 v[54:55], v[50:51], off
	v_pk_add_f32 v[50:51], v[52:53], 1.0 op_sel_hi:[1,0]
	v_pk_mul_f32 v[48:49], v[44:45], v[48:49]
	v_exp_f32_e64 v44, -v44
	v_exp_f32_e64 v45, -v45
	v_pk_mul_f32 v[42:43], v[42:43], v[46:47]
	v_rcp_f32_e32 v46, v50
	v_rcp_f32_e32 v47, v51
	v_pk_add_f32 v[44:45], v[44:45], 1.0 op_sel_hi:[1,0]
	v_pk_mul_f32 v[32:33], v[28:29], v[32:33]
	v_rcp_f32_e32 v44, v44
	v_rcp_f32_e32 v45, v45
	v_pk_mul_f32 v[42:43], v[46:47], v[42:43]
	v_exp_f32_e64 v46, -v34
	v_exp_f32_e64 v47, -v35
	v_pk_mul_f32 v[44:45], v[44:45], v[48:49]
	v_exp_f32_e64 v48, -v36
	v_exp_f32_e64 v49, -v37
	v_pk_add_f32 v[46:47], v[46:47], 1.0 op_sel_hi:[1,0]
	v_pk_mul_f32 v[34:35], v[34:35], v[38:39]
	v_rcp_f32_e32 v46, v46
	v_rcp_f32_e32 v47, v47
	v_pk_add_f32 v[48:49], v[48:49], 1.0 op_sel_hi:[1,0]
	v_med3_f32 v38, v42, s61, v141
	v_rcp_f32_e32 v48, v48
	v_rcp_f32_e32 v49, v49
	v_pk_mul_f32 v[34:35], v[46:47], v[34:35]
	v_med3_f32 v39, v43, s61, v141
	v_med3_f32 v42, v34, s61, v141
	v_med3_f32 v43, v35, s61, v141
	v_mov_b32_e32 v34, 0
	v_mov_b32_e32 v35, 0
	v_cvt_pk_fp8_f32 v34, v38, v39
	v_cvt_pk_fp8_f32 v35, v42, v43
	v_pk_mul_f32 v[36:37], v[36:37], v[40:41]
	v_med3_f32 v40, v44, s61, v141
	v_pk_mul_f32 v[36:37], v[48:49], v[36:37]
	v_med3_f32 v41, v45, s61, v141
	v_med3_f32 v36, v36, s61, v141
	v_med3_f32 v37, v37, s61, v141
	v_cvt_pk_fp8_f32 v34, v40, v41 op_sel:[0,0,1]
	v_cvt_pk_fp8_f32 v35, v36, v37 op_sel:[0,0,1]
	v_exp_f32_e64 v36, -v26
	v_exp_f32_e64 v37, -v27
	v_add_u32_e32 v38, 0x90, v142
	v_mad_i64_i32 v[38:39], s[0:1], v38, s62, v[114:115]
	v_lshl_add_u64 v[38:39], v[38:39], 0, v[134:135]
	global_store_dwordx2 v[38:39], v[34:35], off
	v_pk_add_f32 v[34:35], v[36:37], 1.0 op_sel_hi:[1,0]
	v_exp_f32_e64 v28, -v28
	v_exp_f32_e64 v29, -v29
	v_pk_mul_f32 v[26:27], v[26:27], v[30:31]
	v_rcp_f32_e32 v30, v34
	v_rcp_f32_e32 v31, v35
	v_pk_add_f32 v[28:29], v[28:29], 1.0 op_sel_hi:[1,0]
	v_pk_mul_f32 v[16:17], v[12:13], v[16:17]
	v_rcp_f32_e32 v28, v28
	v_rcp_f32_e32 v29, v29
	v_pk_mul_f32 v[26:27], v[30:31], v[26:27]
	v_exp_f32_e64 v30, -v18
	v_exp_f32_e64 v31, -v19
	v_pk_mul_f32 v[28:29], v[28:29], v[32:33]
	v_exp_f32_e64 v32, -v20
	v_exp_f32_e64 v33, -v21
	v_pk_add_f32 v[30:31], v[30:31], 1.0 op_sel_hi:[1,0]
	v_pk_mul_f32 v[18:19], v[18:19], v[22:23]
	v_rcp_f32_e32 v30, v30
	v_rcp_f32_e32 v31, v31
	v_pk_add_f32 v[32:33], v[32:33], 1.0 op_sel_hi:[1,0]
	v_med3_f32 v22, v26, s61, v141
	v_rcp_f32_e32 v32, v32
	v_rcp_f32_e32 v33, v33
	v_pk_mul_f32 v[18:19], v[30:31], v[18:19]
	v_med3_f32 v23, v27, s61, v141
	v_med3_f32 v26, v18, s61, v141
	v_med3_f32 v27, v19, s61, v141
	v_mov_b32_e32 v18, 0
	v_mov_b32_e32 v19, 0
	v_cvt_pk_fp8_f32 v18, v22, v23
	v_cvt_pk_fp8_f32 v19, v26, v27
	v_pk_mul_f32 v[20:21], v[20:21], v[24:25]
	v_med3_f32 v24, v28, s61, v141
	v_pk_mul_f32 v[20:21], v[32:33], v[20:21]
	v_med3_f32 v25, v29, s61, v141
	v_med3_f32 v20, v20, s61, v141
	v_med3_f32 v21, v21, s61, v141
	v_cvt_pk_fp8_f32 v18, v24, v25 op_sel:[0,0,1]
	v_cvt_pk_fp8_f32 v19, v20, v21 op_sel:[0,0,1]
	v_exp_f32_e64 v20, -v10
	v_exp_f32_e64 v21, -v11
	v_add_u32_e32 v22, 0xa0, v142
	v_mad_i64_i32 v[22:23], s[0:1], v22, s62, v[114:115]
	v_lshl_add_u64 v[22:23], v[22:23], 0, v[134:135]
	global_store_dwordx2 v[22:23], v[18:19], off
	v_pk_add_f32 v[18:19], v[20:21], 1.0 op_sel_hi:[1,0]
	v_exp_f32_e64 v12, -v12
	v_exp_f32_e64 v13, -v13
	v_pk_mul_f32 v[10:11], v[10:11], v[14:15]
	v_rcp_f32_e32 v14, v18
	v_rcp_f32_e32 v15, v19
	v_pk_add_f32 v[12:13], v[12:13], 1.0 op_sel_hi:[1,0]
	v_pk_mul_f32 v[2:3], v[6:7], v[2:3]
	v_rcp_f32_e32 v12, v12
	v_rcp_f32_e32 v13, v13
	v_pk_mul_f32 v[10:11], v[14:15], v[10:11]
	v_exp_f32_e64 v14, -v6
	v_exp_f32_e64 v15, -v7
	v_pk_mul_f32 v[12:13], v[12:13], v[16:17]
	v_exp_f32_e64 v16, -v8
	v_exp_f32_e64 v17, -v9
	v_pk_add_f32 v[14:15], v[14:15], 1.0 op_sel_hi:[1,0]
	v_med3_f32 v6, v10, s61, v141
	v_rcp_f32_e32 v14, v14
	v_rcp_f32_e32 v15, v15
	v_pk_add_f32 v[16:17], v[16:17], 1.0 op_sel_hi:[1,0]
	v_med3_f32 v7, v11, s61, v141
	v_rcp_f32_e32 v16, v16
	v_rcp_f32_e32 v17, v17
	v_pk_mul_f32 v[2:3], v[14:15], v[2:3]
	v_pk_mul_f32 v[4:5], v[8:9], v[4:5]
	v_med3_f32 v10, v2, s61, v141
	v_med3_f32 v11, v3, s61, v141
	v_mov_b32_e32 v2, 0
	v_mov_b32_e32 v3, 0
	v_cvt_pk_fp8_f32 v2, v6, v7
	v_cvt_pk_fp8_f32 v3, v10, v11
	v_pk_mul_f32 v[4:5], v[16:17], v[4:5]
	v_med3_f32 v121, v124, s61, v141
	v_med3_f32 v122, v125, s61, v141
	v_med3_f32 v8, v12, s61, v141
	v_med3_f32 v9, v13, s61, v141
	v_med3_f32 v4, v4, s61, v141
	v_med3_f32 v5, v5, s61, v141
	v_cvt_pk_fp8_f32 v118, v121, v122 op_sel:[0,0,1]
	v_cvt_pk_fp8_f32 v2, v8, v9 op_sel:[0,0,1]
	v_cvt_pk_fp8_f32 v3, v4, v5 op_sel:[0,0,1]
	v_add_u32_e32 v4, 0xb0, v142
	v_mad_i64_i32 v[120:121], s[0:1], v142, s62, v[114:115]
	v_mad_i64_i32 v[4:5], s[0:1], v4, s62, v[114:115]
	v_lshl_add_u64 v[120:121], v[120:121], 0, v[134:135]
	v_lshl_add_u64 v[4:5], v[4:5], 0, v[134:135]
	s_andn2_b64 vcc, exec, s[2:3]
	s_mov_b64 s[0:1], -1
	global_store_dwordx2 v[120:121], v[118:119], off
	global_store_dwordx2 v[4:5], v[2:3], off
	s_mov_b32 s98, 1
	s_cbranch_vccnz .LBB0_1420
	s_andn2_b64 vcc, exec, s[6:7]
	v_mov_b64 v[122:123], 0
	v_mov_b64 v[124:125], 0
	v_mov_b64 v[114:115], 0
	v_mov_b64 v[116:117], 0
	v_mov_b64 v[106:107], 0
	v_mov_b64 v[108:109], 0
	v_mov_b64 v[98:99], 0
	v_mov_b64 v[100:101], 0
	v_mov_b64 v[90:91], 0
	v_mov_b64 v[92:93], 0
	v_mov_b64 v[82:83], 0
	v_mov_b64 v[84:85], 0
	v_mov_b64 v[74:75], 0
	v_mov_b64 v[76:77], 0
	v_mov_b64 v[66:67], 0
	v_mov_b64 v[68:69], 0
	v_mov_b64 v[126:127], 0
	v_mov_b64 v[128:129], 0
	v_mov_b64 v[118:119], 0
	v_mov_b64 v[120:121], 0
	v_mov_b64 v[110:111], 0
	v_mov_b64 v[112:113], 0
	v_mov_b64 v[102:103], 0
	v_mov_b64 v[104:105], 0
	v_mov_b64 v[94:95], 0
	v_mov_b64 v[96:97], 0
	v_mov_b64 v[86:87], 0
	v_mov_b64 v[88:89], 0
	v_mov_b64 v[78:79], 0
	v_mov_b64 v[80:81], 0
	v_mov_b64 v[70:71], 0
	v_mov_b64 v[72:73], 0
	v_mov_b64 v[58:59], 0
	v_mov_b64 v[60:61], 0
	v_mov_b64 v[50:51], 0
	v_mov_b64 v[52:53], 0
	v_mov_b64 v[42:43], 0
	v_mov_b64 v[44:45], 0
	v_mov_b64 v[34:35], 0
	v_mov_b64 v[36:37], 0
	v_mov_b64 v[26:27], 0
	v_mov_b64 v[28:29], 0
	v_mov_b64 v[18:19], 0
	v_mov_b64 v[20:21], 0
	v_mov_b64 v[10:11], 0
	v_mov_b64 v[12:13], 0
	v_mov_b64 v[6:7], 0
	v_mov_b64 v[8:9], 0
	v_mov_b64 v[62:63], 0
	v_mov_b64 v[64:65], 0
	v_mov_b64 v[54:55], 0
	v_mov_b64 v[56:57], 0
	v_mov_b64 v[46:47], 0
	v_mov_b64 v[48:49], 0
	v_mov_b64 v[38:39], 0
	v_mov_b64 v[40:41], 0
	v_mov_b64 v[30:31], 0
	v_mov_b64 v[32:33], 0
	v_mov_b64 v[22:23], 0
	v_mov_b64 v[24:25], 0
	v_mov_b64 v[14:15], 0
	v_mov_b64 v[16:17], 0
	v_mov_b64 v[2:3], 0
	v_mov_b64 v[4:5], 0
	s_cbranch_vccnz .LBB0_1419
	s_barrier
	s_branch .LBB0_1419
